# K loops: loop-back barrier no longer drains LDS, every LDS wait in the loop body recomputed from the steady-state in-order queue (loop entered and left with an empty queue)
# speedup vs baseline: 1.0032x; 1.0032x over previous
; #define G_LOAD(pr, qr, kt_) if (MODE != 1) { _Pragma("unroll") for (int r = 0; r < NP; ++r) pr[r] = *(const u32x4*)(pp + (size_t)(r * 128) * ldp + (kt_) * BK); \
;                               _Pragma("unroll") for (int r = 0; r < NQ; ++r) qr[r] = *(const u32x4*)(qp + (size_t)(r * 128) * ldq + (kt_) * BK); }
; #define G_STORE(pr, qr, so_) { unsigned char* w_ = wP + (so_); \
;                               _Pragma("unroll") for (int r = 0; r < NP; ++r) *(u32x4*)(w_ + r * 128 * LROW) = pr[r]; \
;                               _Pragma("unroll") for (int r = 0; r < NQ; ++r) *(u32x4*)(w_ + BI * LROW + r * 128 * LROW) = qr[r]; }
;     ...
;     const bf16_t* pp = P + (size_t)lrow * ldp + lch * 8;
;     const bf16_t* qp = Q + (size_t)lrow * ldq + lch * 8;
;     unsigned char* wP = lds + lrow * LROW + lch * 16;
;     const unsigned char* rP = lds + (wi * WI * 32 + (lane & 31)) * LROW + (lane >> 5) * 16;
;     const unsigned char* rQ = lds + BI * LROW + (wj * 64 + (lane & 31)) * LROW + (lane >> 5) * 16;
;     u32x4 p0[NP], q0[NQ], p1[NP], q1[NQ], p2[NP], q2[NQ];
;     bf16x8 fa0[WI], fb0[2], fb1[2];
;     if (ZERO) {
; #pragma unroll
;         for (int it = 0; it < WI; ++it)
; #pragma unroll
;             for (int jt = 0; jt < 2; ++jt)
; #pragma unroll
;                 for (int r = 0; r < 16; ++r) acc[it][jt][r] = 0.f;
;     }
;     const int nk = K / BK;
;     ...
;     if (MODE == 1) {
; #pragma unroll
;         for (int r = 0; r < NP; ++r) { p0[r] = *(const u32x4*)(pp + (size_t)(r * 128) * ldp); p1[r] = p0[r]; p2[r] = p0[r]; }
; #pragma unroll
;         for (int r = 0; r < NQ; ++r) { q0[r] = *(const u32x4*)(qp + (size_t)(r * 128) * ldq); q1[r] = q0[r]; q2[r] = q0[r]; }
;     }
;     G_LOAD(p0, q0, 0)
;     G_LOAD(p1, q1, 1)
;     G_LOAD(p2, q2, 2)
;     G_STORE(p0, q0, 0)
;     G_LOAD(p0, q0, 3)
;     G_STORE(p1, q1, STAGE)
;     __syncthreads();
;     F_LOAD(fa0, fb0, 0, 0)
; template <int MODE>
; DI void phase1(const Params& p, unsigned char* smem, int tid) {
;     ...
;         } else {
;             const int fn = F - 9;
;             int tl = tid; asm volatile("" : "+v"(tl));
;             gemm_tile3r<4, 4, MODE>(hb + (size_t)tt * 256 * 1024, 1024, wt1 + (size_t)(2304 + fn * 256) * 1024, 1024, 1024, lds, acc, tl);
.LBB0_216:
	s_cmp_gt_i32 s93, 8
	s_cselect_b64 s[6:7], -1, 0
	s_cmp_lg_u32 s93, 13
	s_cselect_b64 s[8:9], -1, 0
	s_and_b64 s[10:11], s[6:7], s[8:9]
	s_mov_b64 s[8:9], -1
	s_and_b64 vcc, exec, s[10:11]
	s_cbranch_vccz .LBB0_228
	s_ashr_i32 s5, s4, 31
	v_mov_b32_e32 v40, v212
	s_lshl_b64 s[10:11], s[4:5], 19
	s_add_u32 s14, s85, s10
	v_ashrrev_i32_e32 v32, 2, v40
	s_addc_u32 s15, s90, s11
	s_lshl_b32 s8, s93, 8
	s_mov_b32 s9, s75
	v_ashrrev_i32_e32 v33, 31, v32
	s_lshl_b64 s[12:13], s[8:9], 11
	v_lshlrev_b64 v[34:35], 11, v[32:33]
	v_lshlrev_b32_e32 v2, 4, v40
	s_add_u32 s44, s34, s12
	v_and_b32_e32 v208, 48, v2
	v_lshl_add_u64 v[2:3], s[14:15], 0, v[34:35]
	s_mov_b64 s[98:99], s[14:15]
	s_addc_u32 s45, s35, s13
	v_lshl_add_u64 v[176:177], v[2:3], 0, v[208:209]
	v_add_u32_e32 v250, v34, v208
	v_add_u32_e32 v251, 0x40000, v250
	v_lshl_add_u64 v[0:1], s[44:45], 0, v[34:35]
	s_mov_b64 s[100:101], s[44:45]
	v_add_co_u32_e32 v36, vcc, s16, v176
	v_lshl_add_u64 v[178:179], v[0:1], 0, v[208:209]
	s_nop 0
	v_addc_co_u32_e32 v37, vcc, 0, v177, vcc
	v_add_co_u32_e32 v38, vcc, s16, v178
	v_ashrrev_i32_e32 v33, 6, v40
	s_nop 0
	v_addc_co_u32_e32 v39, vcc, 0, v179, vcc
	global_load_dwordx4 v[0:3], v[176:177], off
	global_load_dwordx4 v[4:7], v[176:177], off offset:64
	global_load_dwordx4 v[8:11], v[36:37], off
	global_load_dwordx4 v[12:15], v[36:37], off offset:64
	global_load_dwordx4 v[16:19], v[178:179], off
	global_load_dwordx4 v[20:23], v[178:179], off offset:64
	global_load_dwordx4 v[24:27], v[38:39], off
	global_load_dwordx4 v[28:31], v[38:39], off offset:64
	global_load_dwordx4 v[172:175], v[176:177], off offset:128
	global_load_dwordx4 v[160:163], v[176:177], off offset:192
	global_load_dwordx4 v[180:183], v[36:37], off offset:128
	global_load_dwordx4 v[156:159], v[36:37], off offset:192
	global_load_dwordx4 v[168:171], v[178:179], off offset:128
	global_load_dwordx4 v[148:151], v[178:179], off offset:192
	global_load_dwordx4 v[164:167], v[38:39], off offset:128
	global_load_dwordx4 v[152:155], v[38:39], off offset:192
	v_lshrrev_b32_e32 v42, 30, v33
	v_mul_lo_u32 v32, v32, s3
	v_add_u32_e32 v42, v33, v42
	v_and_b32_e32 v41, 31, v40
	v_add3_u32 v210, 0, v32, v208
	v_and_b32_e32 v32, 0x3ffffc, v42
	v_lshlrev_b32_e32 v42, 5, v42
	v_lshrrev_b32_e32 v40, 1, v40
	v_sub_u32_e32 v32, v33, v32
	v_and_or_b32 v33, v42, s33, v41
	v_and_b32_e32 v40, 16, v40
	v_mul_lo_u32 v33, v33, s3
	v_lshl_or_b32 v32, v32, 6, v41
	v_mul_lo_u32 v32, v32, s3
	v_add3_u32 v211, 0, v33, v40
	v_add_u32_e32 v194, 0x12000, v210
	v_add3_u32 v204, 0, v32, v40
	s_add_u32 s10, s30, s10
	s_addc_u32 s11, s31, s11
	v_lshl_add_u64 v[188:189], s[10:11], 0, v[34:35]
	s_add_u32 s10, s30, s12
	s_addc_u32 s11, s31, s13
	s_mov_b32 s5, 0
	v_add_u32_e32 v193, 0x19800, v210
	v_add_u32_e32 v196, 0x14800, v210
	v_add_u32_e32 v195, 0x17000, v210
	v_add_u32_e32 v192, 0x1c000, v210
	v_add_u32_e32 v197, 0x14800, v211
	v_add_u32_e32 v198, 0x15200, v211
	v_add_u32_e32 v199, 0x15c00, v211
	v_add_u32_e32 v200, 0x16600, v211
	v_add_u32_e32 v205, 0x5800, v204
	v_add_u32_e32 v201, 0x19800, v204
	v_add_u32_e32 v202, 0x1a200, v204
	v_add_u32_e32 v203, 0x19820, v204
	v_add_u32_e32 v206, 0x14820, v211
	v_add_u32_e32 v207, 0x1a220, v204
	v_add_u32_e32 v216, 0x15220, v211
	v_add_u32_e32 v217, 0x15c20, v211
	v_add_u32_e32 v218, 0x16620, v211
	v_lshl_add_u64 v[190:191], s[10:11], 0, v[34:35]
	s_waitcnt vmcnt(15)
	ds_write_b128 v210, v[0:3] offset:2048
	s_waitcnt vmcnt(14)
	ds_write_b128 v210, v[4:7] offset:43008
	s_waitcnt vmcnt(13)
	ds_write_b128 v210, v[8:11] offset:12288
	s_waitcnt vmcnt(12)
	ds_write_b128 v210, v[12:15] offset:53248
	s_waitcnt vmcnt(11)
	ds_write_b128 v210, v[16:19] offset:22528
	s_waitcnt vmcnt(10)
	ds_write_b128 v210, v[20:23] offset:63488
	s_waitcnt vmcnt(9)
	ds_write_b128 v210, v[24:27] offset:32768
	s_waitcnt vmcnt(8)
	ds_write_b128 v194, v[28:31]
	s_waitcnt lgkmcnt(0)
	s_barrier
	ds_read_b128 v[144:147], v211 offset:2048
	ds_read_b128 v[140:143], v211 offset:4608
	ds_read_b128 v[136:139], v211 offset:7168
	ds_read_b128 v[132:135], v211 offset:9728
	ds_read_b128 v[184:187], v204 offset:22528
	ds_read_b128 v[128:131], v204 offset:25088
	v_mov_b32_e32 v0, 0
	v_mov_b32_e32 v1, v0
	v_mov_b32_e32 v2, v0
	v_mov_b32_e32 v3, v0
	v_mov_b32_e32 v4, v0
	v_mov_b32_e32 v5, v0
	v_mov_b32_e32 v6, v0
	v_mov_b32_e32 v7, v0
	v_mov_b32_e32 v8, v0
	v_mov_b32_e32 v9, v0
	v_mov_b32_e32 v10, v0
	v_mov_b32_e32 v11, v0
	v_mov_b32_e32 v12, v0
	v_mov_b32_e32 v13, v0
	v_mov_b32_e32 v14, v0
	v_mov_b32_e32 v15, v0
	v_mov_b32_e32 v64, v0
	v_mov_b32_e32 v65, v0
	v_mov_b32_e32 v66, v0
	v_mov_b32_e32 v67, v0
	v_mov_b32_e32 v68, v0
	v_mov_b32_e32 v69, v0
	v_mov_b32_e32 v70, v0
	v_mov_b32_e32 v71, v0
	v_mov_b32_e32 v72, v0
	v_mov_b32_e32 v73, v0
	v_mov_b32_e32 v74, v0
	v_mov_b32_e32 v75, v0
	v_mov_b32_e32 v76, v0
	v_mov_b32_e32 v77, v0
	v_mov_b32_e32 v78, v0
	v_mov_b32_e32 v79, v0
	v_mov_b32_e32 v16, v0
	v_mov_b32_e32 v17, v0
	v_mov_b32_e32 v18, v0
	v_mov_b32_e32 v19, v0
	v_mov_b32_e32 v20, v0
	v_mov_b32_e32 v21, v0
	v_mov_b32_e32 v22, v0
	v_mov_b32_e32 v23, v0
	v_mov_b32_e32 v24, v0
	v_mov_b32_e32 v25, v0
	v_mov_b32_e32 v26, v0
	v_mov_b32_e32 v27, v0
	v_mov_b32_e32 v28, v0
	v_mov_b32_e32 v29, v0
	v_mov_b32_e32 v30, v0
	v_mov_b32_e32 v31, v0
	v_mov_b32_e32 v80, v0
	v_mov_b32_e32 v81, v0
	v_mov_b32_e32 v82, v0
	v_mov_b32_e32 v83, v0
	v_mov_b32_e32 v84, v0
	v_mov_b32_e32 v85, v0
	v_mov_b32_e32 v86, v0
	v_mov_b32_e32 v87, v0
	v_mov_b32_e32 v88, v0
	v_mov_b32_e32 v89, v0
	v_mov_b32_e32 v90, v0
	v_mov_b32_e32 v91, v0
	v_mov_b32_e32 v92, v0
	v_mov_b32_e32 v93, v0
	v_mov_b32_e32 v94, v0
	v_mov_b32_e32 v95, v0
	v_mov_b32_e32 v32, v0
; #define G_LOAD(pr, qr, kt_) if (MODE != 1) { _Pragma("unroll") for (int r = 0; r < NP; ++r) pr[r] = *(const u32x4*)(pp + (size_t)(r * 128) * ldp + (kt_) * BK); \
;                               _Pragma("unroll") for (int r = 0; r < NQ; ++r) qr[r] = *(const u32x4*)(qp + (size_t)(r * 128) * ldq + (kt_) * BK); }
; #define G_STORE(pr, qr, so_) { unsigned char* w_ = wP + (so_); \
;                               _Pragma("unroll") for (int r = 0; r < NP; ++r) *(u32x4*)(w_ + r * 128 * LROW) = pr[r]; \
;                               _Pragma("unroll") for (int r = 0; r < NQ; ++r) *(u32x4*)(w_ + BI * LROW + r * 128 * LROW) = qr[r]; }
; #define F_LOAD(fa, fb, so_, ks_) { _Pragma("unroll") for (int it = 0; it < WI; ++it) fa[it] = *(const bf16x8*)(rP + (so_) + it * 32 * LROW + (ks_) * 32); \
;                                   _Pragma("unroll") for (int jt = 0; jt < 2; ++jt) fb[jt] = *(const bf16x8*)(rQ + (so_) + jt * 32 * LROW + (ks_) * 32); }
; #define G_LOAD(pr, qr, kt_) if (MODE != 1) { _Pragma("unroll") for (int r = 0; r < NP; ++r) pr[r] = *(const u32x4*)(pp + (size_t)(r * 128) * ldp + (kt_) * BK); \
;                               _Pragma("unroll") for (int r = 0; r < NQ; ++r) qr[r] = *(const u32x4*)(qp + (size_t)(r * 128) * ldq + (kt_) * BK); }
; #define G_STORE(pr, qr, so_) { unsigned char* w_ = wP + (so_); \
;                               _Pragma("unroll") for (int r = 0; r < NP; ++r) *(u32x4*)(w_ + r * 128 * LROW) = pr[r]; \
;                               _Pragma("unroll") for (int r = 0; r < NQ; ++r) *(u32x4*)(w_ + BI * LROW + r * 128 * LROW) = qr[r]; }
;     ...
;     if (MODE == 1) {
; #pragma unroll
;         for (int r = 0; r < NP; ++r) { p0[r] = *(const u32x4*)(pp + (size_t)(r * 128) * ldp); p1[r] = p0[r]; p2[r] = p0[r]; }
; #pragma unroll
;         for (int r = 0; r < NQ; ++r) { q0[r] = *(const u32x4*)(qp + (size_t)(r * 128) * ldq); q1[r] = q0[r]; q2[r] = q0[r]; }
;     }
;     G_LOAD(p0, q0, 0)
;     G_LOAD(p1, q1, 1)
;     G_LOAD(p2, q2, 2)
;     G_STORE(p0, q0, 0)
;     G_LOAD(p0, q0, 3)
;     G_STORE(p1, q1, STAGE)
;     __syncthreads();
;     F_LOAD(fa0, fb0, 0, 0)
;     int cur = 0, nxt = STAGE, wr = 2 * STAGE;
;     int kt = 0;
; #pragma unroll 1
;     for (; kt + 3 <= nk; kt += 3) {
;         G_HALF(p1, q1, p2, q2, kt)
;         G_HALF(p2, q2, p0, q0, kt + 1)
;         G_HALF(p0, q0, p1, q1, kt + 2)
	v_mov_b32_e32 v33, v0
	v_mov_b32_e32 v34, v0
	v_mov_b32_e32 v35, v0
	v_mov_b32_e32 v36, v0
	v_mov_b32_e32 v37, v0
	v_mov_b32_e32 v38, v0
	v_mov_b32_e32 v39, v0
	v_mov_b32_e32 v40, v0
	v_mov_b32_e32 v41, v0
	v_mov_b32_e32 v42, v0
	v_mov_b32_e32 v43, v0
	v_mov_b32_e32 v44, v0
	v_mov_b32_e32 v45, v0
	v_mov_b32_e32 v46, v0
	v_mov_b32_e32 v47, v0
	v_mov_b32_e32 v96, v0
	v_mov_b32_e32 v97, v0
	v_mov_b32_e32 v98, v0
	v_mov_b32_e32 v99, v0
	v_mov_b32_e32 v100, v0
	v_mov_b32_e32 v101, v0
	v_mov_b32_e32 v102, v0
	v_mov_b32_e32 v103, v0
	v_mov_b32_e32 v104, v0
	v_mov_b32_e32 v105, v0
	v_mov_b32_e32 v106, v0
	v_mov_b32_e32 v107, v0
	v_mov_b32_e32 v108, v0
	v_mov_b32_e32 v109, v0
	v_mov_b32_e32 v110, v0
	v_mov_b32_e32 v111, v0
	v_mov_b32_e32 v48, v0
	v_mov_b32_e32 v49, v0
	v_mov_b32_e32 v50, v0
	v_mov_b32_e32 v51, v0
	v_mov_b32_e32 v52, v0
	v_mov_b32_e32 v53, v0
	v_mov_b32_e32 v54, v0
	v_mov_b32_e32 v55, v0
	v_mov_b32_e32 v56, v0
	v_mov_b32_e32 v57, v0
	v_mov_b32_e32 v58, v0
	v_mov_b32_e32 v59, v0
	v_mov_b32_e32 v60, v0
	v_mov_b32_e32 v61, v0
	v_mov_b32_e32 v62, v0
	v_mov_b32_e32 v63, v0
	v_mov_b32_e32 v112, v0
	v_mov_b32_e32 v113, v0
	v_mov_b32_e32 v114, v0
	v_mov_b32_e32 v115, v0
	v_mov_b32_e32 v116, v0
	v_mov_b32_e32 v117, v0
	v_mov_b32_e32 v118, v0
	v_mov_b32_e32 v119, v0
	v_mov_b32_e32 v120, v0
	v_mov_b32_e32 v121, v0
	v_mov_b32_e32 v122, v0
	v_mov_b32_e32 v123, v0
	v_mov_b32_e32 v124, v0
	v_mov_b32_e32 v125, v0
	v_mov_b32_e32 v126, v0
	v_mov_b32_e32 v127, v0
	s_waitcnt lgkmcnt(0)
.LBB0_218:
	s_nop 0
	s_waitcnt lgkmcnt(4)
	v_mfma_f32_32x32x16_bf16 v[112:127], v[144:147], v[184:187], v[112:127]
	ds_read_b128 v[220:223], v204 offset:22560
	s_waitcnt vmcnt(7)
	ds_write_b128 v196, v[172:175]
	s_waitcnt lgkmcnt(5)
	v_mfma_f32_32x32x16_bf16 v[48:63], v[144:147], v[128:131], v[48:63]
	ds_read_b128 v[172:175], v211 offset:2080
	global_load_dwordx4 v[144:147], v250, s[98:99] offset:256
	s_waitcnt lgkmcnt(5)
	v_mfma_f32_32x32x16_bf16 v[96:111], v[140:143], v[184:187], v[96:111]
	ds_read_b128 v[224:227], v204 offset:25120
	s_waitcnt vmcnt(6)
	ds_write_b128 v195, v[180:183]
	v_mfma_f32_32x32x16_bf16 v[32:47], v[140:143], v[128:131], v[32:47]
	ds_read_b128 v[180:183], v211 offset:4640
	global_load_dwordx4 v[140:143], v251, s[98:99] offset:256
	s_waitcnt lgkmcnt(7)
	v_mfma_f32_32x32x16_bf16 v[80:95], v[136:139], v[184:187], v[80:95]
	s_waitcnt vmcnt(5)
	ds_write_b128 v193, v[168:171]
	v_mfma_f32_32x32x16_bf16 v[16:31], v[136:139], v[128:131], v[16:31]
	ds_read_b128 v[168:171], v211 offset:7200
	global_load_dwordx4 v[136:139], v250, s[100:101] offset:256
	s_waitcnt lgkmcnt(8)
	v_mfma_f32_32x32x16_bf16 v[64:79], v[132:135], v[184:187], v[64:79]
	s_waitcnt vmcnt(4)
	ds_write_b128 v192, v[164:167]
	v_mfma_f32_32x32x16_bf16 v[0:15], v[132:135], v[128:131], v[0:15]
	ds_read_b128 v[132:135], v211 offset:9760
	global_load_dwordx4 v[128:131], v251, s[100:101] offset:256
	s_waitcnt lgkmcnt(7)
	v_mfma_f32_32x32x16_bf16 v[112:127], v[172:175], v[220:223], v[112:127]
	ds_read_b128 v[164:167], v204 offset:63488
	s_waitcnt lgkmcnt(7)
	v_mfma_f32_32x32x16_bf16 v[48:63], v[172:175], v[224:227], v[48:63]
	ds_read_b128 v[172:175], v211 offset:43008
	s_waitcnt lgkmcnt(6)
	v_mfma_f32_32x32x16_bf16 v[96:111], v[180:183], v[220:223], v[96:111]
	ds_read_b128 v[184:187], v205 offset:43520
	v_mfma_f32_32x32x16_bf16 v[32:47], v[180:183], v[224:227], v[32:47]
	ds_read_b128 v[180:183], v211 offset:45568
	s_waitcnt lgkmcnt(6)
	v_mfma_f32_32x32x16_bf16 v[80:95], v[168:171], v[220:223], v[80:95]
	v_mfma_f32_32x32x16_bf16 v[16:31], v[168:171], v[224:227], v[16:31]
	ds_read_b128 v[168:171], v211 offset:48128
	s_waitcnt lgkmcnt(5)
	v_mfma_f32_32x32x16_bf16 v[64:79], v[132:135], v[220:223], v[64:79]
	v_mfma_f32_32x32x16_bf16 v[0:15], v[132:135], v[224:227], v[0:15]
	ds_read_b128 v[132:135], v211 offset:50688
	s_barrier
	s_waitcnt lgkmcnt(4)
	v_mfma_f32_32x32x16_bf16 v[112:127], v[172:175], v[164:167], v[112:127]
	ds_read_b128 v[220:223], v204 offset:63520
	ds_write_b128 v210, v[160:163] offset:2048
	s_waitcnt lgkmcnt(5)
	v_mfma_f32_32x32x16_bf16 v[48:63], v[172:175], v[184:187], v[48:63]
	global_load_dwordx4 v[172:175], v250, s[98:99] offset:320
	ds_read_b128 v[160:163], v211 offset:43040
	s_waitcnt lgkmcnt(5)
	v_mfma_f32_32x32x16_bf16 v[96:111], v[180:183], v[164:167], v[96:111]
	ds_read_b128 v[224:227], v205 offset:43552
	ds_write_b128 v210, v[156:159] offset:12288
	v_mfma_f32_32x32x16_bf16 v[32:47], v[180:183], v[184:187], v[32:47]
	global_load_dwordx4 v[180:183], v251, s[98:99] offset:320
	ds_read_b128 v[156:159], v211 offset:45600
	s_waitcnt lgkmcnt(7)
	v_mfma_f32_32x32x16_bf16 v[80:95], v[168:171], v[164:167], v[80:95]
	ds_write_b128 v210, v[148:151] offset:22528
	v_mfma_f32_32x32x16_bf16 v[16:31], v[168:171], v[184:187], v[16:31]
	global_load_dwordx4 v[168:171], v250, s[100:101] offset:320
	ds_read_b128 v[148:151], v211 offset:48160
	s_waitcnt lgkmcnt(8)
	v_mfma_f32_32x32x16_bf16 v[64:79], v[132:135], v[164:167], v[64:79]
	s_waitcnt vmcnt(7)
	ds_write_b128 v210, v[152:155] offset:32768
	v_mfma_f32_32x32x16_bf16 v[0:15], v[132:135], v[184:187], v[0:15]
	global_load_dwordx4 v[164:167], v251, s[100:101] offset:320
	ds_read_b128 v[132:135], v211 offset:50720
	s_waitcnt lgkmcnt(7)
	v_mfma_f32_32x32x16_bf16 v[112:127], v[160:163], v[220:223], v[112:127]
	ds_read_b128 v[152:155], v201
	s_waitcnt lgkmcnt(7)
	v_mfma_f32_32x32x16_bf16 v[48:63], v[160:163], v[224:227], v[48:63]
	ds_read_b128 v[160:163], v197
	s_waitcnt lgkmcnt(6)
	v_mfma_f32_32x32x16_bf16 v[96:111], v[156:159], v[220:223], v[96:111]
	ds_read_b128 v[184:187], v202
	v_mfma_f32_32x32x16_bf16 v[32:47], v[156:159], v[224:227], v[32:47]
	ds_read_b128 v[156:159], v198
	s_waitcnt lgkmcnt(6)
	v_mfma_f32_32x32x16_bf16 v[80:95], v[148:151], v[220:223], v[80:95]
	v_mfma_f32_32x32x16_bf16 v[16:31], v[148:151], v[224:227], v[16:31]
	ds_read_b128 v[148:151], v199
	s_waitcnt lgkmcnt(5)
	v_mfma_f32_32x32x16_bf16 v[64:79], v[132:135], v[220:223], v[64:79]
	v_mfma_f32_32x32x16_bf16 v[0:15], v[132:135], v[224:227], v[0:15]
	ds_read_b128 v[132:135], v200
	s_barrier
; #define G_LOAD(pr, qr, kt_) if (MODE != 1) { _Pragma("unroll") for (int r = 0; r < NP; ++r) pr[r] = *(const u32x4*)(pp + (size_t)(r * 128) * ldp + (kt_) * BK); \
;                               _Pragma("unroll") for (int r = 0; r < NQ; ++r) qr[r] = *(const u32x4*)(qp + (size_t)(r * 128) * ldq + (kt_) * BK); }
; #define G_STORE(pr, qr, so_) { unsigned char* w_ = wP + (so_); \
;                               _Pragma("unroll") for (int r = 0; r < NP; ++r) *(u32x4*)(w_ + r * 128 * LROW) = pr[r]; \
;                               _Pragma("unroll") for (int r = 0; r < NQ; ++r) *(u32x4*)(w_ + BI * LROW + r * 128 * LROW) = qr[r]; }
; #define F_LOAD(fa, fb, so_, ks_) { _Pragma("unroll") for (int it = 0; it < WI; ++it) fa[it] = *(const bf16x8*)(rP + (so_) + it * 32 * LROW + (ks_) * 32); \
;                                   _Pragma("unroll") for (int jt = 0; jt < 2; ++jt) fb[jt] = *(const bf16x8*)(rQ + (so_) + jt * 32 * LROW + (ks_) * 32); }
; #define G_LOAD(pr, qr, kt_) if (MODE != 1) { _Pragma("unroll") for (int r = 0; r < NP; ++r) pr[r] = *(const u32x4*)(pp + (size_t)(r * 128) * ldp + (kt_) * BK); \
;                               _Pragma("unroll") for (int r = 0; r < NQ; ++r) qr[r] = *(const u32x4*)(qp + (size_t)(r * 128) * ldq + (kt_) * BK); }
;     ...
;     if (MODE == 1) {
; #pragma unroll
;         for (int r = 0; r < NP; ++r) { p0[r] = *(const u32x4*)(pp + (size_t)(r * 128) * ldp); p1[r] = p0[r]; p2[r] = p0[r]; }
; #pragma unroll
;         for (int r = 0; r < NQ; ++r) { q0[r] = *(const u32x4*)(qp + (size_t)(r * 128) * ldq); q1[r] = q0[r]; q2[r] = q0[r]; }
;     }
;     G_LOAD(p0, q0, 0)
;     G_LOAD(p1, q1, 1)
;     G_LOAD(p2, q2, 2)
;     G_STORE(p0, q0, 0)
;     G_LOAD(p0, q0, 3)
;     G_STORE(p1, q1, STAGE)
;     __syncthreads();
;     F_LOAD(fa0, fb0, 0, 0)
;     int cur = 0, nxt = STAGE, wr = 2 * STAGE;
;     int kt = 0;
; #pragma unroll 1
;     for (; kt + 3 <= nk; kt += 3) {
;         G_HALF(p1, q1, p2, q2, kt)
;         G_HALF(p2, q2, p0, q0, kt + 1)
;         G_HALF(p0, q0, p1, q1, kt + 2)
;     }
;     if (kt < nk) G_HALF(p1, q1, p2, q2, kt)
;     if (kt + 1 < nk) G_HALF(p2, q2, p0, q0, kt + 1)
	s_waitcnt lgkmcnt(4)
	v_mfma_f32_32x32x16_bf16 v[112:127], v[160:163], v[152:155], v[112:127]
	ds_read_b128 v[220:223], v203
	s_waitcnt vmcnt(7)
	ds_write_b128 v210, v[144:147] offset:43008
	s_waitcnt lgkmcnt(5)
	v_mfma_f32_32x32x16_bf16 v[48:63], v[160:163], v[184:187], v[48:63]
	global_load_dwordx4 v[160:163], v250, s[98:99] offset:384
	ds_read_b128 v[144:147], v206
	s_waitcnt lgkmcnt(5)
	v_mfma_f32_32x32x16_bf16 v[96:111], v[156:159], v[152:155], v[96:111]
	ds_read_b128 v[224:227], v207
	s_waitcnt vmcnt(7)
	ds_write_b128 v210, v[140:143] offset:53248
	v_mfma_f32_32x32x16_bf16 v[32:47], v[156:159], v[184:187], v[32:47]
	global_load_dwordx4 v[156:159], v251, s[98:99] offset:384
	ds_read_b128 v[140:143], v216
	s_waitcnt lgkmcnt(7)
	v_mfma_f32_32x32x16_bf16 v[80:95], v[148:151], v[152:155], v[80:95]
	s_waitcnt vmcnt(7)
	ds_write_b128 v210, v[136:139] offset:63488
	v_mfma_f32_32x32x16_bf16 v[16:31], v[148:151], v[184:187], v[16:31]
	global_load_dwordx4 v[148:151], v250, s[100:101] offset:384
	ds_read_b128 v[136:139], v217
	s_waitcnt lgkmcnt(8)
	v_mfma_f32_32x32x16_bf16 v[64:79], v[132:135], v[152:155], v[64:79]
	s_waitcnt vmcnt(7)
	ds_write_b128 v194, v[128:131]
	v_mfma_f32_32x32x16_bf16 v[0:15], v[132:135], v[184:187], v[0:15]
	ds_read_b128 v[132:135], v218
	global_load_dwordx4 v[152:155], v251, s[100:101] offset:384
	s_waitcnt lgkmcnt(7)
	v_mfma_f32_32x32x16_bf16 v[112:127], v[144:147], v[220:223], v[112:127]
	ds_read_b128 v[184:187], v204 offset:22528
	s_waitcnt lgkmcnt(7)
	v_mfma_f32_32x32x16_bf16 v[48:63], v[144:147], v[224:227], v[48:63]
	ds_read_b128 v[144:147], v211 offset:2048
	s_waitcnt lgkmcnt(6)
	v_mfma_f32_32x32x16_bf16 v[96:111], v[140:143], v[220:223], v[96:111]
	ds_read_b128 v[128:131], v204 offset:25088
	v_mfma_f32_32x32x16_bf16 v[32:47], v[140:143], v[224:227], v[32:47]
	ds_read_b128 v[140:143], v211 offset:4608
	s_waitcnt lgkmcnt(6)
	v_mfma_f32_32x32x16_bf16 v[80:95], v[136:139], v[220:223], v[80:95]
	v_mfma_f32_32x32x16_bf16 v[16:31], v[136:139], v[224:227], v[16:31]
	ds_read_b128 v[136:139], v211 offset:7168
	s_waitcnt lgkmcnt(5)
	v_mfma_f32_32x32x16_bf16 v[64:79], v[132:135], v[220:223], v[64:79]
	v_mfma_f32_32x32x16_bf16 v[0:15], v[132:135], v[224:227], v[0:15]
	ds_read_b128 v[132:135], v211 offset:9728
	s_add_i32 s5, s5, 3
	v_add_u32_e32 v250, 0xc0, v250
	s_cmp_lt_u32 s5, 30
	v_add_u32_e32 v251, 0xc0, v251
	s_barrier
	s_cbranch_scc1 .LBB0_218
	s_waitcnt lgkmcnt(0)
	s_add_i32 s5, s8, 0xfffff700
	v_mfma_f32_32x32x16_bf16 v[112:127], v[144:147], v[184:187], v[112:127]
	ds_read_b128 v[200:203], v204 offset:22560
	s_waitcnt vmcnt(7)
	ds_write_b128 v196, v[172:175]
	ds_read_b128 v[172:175], v211 offset:2080
	v_mfma_f32_32x32x16_bf16 v[96:111], v[140:143], v[184:187], v[96:111]
	ds_read_b128 v[176:179], v204 offset:25120
	s_waitcnt vmcnt(6)
	ds_write_b128 v195, v[180:183]
	ds_read_b128 v[180:183], v211 offset:4640
	v_mfma_f32_32x32x16_bf16 v[80:95], v[136:139], v[184:187], v[80:95]
	s_waitcnt vmcnt(5)
	ds_write_b128 v193, v[168:171]
	ds_read_b128 v[168:171], v211 offset:7200
	v_mfma_f32_32x32x16_bf16 v[64:79], v[132:135], v[184:187], v[64:79]
	s_waitcnt vmcnt(4)
	ds_write_b128 v192, v[164:167]
	ds_read_b128 v[164:167], v211 offset:9760
	s_waitcnt lgkmcnt(7)
	v_mfma_f32_32x32x16_bf16 v[112:127], v[172:175], v[200:203], v[112:127]
	ds_read_b128 v[216:219], v204 offset:63488
	ds_read_b128 v[184:187], v211 offset:43008
	s_waitcnt lgkmcnt(6)
	v_mfma_f32_32x32x16_bf16 v[96:111], v[180:183], v[200:203], v[96:111]
	ds_read_b128 v[188:191], v205 offset:43520
	ds_read_b128 v[192:195], v211 offset:45568
	s_waitcnt lgkmcnt(6)
	v_mfma_f32_32x32x16_bf16 v[80:95], v[168:171], v[200:203], v[80:95]
	ds_read_b128 v[196:199], v211 offset:48128
	s_waitcnt lgkmcnt(5)
	v_mfma_f32_32x32x16_bf16 v[64:79], v[164:167], v[200:203], v[64:79]
	ds_read_b128 v[200:203], v211 offset:50688
	s_waitcnt lgkmcnt(0)
	s_barrier
	v_mfma_f32_32x32x16_bf16 v[112:127], v[184:187], v[216:219], v[112:127]
	ds_read_b128 v[220:223], v204 offset:63520
	s_waitcnt vmcnt(3)
	ds_write_b128 v210, v[160:163] offset:2048
	ds_read_b128 v[160:163], v211 offset:43040
	v_mfma_f32_32x32x16_bf16 v[96:111], v[192:195], v[216:219], v[96:111]
	ds_read_b128 v[204:207], v205 offset:43552
	s_waitcnt vmcnt(2)
	ds_write_b128 v210, v[156:159] offset:12288
	ds_read_b128 v[156:159], v211 offset:45600
	v_mfma_f32_32x32x16_bf16 v[80:95], v[196:199], v[216:219], v[80:95]
	s_waitcnt vmcnt(1)
	ds_write_b128 v210, v[148:151] offset:22528
	ds_read_b128 v[148:151], v211 offset:48160
	v_mfma_f32_32x32x16_bf16 v[64:79], v[200:203], v[216:219], v[64:79]
	s_waitcnt vmcnt(0)
	ds_write_b128 v210, v[152:155] offset:32768
	ds_read_b128 v[152:155], v211 offset:50720
	s_waitcnt lgkmcnt(7)
	v_mfma_f32_32x32x16_bf16 v[112:127], v[160:163], v[220:223], v[112:127]
	s_waitcnt lgkmcnt(4)
	v_mfma_f32_32x32x16_bf16 v[96:111], v[156:159], v[220:223], v[96:111]
	s_waitcnt lgkmcnt(2)
	v_mfma_f32_32x32x16_bf16 v[80:95], v[148:151], v[220:223], v[80:95]
	s_waitcnt lgkmcnt(0)
	v_mfma_f32_32x32x16_bf16 v[64:79], v[152:155], v[220:223], v[64:79]
	v_mov_b32_e32 v216, v212
	s_barrier
; DI u32x2 pk4(float a, float b, float c, float d) { u32x2 r; r.x = pk2(a, b); r.y = pk2(c, d); return r; }
; template <int WI, int WGJ, class GetF, class FinF>
; DI void staged_rows(unsigned char* lds, int tid, GetF get, FinF fin) {
;     constexpr int WGI = 8 / WGJ, BI = WGI * WI * 32, RS = BI * 2 + 16, ROWS = WGJ * 32, NCH = BI / 8;
;     const int lane = tid & 63, wid = tid >> 6, wi = wid / WGJ, wj = wid % WGJ, h = lane >> 5, ln = lane & 31;
; #pragma unroll
;     for (int jt = 0; jt < 2; ++jt) {
;         unsigned char* wrow = lds + (wj * 32 + ln) * RS + (wi * WI * 32 + 4 * h) * 2;
; #pragma unroll
;         for (int it = 0; it < WI; ++it)
; #pragma unroll
;             for (int g = 0; g < 4; ++g) *(u32x2*)(wrow + (it * 32 + 8 * g) * 2) = get(it, jt, g);
;         __syncthreads();
; #pragma unroll 1
;         for (int c = 0; c < ROWS * NCH / NT; ++c) {
;             const int idx = tid + c * NT, lr = idx / NCH, ch = idx % NCH;
;             const u32x4 v = *(const u32x4*)(lds + lr * RS + ch * 16);
;             fin((lr >> 5) * 64 + jt * 32 + (lr & 31), ch * 8, v);
;         }
; template <int MODE>
; DI void phase1(const Params& p, unsigned char* smem, int tid) {
;     ...
;             staged_rows<4, 4>(lds, te,
;                 [&](int it, int jt, int g) { const f32x4 rs = *(const f32x4*)(rstd + tt * 256 + wi * 128 + it * 32 + 8 * g + 4 * h);
;                     return pk4(acc[it][jt][4 * g] * rs[0], acc[it][jt][4 * g + 1] * rs[1], acc[it][jt][4 * g + 2] * rs[2], acc[it][jt][4 * g + 3] * rs[3]); },
;                 [&](int row, int col, u32x4 v) { const int feat = fn * 256 + row, t = tt * 256 + col;
;                     if (t < T) { const int b = t / L, l = t - b * L; __builtin_nontemporal_store(v, (u32x4*)(fvt + ((size_t)(b * NH + (feat >> 6)) * 64 + (feat & 63)) * LP + l)); } });
	s_lshl_b32 s10, s4, 8
	v_ashrrev_i32_e32 v208, 6, v216
	v_lshrrev_b32_e32 v210, 30, v208
	v_add_u32_e32 v210, v208, v210
	v_and_b32_e32 v211, 0x7ffffc, v210
	v_sub_u32_e32 v208, v208, v211
	v_and_b32_e32 v211, 31, v216
	v_lshl_or_b32 v208, v208, 5, v211
	v_lshlrev_b32_e32 v210, 6, v210
	v_mul_lo_u32 v208, v208, s50
	v_and_b32_e32 v210, 0xffffff00, v210
	v_lshrrev_b32_e32 v211, 2, v216
	v_and_b32_e32 v211, 8, v211
	v_add3_u32 v208, 0, v208, v210
	s_ashr_i32 s11, s10, 31
	v_add_u32_e32 v217, v208, v211
	s_lshl_b64 s[12:13], s[10:11], 2
	v_ashrrev_i32_e32 v208, 1, v216
	s_add_u32 s12, s40, s12
	v_and_b32_e32 v210, 0xffffff80, v208
	s_addc_u32 s13, s41, s13
	v_ashrrev_i32_e32 v211, 31, v210
	v_lshrrev_b32_e32 v208, 1, v216
	v_lshl_add_u64 v[210:211], v[210:211], 2, s[12:13]
	v_and_b32_e32 v208, 16, v208
	v_lshl_add_u64 v[210:211], v[210:211], 0, v[208:209]
	global_load_dwordx4 v[222:225], v[210:211], off
	global_load_dwordx4 v[226:229], v[210:211], off offset:32
	global_load_dwordx4 v[230:233], v[210:211], off offset:64
	global_load_dwordx4 v[234:237], v[210:211], off offset:96
	global_load_dwordx4 v[238:241], v[210:211], off offset:128
	global_load_dwordx4 v[242:245], v[210:211], off offset:160
	global_load_dwordx4 v[248:251], v[210:211], off offset:192
	global_load_dwordx4 v[252:255], v[210:211], off offset:224
	s_mov_b32 s9, 0
	s_waitcnt vmcnt(7)
	v_pk_mul_f32 v[112:113], v[112:113], v[222:223]
	v_pk_mul_f32 v[114:115], v[114:115], v[224:225]
	v_cvt_pk_bf16_f32 v218, v112, v113
	v_cvt_pk_bf16_f32 v219, v114, v115
	s_waitcnt vmcnt(6)
	v_pk_mul_f32 v[112:113], v[116:117], v[226:227]
	v_pk_mul_f32 v[114:115], v[118:119], v[228:229]
	v_cvt_pk_bf16_f32 v116, v112, v113
	v_cvt_pk_bf16_f32 v117, v114, v115
	v_add_u32_e32 v112, 0x800, v217
	ds_write2_b64 v112, v[218:219], v[116:117] offset1:2
	s_waitcnt vmcnt(5)
	v_pk_mul_f32 v[114:115], v[120:121], v[230:231]
	v_pk_mul_f32 v[116:117], v[122:123], v[232:233]
	v_cvt_pk_bf16_f32 v118, v114, v115
	v_cvt_pk_bf16_f32 v119, v116, v117
	s_waitcnt vmcnt(4)
	v_pk_mul_f32 v[114:115], v[124:125], v[234:235]
	v_pk_mul_f32 v[116:117], v[126:127], v[236:237]
	v_cvt_pk_bf16_f32 v114, v114, v115
	v_cvt_pk_bf16_f32 v115, v116, v117
	ds_write2_b64 v112, v[118:119], v[114:115] offset0:4 offset1:6
	s_waitcnt vmcnt(3)
	v_pk_mul_f32 v[96:97], v[96:97], v[238:239]
	v_pk_mul_f32 v[98:99], v[98:99], v[240:241]
	v_cvt_pk_bf16_f32 v114, v96, v97
	v_cvt_pk_bf16_f32 v115, v98, v99
	s_waitcnt vmcnt(2)
	v_pk_mul_f32 v[96:97], v[100:101], v[242:243]
	v_pk_mul_f32 v[98:99], v[102:103], v[244:245]
	v_cvt_pk_bf16_f32 v96, v96, v97
	v_cvt_pk_bf16_f32 v97, v98, v99
	ds_write2_b64 v112, v[114:115], v[96:97] offset0:8 offset1:10
	s_waitcnt vmcnt(1)
	v_pk_mul_f32 v[96:97], v[104:105], v[248:249]
	v_pk_mul_f32 v[98:99], v[106:107], v[250:251]
	v_cvt_pk_bf16_f32 v100, v96, v97
	v_cvt_pk_bf16_f32 v101, v98, v99
	s_waitcnt vmcnt(0)
	v_pk_mul_f32 v[96:97], v[108:109], v[252:253]
	v_pk_mul_f32 v[98:99], v[110:111], v[254:255]
	v_cvt_pk_bf16_f32 v96, v96, v97
	v_cvt_pk_bf16_f32 v97, v98, v99
	ds_write2_b64 v112, v[100:101], v[96:97] offset0:12 offset1:14
	global_load_dwordx4 v[222:225], v[210:211], off offset:256
	global_load_dwordx4 v[226:229], v[210:211], off offset:288
	global_load_dwordx4 v[230:233], v[210:211], off offset:320
	global_load_dwordx4 v[234:237], v[210:211], off offset:352
	global_load_dwordx4 v[238:241], v[210:211], off offset:384
	global_load_dwordx4 v[242:245], v[210:211], off offset:416
	global_load_dwordx4 v[248:251], v[210:211], off offset:448
	global_load_dwordx4 v[252:255], v[210:211], off offset:480
	s_waitcnt vmcnt(7)
	v_pk_mul_f32 v[80:81], v[80:81], v[222:223]
	v_pk_mul_f32 v[82:83], v[82:83], v[224:225]
	v_cvt_pk_bf16_f32 v96, v80, v81
	v_cvt_pk_bf16_f32 v97, v82, v83
	s_waitcnt vmcnt(6)
	v_pk_mul_f32 v[80:81], v[84:85], v[226:227]
	v_pk_mul_f32 v[82:83], v[86:87], v[228:229]
	v_cvt_pk_bf16_f32 v80, v80, v81
	v_cvt_pk_bf16_f32 v81, v82, v83
	ds_write2_b64 v112, v[96:97], v[80:81] offset0:16 offset1:18
	s_waitcnt vmcnt(5)
	v_pk_mul_f32 v[80:81], v[88:89], v[230:231]
	v_pk_mul_f32 v[82:83], v[90:91], v[232:233]
	v_cvt_pk_bf16_f32 v84, v80, v81
	v_cvt_pk_bf16_f32 v85, v82, v83
	s_waitcnt vmcnt(4)
	v_pk_mul_f32 v[80:81], v[92:93], v[234:235]
	v_pk_mul_f32 v[82:83], v[94:95], v[236:237]
	v_cvt_pk_bf16_f32 v80, v80, v81
	v_cvt_pk_bf16_f32 v81, v82, v83
	ds_write2_b64 v112, v[84:85], v[80:81] offset0:20 offset1:22
	s_waitcnt vmcnt(3)
	v_pk_mul_f32 v[64:65], v[64:65], v[238:239]
	v_pk_mul_f32 v[66:67], v[66:67], v[240:241]
	v_cvt_pk_bf16_f32 v80, v64, v65
	v_cvt_pk_bf16_f32 v81, v66, v67
	s_waitcnt vmcnt(2)
	v_pk_mul_f32 v[64:65], v[68:69], v[242:243]
	v_pk_mul_f32 v[66:67], v[70:71], v[244:245]
	v_cvt_pk_bf16_f32 v64, v64, v65
	v_cvt_pk_bf16_f32 v65, v66, v67
	ds_write2_b64 v112, v[80:81], v[64:65] offset0:24 offset1:26
	s_waitcnt vmcnt(1)
	v_pk_mul_f32 v[64:65], v[72:73], v[248:249]
	v_pk_mul_f32 v[66:67], v[74:75], v[250:251]
	v_cvt_pk_bf16_f32 v68, v64, v65
	v_cvt_pk_bf16_f32 v69, v66, v67
	s_waitcnt vmcnt(0)
	v_pk_mul_f32 v[64:65], v[76:77], v[252:253]
	v_pk_mul_f32 v[66:67], v[78:79], v[254:255]
	v_cvt_pk_bf16_f32 v64, v64, v65
	v_cvt_pk_bf16_f32 v65, v66, v67
	ds_write2_b64 v112, v[68:69], v[64:65] offset0:28 offset1:30
	s_waitcnt lgkmcnt(0)
	s_barrier
	s_branch .LBB0_221

; #define G_LOAD(pr, qr, kt_) if (MODE != 1) { _Pragma("unroll") for (int r = 0; r < NP; ++r) pr[r] = *(const u32x4*)(pp + (size_t)(r * 128) * ldp + (kt_) * BK); \
;                               _Pragma("unroll") for (int r = 0; r < NQ; ++r) qr[r] = *(const u32x4*)(qp + (size_t)(r * 128) * ldq + (kt_) * BK); }
; #define G_STORE(pr, qr, so_) { unsigned char* w_ = wP + (so_); \
;                               _Pragma("unroll") for (int r = 0; r < NP; ++r) *(u32x4*)(w_ + r * 128 * LROW) = pr[r]; \
;                               _Pragma("unroll") for (int r = 0; r < NQ; ++r) *(u32x4*)(w_ + BI * LROW + r * 128 * LROW) = qr[r]; }
;     ...
;     const bf16_t* pp = P + (size_t)lrow * ldp + lch * 8;
;     const bf16_t* qp = Q + (size_t)lrow * ldq + lch * 8;
;     unsigned char* wP = lds + lrow * LROW + lch * 16;
;     const unsigned char* rP = lds + (wi * WI * 32 + (lane & 31)) * LROW + (lane >> 5) * 16;
;     const unsigned char* rQ = lds + BI * LROW + (wj * 64 + (lane & 31)) * LROW + (lane >> 5) * 16;
;     u32x4 p0[NP], q0[NQ], p1[NP], q1[NQ], p2[NP], q2[NQ];
;     bf16x8 fa0[WI], fb0[2], fb1[2];
;     if (ZERO) {
; #pragma unroll
;         for (int it = 0; it < WI; ++it)
; #pragma unroll
;             for (int jt = 0; jt < 2; ++jt)
; #pragma unroll
;                 for (int r = 0; r < 16; ++r) acc[it][jt][r] = 0.f;
;     }
;     const int nk = K / BK;
;     ...
;     if (MODE == 1) {
; #pragma unroll
;         for (int r = 0; r < NP; ++r) { p0[r] = *(const u32x4*)(pp + (size_t)(r * 128) * ldp); p1[r] = p0[r]; p2[r] = p0[r]; }
; #pragma unroll
;         for (int r = 0; r < NQ; ++r) { q0[r] = *(const u32x4*)(qp + (size_t)(r * 128) * ldq); q1[r] = q0[r]; q2[r] = q0[r]; }
;     }
;     G_LOAD(p0, q0, 0)
;     G_LOAD(p1, q1, 1)
;     G_LOAD(p2, q2, 2)
;     G_STORE(p0, q0, 0)
;     G_LOAD(p0, q0, 3)
;     G_STORE(p1, q1, STAGE)
;     __syncthreads();
;     F_LOAD(fa0, fb0, 0, 0)
; template <int MODE>
; DI void phase1(const Params& p, unsigned char* smem, int tid) {
;     ...
;         if (F < 9 || F == 13) {
;             const int rowbase = F * 256;
;             int tl = tid; asm volatile("" : "+v"(tl));
;             gemm_tile3r<4, 4, MODE>(wt1 + (size_t)rowbase * 1024, 1024, hb + (size_t)tt * 256 * 1024, 1024, 1024, lds, acc, tl);
.LBB0_228:
	s_and_b64 vcc, exec, s[8:9]
	s_cbranch_vccz .LBB0_387
	s_lshl_b32 s88, s93, 8
	v_mov_b32_e32 v52, v212
	s_ashr_i32 s89, s88, 31
	s_lshl_b64 s[8:9], s[88:89], 11
	v_ashrrev_i32_e32 v44, 2, v52
	s_add_u32 s10, s34, s8
	v_ashrrev_i32_e32 v45, 31, v44
	s_addc_u32 s11, s35, s9
	s_ashr_i32 s5, s4, 31
	v_lshlrev_b64 v[46:47], 11, v[44:45]
	v_lshlrev_b32_e32 v0, 4, v52
	v_and_b32_e32 v208, 48, v0
	v_lshl_add_u64 v[0:1], s[10:11], 0, v[46:47]
	s_mov_b64 s[98:99], s[10:11]
	s_lshl_b64 s[10:11], s[4:5], 19
	s_add_u32 s12, s85, s10
	v_lshl_add_u64 v[184:185], v[0:1], 0, v[208:209]
	v_add_u32_e32 v250, v46, v208
	v_add_u32_e32 v251, 0x40000, v250
	s_addc_u32 s13, s90, s11
	v_add_co_u32_e32 v48, vcc, s16, v184
	v_lshl_add_u64 v[0:1], s[12:13], 0, v[46:47]
	s_mov_b64 s[100:101], s[12:13]
	s_nop 0
	v_addc_co_u32_e32 v49, vcc, 0, v185, vcc
	v_lshl_add_u64 v[186:187], v[0:1], 0, v[208:209]
	v_add_co_u32_e32 v50, vcc, s16, v186
	global_load_dwordx4 v[12:15], v[184:185], off
	global_load_dwordx4 v[16:19], v[184:185], off offset:64
	v_addc_co_u32_e32 v51, vcc, 0, v187, vcc
	global_load_dwordx4 v[20:23], v[48:49], off
	global_load_dwordx4 v[24:27], v[48:49], off offset:64
	global_load_dwordx4 v[28:31], v[186:187], off
	global_load_dwordx4 v[32:35], v[186:187], off offset:64
	global_load_dwordx4 v[36:39], v[50:51], off
	global_load_dwordx4 v[40:43], v[50:51], off offset:64
	global_load_dwordx4 v[156:159], v[184:185], off offset:128
	global_load_dwordx4 v[140:143], v[184:185], off offset:192
	global_load_dwordx4 v[152:155], v[48:49], off offset:128
	global_load_dwordx4 v[136:139], v[48:49], off offset:192
	global_load_dwordx4 v[148:151], v[186:187], off offset:128
	global_load_dwordx4 v[132:135], v[186:187], off offset:192
	global_load_dwordx4 v[144:147], v[50:51], off offset:128
	global_load_dwordx4 v[128:131], v[50:51], off offset:192
	v_ashrrev_i32_e32 v45, 6, v52
	v_lshrrev_b32_e32 v54, 30, v45
	v_mul_lo_u32 v44, v44, s3
	v_add_u32_e32 v54, v45, v54
	v_and_b32_e32 v53, 31, v52
	v_add3_u32 v192, 0, v44, v208
	v_and_b32_e32 v44, 0x3ffffc, v54
	v_lshlrev_b32_e32 v54, 5, v54
	v_lshrrev_b32_e32 v52, 1, v52
	v_sub_u32_e32 v44, v45, v44
	v_and_or_b32 v45, v54, s33, v53
	v_and_b32_e32 v52, 16, v52
	v_mul_lo_u32 v45, v45, s3
	v_lshl_or_b32 v44, v44, 6, v53
	v_mul_lo_u32 v44, v44, s3
	v_add3_u32 v193, 0, v45, v52
	v_add_u32_e32 v195, 0x12000, v192
	v_add3_u32 v194, 0, v44, v52
	s_add_u32 s8, s30, s8
	s_addc_u32 s9, s31, s9
	v_lshl_add_u64 v[188:189], s[8:9], 0, v[46:47]
	s_add_u32 s8, s30, s10
	v_mov_b32_e32 v0, 0
	s_addc_u32 s9, s31, s11
	s_mov_b32 s5, 0
	v_mov_b32_e32 v1, v0
	v_mov_b32_e32 v2, v0
	v_mov_b32_e32 v3, v0
	v_mov_b32_e32 v4, v0
	v_mov_b32_e32 v5, v0
	v_mov_b32_e32 v6, v0
	v_mov_b32_e32 v7, v0
	v_mov_b32_e32 v8, v0
	v_mov_b32_e32 v9, v0
	v_mov_b32_e32 v10, v0
	v_mov_b32_e32 v11, v0
	v_lshl_add_u64 v[190:191], s[8:9], 0, v[46:47]
	v_mov_b32_e32 v64, v0
	v_mov_b32_e32 v65, v0
	v_mov_b32_e32 v66, v0
	v_mov_b32_e32 v67, v0
	v_mov_b32_e32 v68, v0
	v_mov_b32_e32 v69, v0
	v_mov_b32_e32 v70, v0
	v_mov_b32_e32 v71, v0
	v_mov_b32_e32 v72, v0
	v_mov_b32_e32 v73, v0
	v_mov_b32_e32 v74, v0
	v_mov_b32_e32 v75, v0
	v_mov_b32_e32 v76, v0
	v_mov_b32_e32 v77, v0
	v_mov_b32_e32 v78, v0
	v_mov_b32_e32 v79, v0
	v_mov_b32_e32 v80, v0
	v_mov_b32_e32 v81, v0
	v_mov_b32_e32 v82, v0
	v_mov_b32_e32 v83, v0
	s_waitcnt vmcnt(15)
	ds_write_b128 v192, v[12:15] offset:2048
	s_waitcnt vmcnt(14)
	ds_write_b128 v192, v[16:19] offset:43008
	s_waitcnt vmcnt(13)
	ds_write_b128 v192, v[20:23] offset:12288
	s_waitcnt vmcnt(12)
	ds_write_b128 v192, v[24:27] offset:53248
	s_waitcnt vmcnt(11)
	ds_write_b128 v192, v[28:31] offset:22528
	s_waitcnt vmcnt(10)
	ds_write_b128 v192, v[32:35] offset:63488
	s_waitcnt vmcnt(9)
	ds_write_b128 v192, v[36:39] offset:32768
	s_waitcnt vmcnt(8)
	ds_write_b128 v195, v[40:43]
	s_waitcnt lgkmcnt(0)
	s_barrier
	ds_read_b128 v[180:183], v193 offset:2048
	ds_read_b128 v[176:179], v193 offset:4608
	ds_read_b128 v[172:175], v193 offset:7168
	ds_read_b128 v[168:171], v193 offset:9728
	ds_read_b128 v[160:163], v194 offset:22528
	ds_read_b128 v[164:167], v194 offset:25088
	v_mov_b32_e32 v12, v0
	v_mov_b32_e32 v13, v0
	v_mov_b32_e32 v14, v0
	v_mov_b32_e32 v15, v0
	v_mov_b32_e32 v16, v0
	v_mov_b32_e32 v17, v0
	v_mov_b32_e32 v18, v0
	v_mov_b32_e32 v19, v0
	v_mov_b32_e32 v20, v0
	v_mov_b32_e32 v21, v0
	v_mov_b32_e32 v22, v0
	v_mov_b32_e32 v23, v0
	v_mov_b32_e32 v24, v0
	v_mov_b32_e32 v25, v0
	v_mov_b32_e32 v26, v0
	v_mov_b32_e32 v27, v0
	v_mov_b32_e32 v28, v0
	v_mov_b32_e32 v29, v0
	v_mov_b32_e32 v30, v0
	v_mov_b32_e32 v31, v0
	v_mov_b32_e32 v84, v0
	v_mov_b32_e32 v85, v0
	v_mov_b32_e32 v86, v0
	v_mov_b32_e32 v87, v0
	v_mov_b32_e32 v88, v0
	v_mov_b32_e32 v89, v0
	v_mov_b32_e32 v90, v0
	v_mov_b32_e32 v91, v0
	v_mov_b32_e32 v92, v0
	v_mov_b32_e32 v93, v0
	v_mov_b32_e32 v94, v0
	v_mov_b32_e32 v95, v0
	v_mov_b32_e32 v32, v0
	v_mov_b32_e32 v33, v0
	v_mov_b32_e32 v34, v0
	v_mov_b32_e32 v35, v0
	v_mov_b32_e32 v36, v0
	v_mov_b32_e32 v37, v0
	v_mov_b32_e32 v38, v0
	v_mov_b32_e32 v39, v0
	v_mov_b32_e32 v40, v0
	v_mov_b32_e32 v41, v0
	v_mov_b32_e32 v42, v0
	v_mov_b32_e32 v43, v0
	v_mov_b32_e32 v44, v0
	v_mov_b32_e32 v45, v0
	v_mov_b32_e32 v46, v0
	v_mov_b32_e32 v47, v0
	v_mov_b32_e32 v96, v0
	v_mov_b32_e32 v97, v0
	v_mov_b32_e32 v98, v0
	v_mov_b32_e32 v99, v0
	v_mov_b32_e32 v100, v0
	v_mov_b32_e32 v101, v0
	v_mov_b32_e32 v102, v0
	v_mov_b32_e32 v103, v0
	v_mov_b32_e32 v104, v0
	v_mov_b32_e32 v105, v0
	v_mov_b32_e32 v106, v0
	v_mov_b32_e32 v107, v0
	v_mov_b32_e32 v108, v0
	v_mov_b32_e32 v109, v0
	v_mov_b32_e32 v110, v0
	v_mov_b32_e32 v111, v0
	v_mov_b32_e32 v48, v0
	v_mov_b32_e32 v49, v0
	v_mov_b32_e32 v50, v0
	v_mov_b32_e32 v51, v0
	v_mov_b32_e32 v52, v0
	v_mov_b32_e32 v53, v0
	v_mov_b32_e32 v54, v0
	v_mov_b32_e32 v55, v0
	v_mov_b32_e32 v56, v0
	v_mov_b32_e32 v57, v0
	v_mov_b32_e32 v58, v0
	v_mov_b32_e32 v59, v0
	v_mov_b32_e32 v60, v0
	v_mov_b32_e32 v61, v0
	v_mov_b32_e32 v62, v0
	v_mov_b32_e32 v63, v0
	v_mov_b32_e32 v112, v0
	v_mov_b32_e32 v113, v0
	v_mov_b32_e32 v114, v0
	v_mov_b32_e32 v115, v0
	v_mov_b32_e32 v116, v0
	v_mov_b32_e32 v117, v0
	v_mov_b32_e32 v118, v0
	v_mov_b32_e32 v119, v0
	v_mov_b32_e32 v120, v0
	v_mov_b32_e32 v121, v0
	v_mov_b32_e32 v122, v0
	v_mov_b32_e32 v123, v0
	v_mov_b32_e32 v124, v0
	v_mov_b32_e32 v125, v0
	v_mov_b32_e32 v126, v0
	v_mov_b32_e32 v127, v0
	v_add_u32_e32 v196, 0x5800, v194
	v_add_u32_e32 v198, 0x19800, v192
	v_add_u32_e32 v200, 0x14800, v192
	v_add_u32_e32 v201, 0x14800, v193
	v_add_u32_e32 v202, 0x19800, v194
	v_add_u32_e32 v199, 0x17000, v192
	v_add_u32_e32 v197, 0x1c000, v192
	v_add_u32_e32 v203, 0x1a200, v194
	v_add_u32_e32 v204, 0x15200, v193
	v_add_u32_e32 v205, 0x15c00, v193
	v_add_u32_e32 v206, 0x16600, v193
	v_add_u32_e32 v207, 0x19820, v194
	v_add_u32_e32 v210, 0x14820, v193
	v_add_u32_e32 v211, 0x1a220, v194
	v_add_u32_e32 v216, 0x15220, v193
	v_add_u32_e32 v217, 0x15c20, v193
	v_add_u32_e32 v218, 0x16620, v193
	s_waitcnt lgkmcnt(0)
; #define G_LOAD(pr, qr, kt_) if (MODE != 1) { _Pragma("unroll") for (int r = 0; r < NP; ++r) pr[r] = *(const u32x4*)(pp + (size_t)(r * 128) * ldp + (kt_) * BK); \
;                               _Pragma("unroll") for (int r = 0; r < NQ; ++r) qr[r] = *(const u32x4*)(qp + (size_t)(r * 128) * ldq + (kt_) * BK); }
; #define G_STORE(pr, qr, so_) { unsigned char* w_ = wP + (so_); \
;                               _Pragma("unroll") for (int r = 0; r < NP; ++r) *(u32x4*)(w_ + r * 128 * LROW) = pr[r]; \
;                               _Pragma("unroll") for (int r = 0; r < NQ; ++r) *(u32x4*)(w_ + BI * LROW + r * 128 * LROW) = qr[r]; }
; #define F_LOAD(fa, fb, so_, ks_) { _Pragma("unroll") for (int it = 0; it < WI; ++it) fa[it] = *(const bf16x8*)(rP + (so_) + it * 32 * LROW + (ks_) * 32); \
;                                   _Pragma("unroll") for (int jt = 0; jt < 2; ++jt) fb[jt] = *(const bf16x8*)(rQ + (so_) + jt * 32 * LROW + (ks_) * 32); }
; #define G_LOAD(pr, qr, kt_) if (MODE != 1) { _Pragma("unroll") for (int r = 0; r < NP; ++r) pr[r] = *(const u32x4*)(pp + (size_t)(r * 128) * ldp + (kt_) * BK); \
;                               _Pragma("unroll") for (int r = 0; r < NQ; ++r) qr[r] = *(const u32x4*)(qp + (size_t)(r * 128) * ldq + (kt_) * BK); }
; #define G_STORE(pr, qr, so_) { unsigned char* w_ = wP + (so_); \
;                               _Pragma("unroll") for (int r = 0; r < NP; ++r) *(u32x4*)(w_ + r * 128 * LROW) = pr[r]; \
;                               _Pragma("unroll") for (int r = 0; r < NQ; ++r) *(u32x4*)(w_ + BI * LROW + r * 128 * LROW) = qr[r]; }
;     ...
;     if (MODE == 1) {
; #pragma unroll
;         for (int r = 0; r < NP; ++r) { p0[r] = *(const u32x4*)(pp + (size_t)(r * 128) * ldp); p1[r] = p0[r]; p2[r] = p0[r]; }
; #pragma unroll
;         for (int r = 0; r < NQ; ++r) { q0[r] = *(const u32x4*)(qp + (size_t)(r * 128) * ldq); q1[r] = q0[r]; q2[r] = q0[r]; }
;     }
;     G_LOAD(p0, q0, 0)
;     G_LOAD(p1, q1, 1)
;     G_LOAD(p2, q2, 2)
;     G_STORE(p0, q0, 0)
;     G_LOAD(p0, q0, 3)
;     G_STORE(p1, q1, STAGE)
;     __syncthreads();
;     F_LOAD(fa0, fb0, 0, 0)
;     int cur = 0, nxt = STAGE, wr = 2 * STAGE;
;     int kt = 0;
; #pragma unroll 1
;     for (; kt + 3 <= nk; kt += 3) {
;         G_HALF(p1, q1, p2, q2, kt)
;         G_HALF(p2, q2, p0, q0, kt + 1)
;         G_HALF(p0, q0, p1, q1, kt + 2)
.LBB0_230:
	s_waitcnt lgkmcnt(4)
	v_mfma_f32_32x32x16_bf16 v[112:127], v[180:183], v[160:163], v[112:127]
	ds_read_b128 v[220:223], v194 offset:22560
	s_waitcnt vmcnt(7)
	ds_write_b128 v200, v[156:159]
	s_waitcnt lgkmcnt(5)
	v_mfma_f32_32x32x16_bf16 v[48:63], v[180:183], v[164:167], v[48:63]
	global_load_dwordx4 v[180:183], v250, s[98:99] offset:256
	ds_read_b128 v[156:159], v193 offset:2080
	s_waitcnt lgkmcnt(5)
	v_mfma_f32_32x32x16_bf16 v[96:111], v[176:179], v[160:163], v[96:111]
	ds_read_b128 v[224:227], v194 offset:25120
	s_waitcnt vmcnt(6)
	ds_write_b128 v199, v[152:155]
	v_mfma_f32_32x32x16_bf16 v[32:47], v[176:179], v[164:167], v[32:47]
	global_load_dwordx4 v[176:179], v251, s[98:99] offset:256
	ds_read_b128 v[152:155], v193 offset:4640
	s_waitcnt lgkmcnt(7)
	v_mfma_f32_32x32x16_bf16 v[80:95], v[172:175], v[160:163], v[80:95]
	s_waitcnt vmcnt(5)
	ds_write_b128 v198, v[148:151]
	v_mfma_f32_32x32x16_bf16 v[16:31], v[172:175], v[164:167], v[16:31]
	global_load_dwordx4 v[172:175], v250, s[100:101] offset:256
	ds_read_b128 v[148:151], v193 offset:7200
	s_waitcnt lgkmcnt(8)
	v_mfma_f32_32x32x16_bf16 v[64:79], v[168:171], v[160:163], v[64:79]
	s_waitcnt vmcnt(4)
	ds_write_b128 v197, v[144:147]
	v_mfma_f32_32x32x16_bf16 v[0:15], v[168:171], v[164:167], v[0:15]
	global_load_dwordx4 v[160:163], v251, s[100:101] offset:256
	ds_read_b128 v[144:147], v193 offset:9760
	s_waitcnt lgkmcnt(7)
	v_mfma_f32_32x32x16_bf16 v[112:127], v[156:159], v[220:223], v[112:127]
	ds_read_b128 v[164:167], v194 offset:63488
	s_waitcnt lgkmcnt(7)
	v_mfma_f32_32x32x16_bf16 v[48:63], v[156:159], v[224:227], v[48:63]
	ds_read_b128 v[156:159], v193 offset:43008
	s_waitcnt lgkmcnt(6)
	v_mfma_f32_32x32x16_bf16 v[96:111], v[152:155], v[220:223], v[96:111]
	ds_read_b128 v[168:171], v196 offset:43520
	v_mfma_f32_32x32x16_bf16 v[32:47], v[152:155], v[224:227], v[32:47]
	ds_read_b128 v[152:155], v193 offset:45568
	s_waitcnt lgkmcnt(6)
	v_mfma_f32_32x32x16_bf16 v[80:95], v[148:151], v[220:223], v[80:95]
	v_mfma_f32_32x32x16_bf16 v[16:31], v[148:151], v[224:227], v[16:31]
	ds_read_b128 v[148:151], v193 offset:48128
	s_waitcnt lgkmcnt(5)
	v_mfma_f32_32x32x16_bf16 v[64:79], v[144:147], v[220:223], v[64:79]
	v_mfma_f32_32x32x16_bf16 v[0:15], v[144:147], v[224:227], v[0:15]
	ds_read_b128 v[144:147], v193 offset:50688
	s_barrier
	s_waitcnt lgkmcnt(4)
	v_mfma_f32_32x32x16_bf16 v[112:127], v[156:159], v[164:167], v[112:127]
	ds_read_b128 v[220:223], v194 offset:63520
	ds_write_b128 v192, v[140:143] offset:2048
	s_waitcnt lgkmcnt(5)
	v_mfma_f32_32x32x16_bf16 v[48:63], v[156:159], v[168:171], v[48:63]
	global_load_dwordx4 v[156:159], v250, s[98:99] offset:320
	ds_read_b128 v[140:143], v193 offset:43040
	s_waitcnt lgkmcnt(5)
	v_mfma_f32_32x32x16_bf16 v[96:111], v[152:155], v[164:167], v[96:111]
	ds_read_b128 v[224:227], v196 offset:43552
	ds_write_b128 v192, v[136:139] offset:12288
	v_mfma_f32_32x32x16_bf16 v[32:47], v[152:155], v[168:171], v[32:47]
	global_load_dwordx4 v[152:155], v251, s[98:99] offset:320
	ds_read_b128 v[136:139], v193 offset:45600
	s_waitcnt lgkmcnt(7)
	v_mfma_f32_32x32x16_bf16 v[80:95], v[148:151], v[164:167], v[80:95]
	ds_write_b128 v192, v[132:135] offset:22528
	v_mfma_f32_32x32x16_bf16 v[16:31], v[148:151], v[168:171], v[16:31]
	global_load_dwordx4 v[148:151], v250, s[100:101] offset:320
	ds_read_b128 v[132:135], v193 offset:48160
	s_waitcnt lgkmcnt(8)
	v_mfma_f32_32x32x16_bf16 v[64:79], v[144:147], v[164:167], v[64:79]
	s_waitcnt vmcnt(7)
	ds_write_b128 v192, v[128:131] offset:32768
	v_mfma_f32_32x32x16_bf16 v[0:15], v[144:147], v[168:171], v[0:15]
	global_load_dwordx4 v[144:147], v251, s[100:101] offset:320
	ds_read_b128 v[128:131], v193 offset:50720
	s_waitcnt lgkmcnt(7)
	v_mfma_f32_32x32x16_bf16 v[112:127], v[140:143], v[220:223], v[112:127]
	ds_read_b128 v[164:167], v202
	s_waitcnt lgkmcnt(7)
	v_mfma_f32_32x32x16_bf16 v[48:63], v[140:143], v[224:227], v[48:63]
	ds_read_b128 v[140:143], v201
	s_waitcnt lgkmcnt(6)
	v_mfma_f32_32x32x16_bf16 v[96:111], v[136:139], v[220:223], v[96:111]
	ds_read_b128 v[168:171], v203
	v_mfma_f32_32x32x16_bf16 v[32:47], v[136:139], v[224:227], v[32:47]
	ds_read_b128 v[136:139], v204
	s_waitcnt lgkmcnt(6)
	v_mfma_f32_32x32x16_bf16 v[80:95], v[132:135], v[220:223], v[80:95]
	v_mfma_f32_32x32x16_bf16 v[16:31], v[132:135], v[224:227], v[16:31]
	ds_read_b128 v[132:135], v205
	s_waitcnt lgkmcnt(5)
	v_mfma_f32_32x32x16_bf16 v[64:79], v[128:131], v[220:223], v[64:79]
	v_mfma_f32_32x32x16_bf16 v[0:15], v[128:131], v[224:227], v[0:15]
	ds_read_b128 v[128:131], v206
	s_barrier
; #define G_LOAD(pr, qr, kt_) if (MODE != 1) { _Pragma("unroll") for (int r = 0; r < NP; ++r) pr[r] = *(const u32x4*)(pp + (size_t)(r * 128) * ldp + (kt_) * BK); \
;                               _Pragma("unroll") for (int r = 0; r < NQ; ++r) qr[r] = *(const u32x4*)(qp + (size_t)(r * 128) * ldq + (kt_) * BK); }
; #define G_STORE(pr, qr, so_) { unsigned char* w_ = wP + (so_); \
;                               _Pragma("unroll") for (int r = 0; r < NP; ++r) *(u32x4*)(w_ + r * 128 * LROW) = pr[r]; \
;                               _Pragma("unroll") for (int r = 0; r < NQ; ++r) *(u32x4*)(w_ + BI * LROW + r * 128 * LROW) = qr[r]; }
; #define F_LOAD(fa, fb, so_, ks_) { _Pragma("unroll") for (int it = 0; it < WI; ++it) fa[it] = *(const bf16x8*)(rP + (so_) + it * 32 * LROW + (ks_) * 32); \
;                                   _Pragma("unroll") for (int jt = 0; jt < 2; ++jt) fb[jt] = *(const bf16x8*)(rQ + (so_) + jt * 32 * LROW + (ks_) * 32); }
; #define G_LOAD(pr, qr, kt_) if (MODE != 1) { _Pragma("unroll") for (int r = 0; r < NP; ++r) pr[r] = *(const u32x4*)(pp + (size_t)(r * 128) * ldp + (kt_) * BK); \
;                               _Pragma("unroll") for (int r = 0; r < NQ; ++r) qr[r] = *(const u32x4*)(qp + (size_t)(r * 128) * ldq + (kt_) * BK); }
;     ...
;     if (MODE == 1) {
; #pragma unroll
;         for (int r = 0; r < NP; ++r) { p0[r] = *(const u32x4*)(pp + (size_t)(r * 128) * ldp); p1[r] = p0[r]; p2[r] = p0[r]; }
; #pragma unroll
;         for (int r = 0; r < NQ; ++r) { q0[r] = *(const u32x4*)(qp + (size_t)(r * 128) * ldq); q1[r] = q0[r]; q2[r] = q0[r]; }
;     }
;     G_LOAD(p0, q0, 0)
;     G_LOAD(p1, q1, 1)
;     G_LOAD(p2, q2, 2)
;     G_STORE(p0, q0, 0)
;     G_LOAD(p0, q0, 3)
;     G_STORE(p1, q1, STAGE)
;     __syncthreads();
;     F_LOAD(fa0, fb0, 0, 0)
;     int cur = 0, nxt = STAGE, wr = 2 * STAGE;
;     int kt = 0;
; #pragma unroll 1
;     for (; kt + 3 <= nk; kt += 3) {
;         G_HALF(p1, q1, p2, q2, kt)
;         G_HALF(p2, q2, p0, q0, kt + 1)
;         G_HALF(p0, q0, p1, q1, kt + 2)
;     }
;     if (kt < nk) G_HALF(p1, q1, p2, q2, kt)
;     if (kt + 1 < nk) G_HALF(p2, q2, p0, q0, kt + 1)
	s_waitcnt lgkmcnt(4)
	v_mfma_f32_32x32x16_bf16 v[112:127], v[140:143], v[164:167], v[112:127]
	ds_read_b128 v[220:223], v207
	s_waitcnt vmcnt(7)
	ds_write_b128 v192, v[180:183] offset:43008
	s_waitcnt lgkmcnt(5)
	v_mfma_f32_32x32x16_bf16 v[48:63], v[140:143], v[168:171], v[48:63]
	global_load_dwordx4 v[140:143], v250, s[98:99] offset:384
	ds_read_b128 v[180:183], v210
	s_waitcnt lgkmcnt(5)
	v_mfma_f32_32x32x16_bf16 v[96:111], v[136:139], v[164:167], v[96:111]
	ds_read_b128 v[224:227], v211
	s_waitcnt vmcnt(7)
	ds_write_b128 v192, v[176:179] offset:53248
	v_mfma_f32_32x32x16_bf16 v[32:47], v[136:139], v[168:171], v[32:47]
	ds_read_b128 v[176:179], v216
	global_load_dwordx4 v[136:139], v251, s[98:99] offset:384
	s_waitcnt lgkmcnt(7)
	v_mfma_f32_32x32x16_bf16 v[80:95], v[132:135], v[164:167], v[80:95]
	s_waitcnt vmcnt(7)
	ds_write_b128 v192, v[172:175] offset:63488
	v_mfma_f32_32x32x16_bf16 v[16:31], v[132:135], v[168:171], v[16:31]
	global_load_dwordx4 v[132:135], v250, s[100:101] offset:384
	ds_read_b128 v[172:175], v217
	s_waitcnt lgkmcnt(8)
	v_mfma_f32_32x32x16_bf16 v[64:79], v[128:131], v[164:167], v[64:79]
	s_waitcnt vmcnt(7)
	ds_write_b128 v195, v[160:163]
	v_mfma_f32_32x32x16_bf16 v[0:15], v[128:131], v[168:171], v[0:15]
	ds_read_b128 v[168:171], v218
	global_load_dwordx4 v[128:131], v251, s[100:101] offset:384
	s_waitcnt lgkmcnt(7)
	v_mfma_f32_32x32x16_bf16 v[112:127], v[180:183], v[220:223], v[112:127]
	ds_read_b128 v[160:163], v194 offset:22528
	s_waitcnt lgkmcnt(7)
	v_mfma_f32_32x32x16_bf16 v[48:63], v[180:183], v[224:227], v[48:63]
	ds_read_b128 v[180:183], v193 offset:2048
	s_waitcnt lgkmcnt(6)
	v_mfma_f32_32x32x16_bf16 v[96:111], v[176:179], v[220:223], v[96:111]
	ds_read_b128 v[164:167], v194 offset:25088
	v_mfma_f32_32x32x16_bf16 v[32:47], v[176:179], v[224:227], v[32:47]
	ds_read_b128 v[176:179], v193 offset:4608
	s_waitcnt lgkmcnt(6)
	v_mfma_f32_32x32x16_bf16 v[80:95], v[172:175], v[220:223], v[80:95]
	v_mfma_f32_32x32x16_bf16 v[16:31], v[172:175], v[224:227], v[16:31]
	ds_read_b128 v[172:175], v193 offset:7168
	s_waitcnt lgkmcnt(5)
	v_mfma_f32_32x32x16_bf16 v[64:79], v[168:171], v[220:223], v[64:79]
	v_mfma_f32_32x32x16_bf16 v[0:15], v[168:171], v[224:227], v[0:15]
	ds_read_b128 v[168:171], v193 offset:9728
	s_add_i32 s5, s5, 3
	v_add_u32_e32 v250, 0xc0, v250
	s_cmp_lt_u32 s5, 30
	v_add_u32_e32 v251, 0xc0, v251
	s_barrier
	s_cbranch_scc1 .LBB0_230
	s_waitcnt lgkmcnt(0)
	v_mfma_f32_32x32x16_bf16 v[112:127], v[180:183], v[160:163], v[112:127]
	ds_read_b128 v[184:187], v194 offset:22560
	s_waitcnt vmcnt(7)
	ds_write_b128 v200, v[156:159]
	v_mfma_f32_32x32x16_bf16 v[48:63], v[180:183], v[164:167], v[48:63]
	ds_read_b128 v[156:159], v193 offset:2080
	v_mfma_f32_32x32x16_bf16 v[96:111], v[176:179], v[160:163], v[96:111]
	ds_read_b128 v[180:183], v194 offset:25120
	s_waitcnt vmcnt(6)
	ds_write_b128 v199, v[152:155]
	v_mfma_f32_32x32x16_bf16 v[32:47], v[176:179], v[164:167], v[32:47]
	ds_read_b128 v[152:155], v193 offset:4640
	v_mfma_f32_32x32x16_bf16 v[80:95], v[172:175], v[160:163], v[80:95]
	s_waitcnt vmcnt(5)
	ds_write_b128 v198, v[148:151]
	v_mfma_f32_32x32x16_bf16 v[16:31], v[172:175], v[164:167], v[16:31]
	ds_read_b128 v[148:151], v193 offset:7200
	v_mfma_f32_32x32x16_bf16 v[64:79], v[168:171], v[160:163], v[64:79]
	s_waitcnt vmcnt(4)
	ds_write_b128 v197, v[144:147]
	v_mfma_f32_32x32x16_bf16 v[0:15], v[168:171], v[164:167], v[0:15]
	ds_read_b128 v[144:147], v193 offset:9760
	s_waitcnt lgkmcnt(7)
	v_mfma_f32_32x32x16_bf16 v[112:127], v[156:159], v[184:187], v[112:127]
	ds_read_b128 v[160:163], v194 offset:63488
	s_waitcnt lgkmcnt(7)
	v_mfma_f32_32x32x16_bf16 v[48:63], v[156:159], v[180:183], v[48:63]
	ds_read_b128 v[156:159], v193 offset:43008
	s_waitcnt lgkmcnt(6)
	v_mfma_f32_32x32x16_bf16 v[96:111], v[152:155], v[184:187], v[96:111]
	ds_read_b128 v[164:167], v196 offset:43520
	v_mfma_f32_32x32x16_bf16 v[32:47], v[152:155], v[180:183], v[32:47]
	ds_read_b128 v[152:155], v193 offset:45568
	s_waitcnt lgkmcnt(6)
	v_mfma_f32_32x32x16_bf16 v[80:95], v[148:151], v[184:187], v[80:95]
	v_mfma_f32_32x32x16_bf16 v[16:31], v[148:151], v[180:183], v[16:31]
	ds_read_b128 v[148:151], v193 offset:48128
	s_waitcnt lgkmcnt(5)
	v_mfma_f32_32x32x16_bf16 v[64:79], v[144:147], v[184:187], v[64:79]
	v_mfma_f32_32x32x16_bf16 v[0:15], v[144:147], v[180:183], v[0:15]
	ds_read_b128 v[144:147], v193 offset:50688
	s_waitcnt lgkmcnt(0)
	s_barrier
	v_mfma_f32_32x32x16_bf16 v[112:127], v[156:159], v[160:163], v[112:127]
	ds_read_b128 v[168:171], v194 offset:63520
	s_waitcnt vmcnt(3)
	ds_write_b128 v192, v[140:143] offset:2048
	v_mfma_f32_32x32x16_bf16 v[48:63], v[156:159], v[164:167], v[48:63]
	ds_read_b128 v[140:143], v193 offset:43040
	v_mfma_f32_32x32x16_bf16 v[96:111], v[152:155], v[160:163], v[96:111]
	ds_read_b128 v[156:159], v196 offset:43552
	s_waitcnt vmcnt(2)
	ds_write_b128 v192, v[136:139] offset:12288
	v_mfma_f32_32x32x16_bf16 v[32:47], v[152:155], v[164:167], v[32:47]
	ds_read_b128 v[136:139], v193 offset:45600
	v_mfma_f32_32x32x16_bf16 v[80:95], v[148:151], v[160:163], v[80:95]
	s_waitcnt vmcnt(1)
	ds_write_b128 v192, v[132:135] offset:22528
	v_mfma_f32_32x32x16_bf16 v[16:31], v[148:151], v[164:167], v[16:31]
	ds_read_b128 v[132:135], v193 offset:48160
	v_mfma_f32_32x32x16_bf16 v[64:79], v[144:147], v[160:163], v[64:79]
	s_waitcnt vmcnt(0)
	ds_write_b128 v192, v[128:131] offset:32768
	v_mfma_f32_32x32x16_bf16 v[0:15], v[144:147], v[164:167], v[0:15]
	ds_read_b128 v[128:131], v193 offset:50720
	s_waitcnt lgkmcnt(7)
	v_mfma_f32_32x32x16_bf16 v[112:127], v[140:143], v[168:171], v[112:127]
	s_waitcnt lgkmcnt(6)
	v_mfma_f32_32x32x16_bf16 v[48:63], v[140:143], v[156:159], v[48:63]
	s_waitcnt lgkmcnt(4)
	v_mfma_f32_32x32x16_bf16 v[96:111], v[136:139], v[168:171], v[96:111]
	v_mfma_f32_32x32x16_bf16 v[32:47], v[136:139], v[156:159], v[32:47]
	s_waitcnt lgkmcnt(2)
	v_mfma_f32_32x32x16_bf16 v[80:95], v[132:135], v[168:171], v[80:95]
	v_mfma_f32_32x32x16_bf16 v[16:31], v[132:135], v[156:159], v[16:31]
	s_waitcnt lgkmcnt(0)
	v_mfma_f32_32x32x16_bf16 v[64:79], v[128:131], v[168:171], v[64:79]
	v_mfma_f32_32x32x16_bf16 v[0:15], v[128:131], v[156:159], v[0:15]
	v_mov_b32_e32 v195, v212
	s_barrier
; template <int MODE>
; DI void phase1(const Params& p, unsigned char* smem, int tid) {
;     ...
;             for (int jt = 0; jt < 2; ++jt) {
;                 const int t = tt * 256 + wj * 64 + jt * 32 + ln;
;                 const float rs = rstd[t];
;                 if (wi == 0) {
;                     float sq = 0.f;
; #pragma unroll
;                     for (int it = 0; it < 4; ++it)
; #pragma unroll
;                         for (int r = 0; r < 16; ++r) { const float v = acc[it][jt][r] * rs; sq += v * v; }
;                     { const auto sw = __builtin_amdgcn_permlane32_swap(__float_as_uint(sq), __float_as_uint(sq), false, false);
;                       sq = __uint_as_float(sw[0]) + __uint_as_float(sw[1]); }
;                     if (h == 0) ((float*)(ws + OFF_RKV))[t] = 1.0f / sqrtf(sq * (1.0f / 128) + EPS);
;                 }
	s_lshl_b32 s92, s4, 8
	v_and_b32_e32 v196, 0xc0, v195
	v_and_b32_e32 v198, 31, v195
	v_or3_b32 v128, v196, s92, v198
	v_bfe_u32 v197, v195, 5, 1
	s_mov_b64 s[4:5], -1
	s_andn2_b64 vcc, exec, s[6:7]
	v_ashrrev_i32_e32 v129, 31, v128
	s_cbranch_vccnz .LBB0_367
	v_lshl_add_u64 v[130:131], v[128:129], 2, s[40:41]
	global_load_dword v134, v[130:131], off
	s_movk_i32 s4, 0x100
	v_cmp_gt_u32_e64 s[6:7], s4, v195
	v_cmp_eq_u32_e64 s[4:5], 0, v197
	s_and_saveexec_b64 s[10:11], s[6:7]
	s_cbranch_execz .LBB0_235
	s_waitcnt vmcnt(0)
	v_mul_f32_e32 v130, v113, v134
	v_mul_f32_e32 v131, v112, v134
	v_mul_f32_e32 v130, v130, v130
	v_fmac_f32_e32 v130, v131, v131
	v_mul_f32_e32 v131, v114, v134
	v_fmac_f32_e32 v130, v131, v131
	v_mul_f32_e32 v131, v115, v134
	v_fmac_f32_e32 v130, v131, v131
	v_mul_f32_e32 v131, v116, v134
	v_fmac_f32_e32 v130, v131, v131
	v_mul_f32_e32 v131, v117, v134
	v_fmac_f32_e32 v130, v131, v131
	v_mul_f32_e32 v131, v118, v134
	v_fmac_f32_e32 v130, v131, v131
	v_mul_f32_e32 v131, v119, v134
	v_fmac_f32_e32 v130, v131, v131
	v_mul_f32_e32 v131, v120, v134
	v_fmac_f32_e32 v130, v131, v131
	v_mul_f32_e32 v131, v121, v134
	v_fmac_f32_e32 v130, v131, v131
	v_mul_f32_e32 v131, v122, v134
	v_fmac_f32_e32 v130, v131, v131
	v_mul_f32_e32 v131, v123, v134
	v_fmac_f32_e32 v130, v131, v131
	v_mul_f32_e32 v131, v124, v134
	v_fmac_f32_e32 v130, v131, v131
	v_mul_f32_e32 v131, v125, v134
	v_fmac_f32_e32 v130, v131, v131
	v_mul_f32_e32 v131, v126, v134
	v_fmac_f32_e32 v130, v131, v131
	v_mul_f32_e32 v131, v127, v134
	v_fmac_f32_e32 v130, v131, v131
	v_mul_f32_e32 v131, v96, v134
	v_fmac_f32_e32 v130, v131, v131
	v_mul_f32_e32 v131, v97, v134
	v_fmac_f32_e32 v130, v131, v131
	v_mul_f32_e32 v131, v98, v134
	v_fmac_f32_e32 v130, v131, v131
	v_mul_f32_e32 v131, v99, v134
	v_fmac_f32_e32 v130, v131, v131
	v_mul_f32_e32 v131, v100, v134
	v_fmac_f32_e32 v130, v131, v131
	v_mul_f32_e32 v131, v101, v134
	v_fmac_f32_e32 v130, v131, v131
	v_mul_f32_e32 v131, v102, v134
	v_fmac_f32_e32 v130, v131, v131
	v_mul_f32_e32 v131, v103, v134
	v_fmac_f32_e32 v130, v131, v131
	v_mul_f32_e32 v131, v104, v134
	v_fmac_f32_e32 v130, v131, v131
	v_mul_f32_e32 v131, v105, v134
	v_fmac_f32_e32 v130, v131, v131
	v_mul_f32_e32 v131, v106, v134
	v_fmac_f32_e32 v130, v131, v131
	v_mul_f32_e32 v131, v107, v134
	v_fmac_f32_e32 v130, v131, v131
	v_mul_f32_e32 v131, v108, v134
	v_fmac_f32_e32 v130, v131, v131
	v_mul_f32_e32 v131, v109, v134
	v_fmac_f32_e32 v130, v131, v131
	v_mul_f32_e32 v131, v110, v134
	v_fmac_f32_e32 v130, v131, v131
	v_mul_f32_e32 v131, v111, v134
	v_fmac_f32_e32 v130, v131, v131
	v_mul_f32_e32 v131, v80, v134
	v_fmac_f32_e32 v130, v131, v131
	v_mul_f32_e32 v131, v81, v134
	v_fmac_f32_e32 v130, v131, v131
	v_mul_f32_e32 v131, v82, v134
	v_fmac_f32_e32 v130, v131, v131
	v_mul_f32_e32 v131, v83, v134
	v_fmac_f32_e32 v130, v131, v131
	v_mul_f32_e32 v131, v84, v134
	v_fmac_f32_e32 v130, v131, v131
	v_mul_f32_e32 v131, v85, v134
	v_fmac_f32_e32 v130, v131, v131
	v_mul_f32_e32 v131, v86, v134
	v_fmac_f32_e32 v130, v131, v131
	v_mul_f32_e32 v131, v87, v134
	v_fmac_f32_e32 v130, v131, v131
	v_mul_f32_e32 v131, v88, v134
	v_fmac_f32_e32 v130, v131, v131
	v_mul_f32_e32 v131, v89, v134
	v_fmac_f32_e32 v130, v131, v131
	v_mul_f32_e32 v131, v90, v134
	v_fmac_f32_e32 v130, v131, v131
	v_mul_f32_e32 v131, v91, v134
	v_fmac_f32_e32 v130, v131, v131
	v_mul_f32_e32 v131, v92, v134
	v_fmac_f32_e32 v130, v131, v131
	v_mul_f32_e32 v131, v93, v134
	v_fmac_f32_e32 v130, v131, v131
	v_mul_f32_e32 v131, v94, v134
	v_fmac_f32_e32 v130, v131, v131
	v_mul_f32_e32 v131, v95, v134
	v_fmac_f32_e32 v130, v131, v131
	v_mul_f32_e32 v131, v64, v134
	v_fmac_f32_e32 v130, v131, v131
	v_mul_f32_e32 v131, v65, v134
	v_fmac_f32_e32 v130, v131, v131
	v_mul_f32_e32 v131, v66, v134
	v_fmac_f32_e32 v130, v131, v131
	v_mul_f32_e32 v131, v67, v134
	v_fmac_f32_e32 v130, v131, v131
	v_mul_f32_e32 v131, v68, v134
	v_fmac_f32_e32 v130, v131, v131
	v_mul_f32_e32 v131, v69, v134
	v_fmac_f32_e32 v130, v131, v131
	v_mul_f32_e32 v131, v70, v134
	v_fmac_f32_e32 v130, v131, v131
	v_mul_f32_e32 v131, v71, v134
	v_fmac_f32_e32 v130, v131, v131
	v_mul_f32_e32 v131, v72, v134
	v_fmac_f32_e32 v130, v131, v131
	v_mul_f32_e32 v131, v73, v134
	v_fmac_f32_e32 v130, v131, v131
	v_mul_f32_e32 v131, v74, v134
	v_fmac_f32_e32 v130, v131, v131
	v_mul_f32_e32 v131, v75, v134
	v_fmac_f32_e32 v130, v131, v131
	v_mul_f32_e32 v131, v76, v134
	v_fmac_f32_e32 v130, v131, v131
	v_mul_f32_e32 v131, v77, v134
	v_fmac_f32_e32 v130, v131, v131
	v_mul_f32_e32 v131, v78, v134
	v_fmac_f32_e32 v130, v131, v131
	v_mul_f32_e32 v131, v79, v134
	v_fmac_f32_e32 v130, v131, v131
	v_mov_b32_e32 v131, v130
	s_nop 1
	v_permlane32_swap_b32_e32 v130, v131
	s_and_b64 exec, exec, s[4:5]
	s_cbranch_execz .LBB0_235
	v_add_f32_e32 v130, v130, v131
	v_fmamk_f32 v130, v130, 0x3c000000, v213
	s_mov_b32 s8, 0xf800000
	v_mul_f32_e32 v131, 0x4f800000, v130
	v_cmp_gt_f32_e32 vcc, s8, v130
	s_nop 1
	v_cndmask_b32_e32 v130, v130, v131, vcc
	v_sqrt_f32_e32 v131, v130
	s_nop 0
	v_add_u32_e32 v132, -1, v131
	v_fma_f32 v135, -v132, v131, v130
	v_add_u32_e32 v133, 1, v131
	v_cmp_ge_f32_e64 s[8:9], 0, v135
	s_nop 1
	v_cndmask_b32_e64 v132, v131, v132, s[8:9]
	v_fma_f32 v131, -v133, v131, v130
	v_cmp_lt_f32_e64 s[8:9], 0, v131
	s_nop 1
	v_cndmask_b32_e64 v131, v132, v133, s[8:9]
	v_mul_f32_e32 v132, 0x37800000, v131
	v_cndmask_b32_e32 v131, v131, v132, vcc
	v_cmp_class_f32_e32 vcc, v130, v214
	s_nop 1
	v_cndmask_b32_e32 v130, v131, v130, vcc
	v_div_scale_f32 v131, s[8:9], v130, v130, 1.0
	v_rcp_f32_e32 v132, v131
	v_readlane_b32 s8, v247, 11
	v_readlane_b32 s9, v247, 12
	v_fma_f32 v133, -v131, v132, 1.0
	v_fmac_f32_e32 v132, v133, v132
	v_div_scale_f32 v133, vcc, 1.0, v130, 1.0
	v_mul_f32_e32 v135, v133, v132
	v_fma_f32 v136, -v131, v135, v133
	v_fmac_f32_e32 v135, v136, v132
	v_fma_f32 v131, -v131, v135, v133
	v_div_fmas_f32 v131, v131, v132, v135
	v_div_fixup_f32 v132, v131, v130, 1.0
	v_lshl_add_u64 v[130:131], v[128:129], 2, s[8:9]
	global_store_dword v[130:131], v132, off

; #define G_LOAD(pr, qr, kt_) if (MODE != 1) { _Pragma("unroll") for (int r = 0; r < NP; ++r) pr[r] = *(const u32x4*)(pp + (size_t)(r * 128) * ldp + (kt_) * BK); \
;                               _Pragma("unroll") for (int r = 0; r < NQ; ++r) qr[r] = *(const u32x4*)(qp + (size_t)(r * 128) * ldq + (kt_) * BK); }
; #define G_STORE(pr, qr, so_) { unsigned char* w_ = wP + (so_); \
;                               _Pragma("unroll") for (int r = 0; r < NP; ++r) *(u32x4*)(w_ + r * 128 * LROW) = pr[r]; \
;                               _Pragma("unroll") for (int r = 0; r < NQ; ++r) *(u32x4*)(w_ + BI * LROW + r * 128 * LROW) = qr[r]; }
; #define F_LOAD(fa, fb, so_, ks_) { _Pragma("unroll") for (int it = 0; it < WI; ++it) fa[it] = *(const bf16x8*)(rP + (so_) + it * 32 * LROW + (ks_) * 32); \
;                                   _Pragma("unroll") for (int jt = 0; jt < 2; ++jt) fb[jt] = *(const bf16x8*)(rQ + (so_) + jt * 32 * LROW + (ks_) * 32); }
; #define G_LOAD(pr, qr, kt_) if (MODE != 1) { _Pragma("unroll") for (int r = 0; r < NP; ++r) pr[r] = *(const u32x4*)(pp + (size_t)(r * 128) * ldp + (kt_) * BK); \
;                               _Pragma("unroll") for (int r = 0; r < NQ; ++r) qr[r] = *(const u32x4*)(qp + (size_t)(r * 128) * ldq + (kt_) * BK); }
; #define G_STORE(pr, qr, so_) { unsigned char* w_ = wP + (so_); \
;                               _Pragma("unroll") for (int r = 0; r < NP; ++r) *(u32x4*)(w_ + r * 128 * LROW) = pr[r]; \
;                               _Pragma("unroll") for (int r = 0; r < NQ; ++r) *(u32x4*)(w_ + BI * LROW + r * 128 * LROW) = qr[r]; }
; #define F_LOAD(fa, fb, so_, ks_) { _Pragma("unroll") for (int it = 0; it < WI; ++it) fa[it] = *(const bf16x8*)(rP + (so_) + it * 32 * LROW + (ks_) * 32); \
;                                   _Pragma("unroll") for (int jt = 0; jt < 2; ++jt) fb[jt] = *(const bf16x8*)(rQ + (so_) + jt * 32 * LROW + (ks_) * 32); }
;     ...
;     if (ZERO) {
; #pragma unroll
;         for (int it = 0; it < WI; ++it)
; #pragma unroll
;             for (int jt = 0; jt < 2; ++jt)
; #pragma unroll
;                 for (int r = 0; r < 16; ++r) acc[it][jt][r] = 0.f;
;     }
;     constexpr int nk = 1024 / BK;
;     ...
;     G_STORE(p0, q0, 0)
;     G_LOAD(p0, q0, 3)
;     G_STORE(p1, q1, STAGE)
;     __syncthreads();
;     F_LOAD(fa0, fb0, 0, 0)
.LBB0_919:
	s_and_b64 vcc, exec, s[26:27]
	s_cbranch_vccz .LBB0_913
	s_waitcnt vmcnt(2)
	v_mov_b32_e32 v36, v198
	s_mov_b32 s20, 0
	s_waitcnt vmcnt(0)
	v_ashrrev_i32_e32 v32, 6, v36
	v_lshrrev_b32_e32 v33, 30, v32
	v_add_u32_e32 v37, v32, v33
	v_and_b32_e32 v33, 0x3ffffc, v37
	v_sub_u32_e32 v38, v32, v33
	v_ashrrev_i32_e32 v32, 2, v36
	v_ashrrev_i32_e32 v33, 31, v32
	v_lshlrev_b64 v[34:35], 11, v[32:33]
	v_lshlrev_b32_e32 v33, 4, v36
	v_and_b32_e32 v184, 48, v33
	v_lshl_add_u64 v[196:197], s[6:7], 0, v[34:35]
	v_lshl_add_u64 v[194:195], v[196:197], 0, v[184:185]
	v_lshl_add_u64 v[190:191], s[8:9], 0, v[34:35]
	v_add_co_u32_e32 v192, vcc, s29, v194
	v_mul_lo_u32 v32, v32, s30
	v_lshl_add_u64 v[188:189], v[190:191], 0, v[184:185]
	v_addc_co_u32_e32 v193, vcc, 0, v195, vcc
	v_add3_u32 v202, 0, v32, v184
	v_add_co_u32_e32 v186, vcc, s29, v188
	ds_write_b128 v202, v[16:19] offset:2048
	ds_write_b128 v202, v[24:27] offset:12288
	ds_write_b128 v202, v[20:23] offset:22528
	ds_write_b128 v202, v[28:31] offset:32768
	v_addc_co_u32_e32 v187, vcc, 0, v189, vcc
	global_load_dwordx4 v[144:147], v[194:195], off offset:192
	global_load_dwordx4 v[152:155], v[192:193], off offset:192
	global_load_dwordx4 v[148:151], v[188:189], off offset:192
	global_load_dwordx4 v[156:159], v[186:187], off offset:192
	v_lshlrev_b32_e32 v33, 5, v37
	v_and_b32_e32 v37, 31, v36
	v_and_or_b32 v33, v33, s31, v37
	v_lshrrev_b32_e32 v36, 1, v36
	v_mul_lo_u32 v33, v33, s30
	v_and_b32_e32 v36, 16, v36
	v_lshl_or_b32 v37, v38, 6, v37
	v_mul_lo_u32 v37, v37, s30
	v_add3_u32 v199, 0, v33, v36
	v_add_u32_e32 v203, 0x12000, v202
	v_add3_u32 v201, 0, v37, v36
	ds_write_b128 v202, v[0:3] offset:43008
	ds_write_b128 v202, v[12:15] offset:53248
	ds_write_b128 v202, v[4:7] offset:63488
	ds_write_b128 v203, v[8:11]
	s_waitcnt lgkmcnt(0)
	s_barrier
	ds_read_b128 v[160:163], v199 offset:2048
	ds_read_b128 v[164:167], v199 offset:4608
	ds_read_b128 v[168:171], v199 offset:7168
	ds_read_b128 v[180:183], v199 offset:9728
	ds_read_b128 v[172:175], v201 offset:22528
	ds_read_b128 v[176:179], v201 offset:25088
	v_mov_b32_e32 v0, 0
	v_add_u32_e32 v200, 0x5800, v201
	v_add_u32_e32 v217, 0x19800, v202
	v_add_u32_e32 v219, 0x14800, v202
	v_add_u32_e32 v214, 0x14800, v199
	v_add_u32_e32 v215, 0x19800, v201
	v_add_u32_e32 v218, 0x17000, v202
	v_add_u32_e32 v216, 0x1c000, v202
	v_add_u32_e32 v213, 0x1a200, v201
	v_add_u32_e32 v212, 0x15200, v199
	v_add_u32_e32 v211, 0x15c00, v199
	v_add_u32_e32 v210, 0x16600, v199
	v_add_u32_e32 v209, 0x19820, v201
	v_add_u32_e32 v208, 0x14820, v199
	v_add_u32_e32 v207, 0x1a220, v201
	v_add_u32_e32 v206, 0x15220, v199
	v_add_u32_e32 v205, 0x15c20, v199
	v_add_u32_e32 v204, 0x16620, v199
	v_mov_b32_e32 v1, v0
	v_mov_b32_e32 v2, v0
	v_mov_b32_e32 v3, v0
	v_mov_b32_e32 v4, v0
	v_mov_b32_e32 v5, v0
	v_mov_b32_e32 v6, v0
	v_mov_b32_e32 v7, v0
	v_mov_b32_e32 v8, v0
	v_mov_b32_e32 v9, v0
	v_mov_b32_e32 v10, v0
	v_mov_b32_e32 v11, v0
	v_mov_b32_e32 v12, v0
	v_mov_b32_e32 v13, v0
	v_mov_b32_e32 v14, v0
	v_mov_b32_e32 v15, v0
	v_mov_b32_e32 v64, v0
	v_mov_b32_e32 v65, v0
	v_mov_b32_e32 v66, v0
	v_mov_b32_e32 v67, v0
	v_mov_b32_e32 v68, v0
	v_mov_b32_e32 v69, v0
	v_mov_b32_e32 v70, v0
	v_mov_b32_e32 v71, v0
	v_mov_b32_e32 v72, v0
	v_mov_b32_e32 v73, v0
	v_mov_b32_e32 v74, v0
	v_mov_b32_e32 v75, v0
	v_mov_b32_e32 v76, v0
	v_mov_b32_e32 v77, v0
	v_mov_b32_e32 v78, v0
	v_mov_b32_e32 v79, v0
	v_mov_b32_e32 v16, v0
	v_mov_b32_e32 v17, v0
	v_mov_b32_e32 v18, v0
	v_mov_b32_e32 v19, v0
	v_mov_b32_e32 v20, v0
	v_mov_b32_e32 v21, v0
	v_mov_b32_e32 v22, v0
	v_mov_b32_e32 v23, v0
	v_mov_b32_e32 v24, v0
	v_mov_b32_e32 v25, v0
	v_mov_b32_e32 v26, v0
	v_mov_b32_e32 v27, v0
	v_mov_b32_e32 v28, v0
	v_mov_b32_e32 v29, v0
	v_mov_b32_e32 v30, v0
	v_mov_b32_e32 v31, v0
	v_mov_b32_e32 v80, v0
	v_mov_b32_e32 v81, v0
	v_mov_b32_e32 v82, v0
	v_mov_b32_e32 v83, v0
	v_mov_b32_e32 v84, v0
	v_mov_b32_e32 v85, v0
	v_mov_b32_e32 v86, v0
	v_mov_b32_e32 v87, v0
	v_mov_b32_e32 v88, v0
	v_mov_b32_e32 v89, v0
	v_mov_b32_e32 v90, v0
	v_mov_b32_e32 v91, v0
	v_mov_b32_e32 v92, v0
	v_mov_b32_e32 v93, v0
	v_mov_b32_e32 v94, v0
	v_mov_b32_e32 v95, v0
	v_mov_b32_e32 v32, v0
	v_mov_b32_e32 v33, v0
	v_mov_b32_e32 v34, v0
	v_mov_b32_e32 v35, v0
	v_mov_b32_e32 v36, v0
	v_mov_b32_e32 v37, v0
	v_mov_b32_e32 v38, v0
	v_mov_b32_e32 v39, v0
	v_mov_b32_e32 v40, v0
	v_mov_b32_e32 v41, v0
	v_mov_b32_e32 v42, v0
	v_mov_b32_e32 v43, v0
	v_mov_b32_e32 v44, v0
	v_mov_b32_e32 v45, v0
	v_mov_b32_e32 v46, v0
	v_mov_b32_e32 v47, v0
	v_mov_b32_e32 v96, v0
	v_mov_b32_e32 v97, v0
	v_mov_b32_e32 v98, v0
	v_mov_b32_e32 v99, v0
	v_mov_b32_e32 v100, v0
	v_mov_b32_e32 v101, v0
	v_mov_b32_e32 v102, v0
	v_mov_b32_e32 v103, v0
	v_mov_b32_e32 v104, v0
	v_mov_b32_e32 v105, v0
	v_mov_b32_e32 v106, v0
	v_mov_b32_e32 v107, v0
	v_mov_b32_e32 v108, v0
	v_mov_b32_e32 v109, v0
	v_mov_b32_e32 v110, v0
	v_mov_b32_e32 v111, v0
	v_mov_b32_e32 v48, v0
	v_mov_b32_e32 v49, v0
	v_mov_b32_e32 v50, v0
	v_mov_b32_e32 v51, v0
	v_mov_b32_e32 v52, v0
	v_mov_b32_e32 v53, v0
	v_mov_b32_e32 v54, v0
	v_mov_b32_e32 v55, v0
	v_mov_b32_e32 v56, v0
	v_mov_b32_e32 v57, v0
	v_mov_b32_e32 v58, v0
	v_mov_b32_e32 v59, v0
	v_mov_b32_e32 v60, v0
	v_mov_b32_e32 v61, v0
	v_mov_b32_e32 v62, v0
	v_mov_b32_e32 v63, v0
	v_mov_b32_e32 v112, v0
	v_mov_b32_e32 v113, v0
	v_mov_b32_e32 v114, v0
	v_mov_b32_e32 v115, v0
	v_mov_b32_e32 v116, v0
	v_mov_b32_e32 v117, v0
	v_mov_b32_e32 v118, v0
	v_mov_b32_e32 v119, v0
	v_mov_b32_e32 v120, v0
	v_mov_b32_e32 v121, v0
	v_mov_b32_e32 v122, v0
	v_mov_b32_e32 v123, v0
	v_mov_b32_e32 v124, v0
	v_mov_b32_e32 v125, v0
	v_mov_b32_e32 v126, v0
	v_mov_b32_e32 v127, v0
	s_waitcnt lgkmcnt(0)
; #define G_LOAD(pr, qr, kt_) if (MODE != 1) { _Pragma("unroll") for (int r = 0; r < NP; ++r) pr[r] = *(const u32x4*)(pp + (size_t)(r * 128) * ldp + (kt_) * BK); \
;                               _Pragma("unroll") for (int r = 0; r < NQ; ++r) qr[r] = *(const u32x4*)(qp + (size_t)(r * 128) * ldq + (kt_) * BK); }
; #define G_STORE(pr, qr, so_) { unsigned char* w_ = wP + (so_); \
;                               _Pragma("unroll") for (int r = 0; r < NP; ++r) *(u32x4*)(w_ + r * 128 * LROW) = pr[r]; \
;                               _Pragma("unroll") for (int r = 0; r < NQ; ++r) *(u32x4*)(w_ + BI * LROW + r * 128 * LROW) = qr[r]; }
; #define F_LOAD(fa, fb, so_, ks_) { _Pragma("unroll") for (int it = 0; it < WI; ++it) fa[it] = *(const bf16x8*)(rP + (so_) + it * 32 * LROW + (ks_) * 32); \
;                                   _Pragma("unroll") for (int jt = 0; jt < 2; ++jt) fb[jt] = *(const bf16x8*)(rQ + (so_) + jt * 32 * LROW + (ks_) * 32); }
; #define G_LOAD(pr, qr, kt_) if (MODE != 1) { _Pragma("unroll") for (int r = 0; r < NP; ++r) pr[r] = *(const u32x4*)(pp + (size_t)(r * 128) * ldp + (kt_) * BK); \
;                               _Pragma("unroll") for (int r = 0; r < NQ; ++r) qr[r] = *(const u32x4*)(qp + (size_t)(r * 128) * ldq + (kt_) * BK); }
; #define G_STORE(pr, qr, so_) { unsigned char* w_ = wP + (so_); \
;                               _Pragma("unroll") for (int r = 0; r < NP; ++r) *(u32x4*)(w_ + r * 128 * LROW) = pr[r]; \
;                               _Pragma("unroll") for (int r = 0; r < NQ; ++r) *(u32x4*)(w_ + BI * LROW + r * 128 * LROW) = qr[r]; }
; #define F_LOAD(fa, fb, so_, ks_) { _Pragma("unroll") for (int it = 0; it < WI; ++it) fa[it] = *(const bf16x8*)(rP + (so_) + it * 32 * LROW + (ks_) * 32); \
;                                   _Pragma("unroll") for (int jt = 0; jt < 2; ++jt) fb[jt] = *(const bf16x8*)(rQ + (so_) + jt * 32 * LROW + (ks_) * 32); }
;     ...
;     G_STORE(p0, q0, 0)
;     G_LOAD(p0, q0, 3)
;     G_STORE(p1, q1, STAGE)
;     __syncthreads();
;     F_LOAD(fa0, fb0, 0, 0)
;     int cur = 0, nxt = STAGE, wr = 2 * STAGE;
;     int kt = 0;
; #pragma unroll 1
;     for (; kt + 3 <= nk - 4; kt += 3) {
;         G_HALF(p1, q1, p2, q2, kt)
;         G_HALF(p2, q2, p0, q0, kt + 1)
;         G_HALF(p0, q0, p1, q1, kt + 2)
;     }
.LBB0_921:
	s_nop 0
	s_waitcnt lgkmcnt(4)
	v_mfma_f32_32x32x16_bf16 v[112:127], v[160:163], v[172:175], v[112:127]
	v_lshl_add_u64 v[228:229], v[190:191], 0, v[184:185]
	v_lshl_add_u64 v[230:231], v[196:197], 0, v[184:185]
	ds_read_b128 v[220:223], v201 offset:22560
	s_waitcnt vmcnt(7)
	ds_write_b128 v219, v[132:135]
	s_waitcnt lgkmcnt(5)
	v_mfma_f32_32x32x16_bf16 v[48:63], v[160:163], v[176:179], v[48:63]
	global_load_dwordx4 v[160:163], v[230:231], off offset:256
	ds_read_b128 v[132:135], v199 offset:2080
	s_waitcnt lgkmcnt(5)
	v_mfma_f32_32x32x16_bf16 v[96:111], v[164:167], v[172:175], v[96:111]
	ds_read_b128 v[224:227], v201 offset:25120
	s_waitcnt vmcnt(7)
	ds_write_b128 v218, v[128:131]
	v_mfma_f32_32x32x16_bf16 v[32:47], v[164:167], v[176:179], v[32:47]
	v_add_co_u32_e32 v232, vcc, s29, v230
	ds_read_b128 v[128:131], v199 offset:4640
	s_nop 0
	v_addc_co_u32_e32 v233, vcc, 0, v231, vcc
	global_load_dwordx4 v[164:167], v[232:233], off offset:256
	s_waitcnt lgkmcnt(7)
	v_mfma_f32_32x32x16_bf16 v[80:95], v[168:171], v[172:175], v[80:95]
	s_waitcnt vmcnt(7)
	ds_write_b128 v217, v[136:139]
	v_mfma_f32_32x32x16_bf16 v[16:31], v[168:171], v[176:179], v[16:31]
	global_load_dwordx4 v[168:171], v[228:229], off offset:256
	ds_read_b128 v[136:139], v199 offset:7200
	s_waitcnt lgkmcnt(8)
	v_mfma_f32_32x32x16_bf16 v[64:79], v[180:183], v[172:175], v[64:79]
	s_waitcnt vmcnt(7)
	ds_write_b128 v216, v[140:143]
	v_mfma_f32_32x32x16_bf16 v[0:15], v[180:183], v[176:179], v[0:15]
	v_add_co_u32_e32 v234, vcc, s29, v228
	ds_read_b128 v[140:143], v199 offset:9760
	s_nop 0
	v_addc_co_u32_e32 v235, vcc, 0, v229, vcc
	global_load_dwordx4 v[172:175], v[234:235], off offset:256
	s_waitcnt lgkmcnt(7)
	v_mfma_f32_32x32x16_bf16 v[112:127], v[132:135], v[220:223], v[112:127]
	ds_read_b128 v[176:179], v201 offset:63488
	s_waitcnt lgkmcnt(7)
	v_mfma_f32_32x32x16_bf16 v[48:63], v[132:135], v[224:227], v[48:63]
	ds_read_b128 v[132:135], v199 offset:43008
	s_waitcnt lgkmcnt(6)
	v_mfma_f32_32x32x16_bf16 v[96:111], v[128:131], v[220:223], v[96:111]
	ds_read_b128 v[180:183], v200 offset:43520
	v_mfma_f32_32x32x16_bf16 v[32:47], v[128:131], v[224:227], v[32:47]
	ds_read_b128 v[128:131], v199 offset:45568
	s_waitcnt lgkmcnt(6)
	v_mfma_f32_32x32x16_bf16 v[80:95], v[136:139], v[220:223], v[80:95]
	v_mfma_f32_32x32x16_bf16 v[16:31], v[136:139], v[224:227], v[16:31]
	ds_read_b128 v[136:139], v199 offset:48128
	s_waitcnt lgkmcnt(5)
	v_mfma_f32_32x32x16_bf16 v[64:79], v[140:143], v[220:223], v[64:79]
	v_mfma_f32_32x32x16_bf16 v[0:15], v[140:143], v[224:227], v[0:15]
	ds_read_b128 v[140:143], v199 offset:50688
	s_barrier
	s_waitcnt lgkmcnt(4)
	v_mfma_f32_32x32x16_bf16 v[112:127], v[132:135], v[176:179], v[112:127]
	ds_read_b128 v[220:223], v201 offset:63520
	s_waitcnt vmcnt(7)
	ds_write_b128 v202, v[144:147] offset:2048
	s_waitcnt lgkmcnt(5)
	v_mfma_f32_32x32x16_bf16 v[48:63], v[132:135], v[180:183], v[48:63]
	global_load_dwordx4 v[132:135], v[230:231], off offset:320
	ds_read_b128 v[144:147], v199 offset:43040
	s_waitcnt lgkmcnt(5)
	v_mfma_f32_32x32x16_bf16 v[96:111], v[128:131], v[176:179], v[96:111]
	ds_read_b128 v[224:227], v200 offset:43552
	s_waitcnt vmcnt(7)
	ds_write_b128 v202, v[152:155] offset:12288
	v_mfma_f32_32x32x16_bf16 v[32:47], v[128:131], v[180:183], v[32:47]
	global_load_dwordx4 v[128:131], v[232:233], off offset:320
	ds_read_b128 v[152:155], v199 offset:45600
	s_waitcnt lgkmcnt(7)
	v_mfma_f32_32x32x16_bf16 v[80:95], v[136:139], v[176:179], v[80:95]
	s_waitcnt vmcnt(7)
	ds_write_b128 v202, v[148:151] offset:22528
	v_mfma_f32_32x32x16_bf16 v[16:31], v[136:139], v[180:183], v[16:31]
	global_load_dwordx4 v[136:139], v[228:229], off offset:320
	ds_read_b128 v[148:151], v199 offset:48160
	s_waitcnt lgkmcnt(8)
	v_mfma_f32_32x32x16_bf16 v[64:79], v[140:143], v[176:179], v[64:79]
	s_waitcnt vmcnt(7)
	ds_write_b128 v202, v[156:159] offset:32768
	v_mfma_f32_32x32x16_bf16 v[0:15], v[140:143], v[180:183], v[0:15]
	global_load_dwordx4 v[140:143], v[234:235], off offset:320
	ds_read_b128 v[156:159], v199 offset:50720
	s_waitcnt lgkmcnt(7)
	v_mfma_f32_32x32x16_bf16 v[112:127], v[144:147], v[220:223], v[112:127]
	ds_read_b128 v[176:179], v215
	s_waitcnt lgkmcnt(7)
	v_mfma_f32_32x32x16_bf16 v[48:63], v[144:147], v[224:227], v[48:63]
	ds_read_b128 v[144:147], v214
	s_waitcnt lgkmcnt(6)
	v_mfma_f32_32x32x16_bf16 v[96:111], v[152:155], v[220:223], v[96:111]
	ds_read_b128 v[180:183], v213
	v_mfma_f32_32x32x16_bf16 v[32:47], v[152:155], v[224:227], v[32:47]
	ds_read_b128 v[152:155], v212
	s_waitcnt lgkmcnt(6)
	v_mfma_f32_32x32x16_bf16 v[80:95], v[148:151], v[220:223], v[80:95]
	v_mfma_f32_32x32x16_bf16 v[16:31], v[148:151], v[224:227], v[16:31]
	ds_read_b128 v[148:151], v211
	s_waitcnt lgkmcnt(5)
	v_mfma_f32_32x32x16_bf16 v[64:79], v[156:159], v[220:223], v[64:79]
	v_mfma_f32_32x32x16_bf16 v[0:15], v[156:159], v[224:227], v[0:15]
	ds_read_b128 v[156:159], v210
	s_barrier
; #define G_LOAD(pr, qr, kt_) if (MODE != 1) { _Pragma("unroll") for (int r = 0; r < NP; ++r) pr[r] = *(const u32x4*)(pp + (size_t)(r * 128) * ldp + (kt_) * BK); \
;                               _Pragma("unroll") for (int r = 0; r < NQ; ++r) qr[r] = *(const u32x4*)(qp + (size_t)(r * 128) * ldq + (kt_) * BK); }
; #define G_STORE(pr, qr, so_) { unsigned char* w_ = wP + (so_); \
;                               _Pragma("unroll") for (int r = 0; r < NP; ++r) *(u32x4*)(w_ + r * 128 * LROW) = pr[r]; \
;                               _Pragma("unroll") for (int r = 0; r < NQ; ++r) *(u32x4*)(w_ + BI * LROW + r * 128 * LROW) = qr[r]; }
; #define F_LOAD(fa, fb, so_, ks_) { _Pragma("unroll") for (int it = 0; it < WI; ++it) fa[it] = *(const bf16x8*)(rP + (so_) + it * 32 * LROW + (ks_) * 32); \
;                                   _Pragma("unroll") for (int jt = 0; jt < 2; ++jt) fb[jt] = *(const bf16x8*)(rQ + (so_) + jt * 32 * LROW + (ks_) * 32); }
; #define G_LOAD(pr, qr, kt_) if (MODE != 1) { _Pragma("unroll") for (int r = 0; r < NP; ++r) pr[r] = *(const u32x4*)(pp + (size_t)(r * 128) * ldp + (kt_) * BK); \
;                               _Pragma("unroll") for (int r = 0; r < NQ; ++r) qr[r] = *(const u32x4*)(qp + (size_t)(r * 128) * ldq + (kt_) * BK); }
; #define G_STORE(pr, qr, so_) { unsigned char* w_ = wP + (so_); \
;                               _Pragma("unroll") for (int r = 0; r < NP; ++r) *(u32x4*)(w_ + r * 128 * LROW) = pr[r]; \
;                               _Pragma("unroll") for (int r = 0; r < NQ; ++r) *(u32x4*)(w_ + BI * LROW + r * 128 * LROW) = qr[r]; }
; #define F_LOAD(fa, fb, so_, ks_) { _Pragma("unroll") for (int it = 0; it < WI; ++it) fa[it] = *(const bf16x8*)(rP + (so_) + it * 32 * LROW + (ks_) * 32); \
;                                   _Pragma("unroll") for (int jt = 0; jt < 2; ++jt) fb[jt] = *(const bf16x8*)(rQ + (so_) + jt * 32 * LROW + (ks_) * 32); }
;     ...
;     G_STORE(p0, q0, 0)
;     G_LOAD(p0, q0, 3)
;     G_STORE(p1, q1, STAGE)
;     __syncthreads();
;     F_LOAD(fa0, fb0, 0, 0)
;     int cur = 0, nxt = STAGE, wr = 2 * STAGE;
;     int kt = 0;
; #pragma unroll 1
;     for (; kt + 3 <= nk - 4; kt += 3) {
;         G_HALF(p1, q1, p2, q2, kt)
;         G_HALF(p2, q2, p0, q0, kt + 1)
;         G_HALF(p0, q0, p1, q1, kt + 2)
;     }
;     G_HALF(p1, q1, p2, q2, nk - 5)
	s_waitcnt lgkmcnt(4)
	v_mfma_f32_32x32x16_bf16 v[112:127], v[144:147], v[176:179], v[112:127]
	ds_read_b128 v[220:223], v209
	s_waitcnt vmcnt(7)
	ds_write_b128 v202, v[160:163] offset:43008
	s_waitcnt lgkmcnt(5)
	v_mfma_f32_32x32x16_bf16 v[48:63], v[144:147], v[180:183], v[48:63]
	global_load_dwordx4 v[144:147], v[230:231], off offset:384
	ds_read_b128 v[160:163], v208
	s_waitcnt lgkmcnt(5)
	v_mfma_f32_32x32x16_bf16 v[96:111], v[152:155], v[176:179], v[96:111]
	ds_read_b128 v[224:227], v207
	s_waitcnt vmcnt(7)
	ds_write_b128 v202, v[164:167] offset:53248
	v_mfma_f32_32x32x16_bf16 v[32:47], v[152:155], v[180:183], v[32:47]
	global_load_dwordx4 v[152:155], v[232:233], off offset:384
	ds_read_b128 v[164:167], v206
	s_waitcnt lgkmcnt(7)
	v_mfma_f32_32x32x16_bf16 v[80:95], v[148:151], v[176:179], v[80:95]
	s_waitcnt vmcnt(7)
	ds_write_b128 v202, v[168:171] offset:63488
	v_mfma_f32_32x32x16_bf16 v[16:31], v[148:151], v[180:183], v[16:31]
	global_load_dwordx4 v[148:151], v[228:229], off offset:384
	ds_read_b128 v[168:171], v205
	s_waitcnt lgkmcnt(8)
	v_mfma_f32_32x32x16_bf16 v[64:79], v[156:159], v[176:179], v[64:79]
	s_waitcnt vmcnt(7)
	ds_write_b128 v203, v[172:175]
	v_mfma_f32_32x32x16_bf16 v[0:15], v[156:159], v[180:183], v[0:15]
	global_load_dwordx4 v[156:159], v[234:235], off offset:384
	ds_read_b128 v[180:183], v204
	s_waitcnt lgkmcnt(7)
	v_mfma_f32_32x32x16_bf16 v[112:127], v[160:163], v[220:223], v[112:127]
	ds_read_b128 v[172:175], v201 offset:22528
	s_waitcnt lgkmcnt(7)
	v_mfma_f32_32x32x16_bf16 v[48:63], v[160:163], v[224:227], v[48:63]
	ds_read_b128 v[160:163], v199 offset:2048
	s_waitcnt lgkmcnt(6)
	v_mfma_f32_32x32x16_bf16 v[96:111], v[164:167], v[220:223], v[96:111]
	ds_read_b128 v[176:179], v201 offset:25088
	v_mfma_f32_32x32x16_bf16 v[32:47], v[164:167], v[224:227], v[32:47]
	ds_read_b128 v[164:167], v199 offset:4608
	s_waitcnt lgkmcnt(6)
	v_mfma_f32_32x32x16_bf16 v[80:95], v[168:171], v[220:223], v[80:95]
	v_mfma_f32_32x32x16_bf16 v[16:31], v[168:171], v[224:227], v[16:31]
	ds_read_b128 v[168:171], v199 offset:7168
	s_waitcnt lgkmcnt(5)
	v_mfma_f32_32x32x16_bf16 v[64:79], v[180:183], v[220:223], v[64:79]
	v_mfma_f32_32x32x16_bf16 v[0:15], v[180:183], v[224:227], v[0:15]
	ds_read_b128 v[180:183], v199 offset:9728
	s_add_i32 s20, s20, 3
	v_lshl_add_u64 v[196:197], v[196:197], 0, s[18:19]
	s_cmp_lt_u32 s20, 26
	v_lshl_add_u64 v[190:191], v[190:191], 0, s[18:19]
	s_barrier
	s_cbranch_scc1 .LBB0_921
	s_waitcnt lgkmcnt(0)
	v_mfma_f32_32x32x16_bf16 v[112:127], v[160:163], v[172:175], v[112:127]
	ds_read_b128 v[220:223], v201 offset:22560
	s_waitcnt vmcnt(7)
	ds_write_b128 v219, v[132:135]
	v_mfma_f32_32x32x16_bf16 v[48:63], v[160:163], v[176:179], v[48:63]
	global_load_dwordx4 v[160:163], v[194:195], off offset:1984
	ds_read_b128 v[194:197], v199 offset:2080
	v_mfma_f32_32x32x16_bf16 v[96:111], v[164:167], v[172:175], v[96:111]
	ds_read_b128 v[224:227], v201 offset:25120
	s_waitcnt vmcnt(7)
	ds_write_b128 v218, v[128:131]
	v_mfma_f32_32x32x16_bf16 v[32:47], v[164:167], v[176:179], v[32:47]
	global_load_dwordx4 v[164:167], v[192:193], off offset:1984
	ds_read_b128 v[190:193], v199 offset:4640
	v_mfma_f32_32x32x16_bf16 v[80:95], v[168:171], v[172:175], v[80:95]
	s_waitcnt vmcnt(7)
	ds_write_b128 v217, v[136:139]
	v_mfma_f32_32x32x16_bf16 v[16:31], v[168:171], v[176:179], v[16:31]
	global_load_dwordx4 v[168:171], v[188:189], off offset:1984
	ds_read_b128 v[228:231], v199 offset:7200
	v_mfma_f32_32x32x16_bf16 v[64:79], v[180:183], v[172:175], v[64:79]
	s_waitcnt vmcnt(7)
	ds_write_b128 v216, v[140:143]
	v_mfma_f32_32x32x16_bf16 v[0:15], v[180:183], v[176:179], v[0:15]
	global_load_dwordx4 v[172:175], v[186:187], off offset:1984
	ds_read_b128 v[176:179], v199 offset:9760
	s_waitcnt lgkmcnt(7)
	v_mfma_f32_32x32x16_bf16 v[112:127], v[194:197], v[220:223], v[112:127]
	ds_read_b128 v[180:183], v201 offset:63488
	s_waitcnt lgkmcnt(7)
	v_mfma_f32_32x32x16_bf16 v[48:63], v[194:197], v[224:227], v[48:63]
	ds_read_b128 v[186:189], v199 offset:43008
	s_waitcnt lgkmcnt(6)
	v_mfma_f32_32x32x16_bf16 v[96:111], v[190:193], v[220:223], v[96:111]
	ds_read_b128 v[194:197], v200 offset:43520
	v_mfma_f32_32x32x16_bf16 v[32:47], v[190:193], v[224:227], v[32:47]
	ds_read_b128 v[190:193], v199 offset:45568
	s_waitcnt lgkmcnt(6)
	v_mfma_f32_32x32x16_bf16 v[80:95], v[228:231], v[220:223], v[80:95]
	v_mfma_f32_32x32x16_bf16 v[16:31], v[228:231], v[224:227], v[16:31]
	ds_read_b128 v[216:219], v199 offset:48128
	s_waitcnt lgkmcnt(5)
	v_mfma_f32_32x32x16_bf16 v[64:79], v[176:179], v[220:223], v[64:79]
	v_mfma_f32_32x32x16_bf16 v[0:15], v[176:179], v[224:227], v[0:15]
	ds_read_b128 v[176:179], v199 offset:50688
	s_waitcnt lgkmcnt(0)
	s_barrier
; #define G_HALF(pl, ql, ps, qs, kt_) { const int k4_ = min((kt_) + 4, nk - 1); \
;         SB G_LOAD(pl, ql, k4_) F_LOAD(fa1, fb1, cur, 1) SB G_MFMA(fa0, fb0) SB G_STORE(ps, qs, wr) F_LOAD(fa0, fb0, nxt, 0) SB G_MFMA(fa1, fb1) SB \
;         __syncthreads(); { const int t_ = cur; cur = nxt; nxt = wr; wr = t_; } }
; #define G_HALF(pl, ql, ps, qs, kt_) { const int k4_ = min((kt_) + 4, nk - 1); \
;         SB R_BURST1(fb0, fb1, cur, 1, pl, ql, k4_, ps, qs, wr) R_BURST2(fb1, fb0, nxt, 0, ps, qs, wr) \
;         __syncthreads(); { const int t_ = cur; cur = nxt; nxt = wr; wr = t_; } }
; #define G_HALF(pl, ql, ps, qs, kt_) { const int k4_ = min((kt_) + 4, nk - 1); \
;         SB R_BURST1(fb0, fb1, cur, 1, pl, ql, k4_, ps, qs, wr) R_BURST2(fb1, fb0, nxt, 0, ps, qs, wr) \
;         __syncthreads(); { const int t_ = cur; cur = nxt; nxt = wr; wr = t_; } }
; #define G_HALF_NL(ps, qs, kt_) { SB R_BURST1S(fb0, fb1, cur, 1, ps, qs, wr) R_BURST2(fb1, fb0, nxt, 0, ps, qs, wr) \
;         __syncthreads(); { const int t_ = cur; cur = nxt; nxt = wr; wr = t_; } }
;     ...
;     G_HALF(p1, q1, p2, q2, nk - 5)
;     G_HALF_NL(p0, q0, nk - 4)
;     G_HALF_NL(p1, q1, nk - 3)
	v_mfma_f32_32x32x16_bf16 v[112:127], v[186:189], v[180:183], v[112:127]
	ds_read_b128 v[220:223], v201 offset:63520
	s_waitcnt vmcnt(7)
	ds_write_b128 v202, v[144:147] offset:2048
	v_mfma_f32_32x32x16_bf16 v[48:63], v[186:189], v[194:197], v[48:63]
	ds_read_b128 v[186:189], v199 offset:43040
	v_mfma_f32_32x32x16_bf16 v[96:111], v[190:193], v[180:183], v[96:111]
	ds_read_b128 v[224:227], v200 offset:43552
	s_waitcnt vmcnt(6)
	ds_write_b128 v202, v[152:155] offset:12288
	v_mfma_f32_32x32x16_bf16 v[32:47], v[190:193], v[194:197], v[32:47]
	ds_read_b128 v[190:193], v199 offset:45600
	v_mfma_f32_32x32x16_bf16 v[80:95], v[216:219], v[180:183], v[80:95]
	s_waitcnt vmcnt(5)
	ds_write_b128 v202, v[148:151] offset:22528
	v_mfma_f32_32x32x16_bf16 v[16:31], v[216:219], v[194:197], v[16:31]
	ds_read_b128 v[216:219], v199 offset:48160
	v_mfma_f32_32x32x16_bf16 v[64:79], v[176:179], v[180:183], v[64:79]
	s_waitcnt vmcnt(4)
	ds_write_b128 v202, v[156:159] offset:32768
	v_mfma_f32_32x32x16_bf16 v[0:15], v[176:179], v[194:197], v[0:15]
	ds_read_b128 v[176:179], v199 offset:50720
	s_waitcnt lgkmcnt(7)
	v_mfma_f32_32x32x16_bf16 v[112:127], v[186:189], v[220:223], v[112:127]
	ds_read_b128 v[180:183], v215
	s_waitcnt lgkmcnt(7)
	v_mfma_f32_32x32x16_bf16 v[48:63], v[186:189], v[224:227], v[48:63]
	ds_read_b128 v[186:189], v214
	s_waitcnt lgkmcnt(6)
	v_mfma_f32_32x32x16_bf16 v[96:111], v[190:193], v[220:223], v[96:111]
	ds_read_b128 v[194:197], v213
	v_mfma_f32_32x32x16_bf16 v[32:47], v[190:193], v[224:227], v[32:47]
	ds_read_b128 v[190:193], v212
	s_waitcnt lgkmcnt(6)
	v_mfma_f32_32x32x16_bf16 v[80:95], v[216:219], v[220:223], v[80:95]
	v_mfma_f32_32x32x16_bf16 v[16:31], v[216:219], v[224:227], v[16:31]
	ds_read_b128 v[212:215], v211
	s_waitcnt lgkmcnt(5)
	v_mfma_f32_32x32x16_bf16 v[64:79], v[176:179], v[220:223], v[64:79]
	v_mfma_f32_32x32x16_bf16 v[0:15], v[176:179], v[224:227], v[0:15]
	ds_read_b128 v[176:179], v210
	s_waitcnt lgkmcnt(0)
	s_barrier
	v_mfma_f32_32x32x16_bf16 v[112:127], v[186:189], v[180:183], v[112:127]
	ds_read_b128 v[216:219], v209
	s_waitcnt vmcnt(3)
	ds_write_b128 v202, v[160:163] offset:43008
	v_mfma_f32_32x32x16_bf16 v[48:63], v[186:189], v[194:197], v[48:63]
	ds_read_b128 v[186:189], v208
	v_mfma_f32_32x32x16_bf16 v[96:111], v[190:193], v[180:183], v[96:111]
	ds_read_b128 v[208:211], v207
	s_waitcnt vmcnt(2)
	ds_write_b128 v202, v[164:167] offset:53248
	v_mfma_f32_32x32x16_bf16 v[32:47], v[190:193], v[194:197], v[32:47]
	ds_read_b128 v[190:193], v206
	v_mfma_f32_32x32x16_bf16 v[80:95], v[212:215], v[180:183], v[80:95]
	s_waitcnt vmcnt(1)
	ds_write_b128 v202, v[168:171] offset:63488
	v_mfma_f32_32x32x16_bf16 v[16:31], v[212:215], v[194:197], v[16:31]
	ds_read_b128 v[212:215], v205
	v_mfma_f32_32x32x16_bf16 v[64:79], v[176:179], v[180:183], v[64:79]
	s_waitcnt vmcnt(0)
	ds_write_b128 v203, v[172:175]
	v_mfma_f32_32x32x16_bf16 v[0:15], v[176:179], v[194:197], v[0:15]
	ds_read_b128 v[176:179], v204
	s_waitcnt lgkmcnt(7)
	v_mfma_f32_32x32x16_bf16 v[112:127], v[186:189], v[216:219], v[112:127]
	ds_read_b128 v[180:183], v201 offset:22528
	s_waitcnt lgkmcnt(7)
	v_mfma_f32_32x32x16_bf16 v[48:63], v[186:189], v[208:211], v[48:63]
	ds_read_b128 v[186:189], v199 offset:2048
	s_waitcnt lgkmcnt(6)
	v_mfma_f32_32x32x16_bf16 v[96:111], v[190:193], v[216:219], v[96:111]
	ds_read_b128 v[194:197], v201 offset:25088
	v_mfma_f32_32x32x16_bf16 v[32:47], v[190:193], v[208:211], v[32:47]
	ds_read_b128 v[190:193], v199 offset:4608
	s_waitcnt lgkmcnt(6)
	v_mfma_f32_32x32x16_bf16 v[80:95], v[212:215], v[216:219], v[80:95]
	v_mfma_f32_32x32x16_bf16 v[16:31], v[212:215], v[208:211], v[16:31]
	ds_read_b128 v[202:205], v199 offset:7168
	s_waitcnt lgkmcnt(5)
	v_mfma_f32_32x32x16_bf16 v[64:79], v[176:179], v[216:219], v[64:79]
	v_mfma_f32_32x32x16_bf16 v[0:15], v[176:179], v[208:211], v[0:15]
	ds_read_b128 v[176:179], v199 offset:9728
	s_waitcnt lgkmcnt(0)
	s_barrier
; #define G_LOAD(pr, qr, kt_) if (MODE != 1) { _Pragma("unroll") for (int r = 0; r < NP; ++r) pr[r] = *(const u32x4*)(pp + (size_t)(r * 128) * ldp + (kt_) * BK); \
;                               _Pragma("unroll") for (int r = 0; r < NQ; ++r) qr[r] = *(const u32x4*)(qp + (size_t)(r * 128) * ldq + (kt_) * BK); }
;     ...
;     G_STORE(p0, q0, 0)
;     G_LOAD(p0, q0, 3)
;     G_STORE(p1, q1, STAGE)
;     __syncthreads();
;     F_LOAD(fa0, fb0, 0, 0)
;     int cur = 0, nxt = STAGE, wr = 2 * STAGE;
;     int kt = 0;
; #pragma unroll 1
;     for (; kt + 3 <= nk - 4; kt += 3) {
;         G_HALF(p1, q1, p2, q2, kt)
;         G_HALF(p2, q2, p0, q0, kt + 1)
;         G_HALF(p0, q0, p1, q1, kt + 2)
;     }
;     G_HALF(p1, q1, p2, q2, nk - 5)
;     G_HALF_NL(p0, q0, nk - 4)
;     G_HALF_NL(p1, q1, nk - 3)
;     G_HALF_NN(nk - 2)
;     G_HALF_NN(nk - 1)
; DI void phase3b(const Params& p, unsigned char* smem, int tid) {
;     ...
;     auto tile_ptrs = [&](int rb, const bf16_t*& P, const bf16_t*& Q) __attribute__((always_inline)) -> bool {
;         const int idp = rb + xcd * (per_round >> 3) + cu;
;         if (rb >= 16 * 64 || idp >= 16 * 64) return false;
;         const int half = idp >> 9, i9 = idp & 511, f = (i9 & 31) >> 2, tt = (i9 >> 5) * 4 + (i9 & 3);
;         P = (const bf16_t*)(ws + (half == 0 ? OFF_WZ : OFF_WG)) + (size_t)f * 256 * 1024;
;         Q = hb + (size_t)real_tile_row256(tt) * 1024;
;         return true;
;     };
;     GSets gs;
;     const bf16_t* Pn = nullptr; const bf16_t* Qn = nullptr;
;     bool vn = tile_ptrs(0, Pn, Qn);
;     if (vn) { int ti = tid; asm volatile("" : "+v"(ti)); gemm_issue(Pn, Qn, gs, ti); }
;     for (int rb = 0; rb < 16 * 64; rb += per_round) {
;         const int idp = rb + xcd * (per_round >> 3) + cu;
;         const bool v = vn;
;         const bf16_t* P = Pn; const bf16_t* Q = Qn;
;         if (!v) { vn = tile_ptrs(rb + per_round, Pn, Qn); if (vn) { int ti = tid; asm volatile("" : "+v"(ti)); gemm_issue(Pn, Qn, gs, ti); } continue; }
;         const int half = idp >> 9, i9 = idp & 511;
;         const int f = (i9 & 31) >> 2, tt = (i9 >> 5) * 4 + (i9 & 3);
;         const int r0 = real_tile_row256(tt);
;         f32x16 acc[4][2];
;         { int tl = tid; asm volatile("" : "+v"(tl));
;           gemm_tile3p<4, 4>(P, 1024, Q, 1024, lds, acc, tl, gs); }
;         vn = tile_ptrs(rb + per_round, Pn, Qn);
	v_mfma_f32_32x32x16_bf16 v[112:127], v[186:189], v[180:183], v[112:127]
	ds_read_b128 v[206:209], v201 offset:22560
	v_mfma_f32_32x32x16_bf16 v[48:63], v[186:189], v[194:197], v[48:63]
	ds_read_b128 v[186:189], v199 offset:2080
	v_mfma_f32_32x32x16_bf16 v[96:111], v[190:193], v[180:183], v[96:111]
	ds_read_b128 v[210:213], v201 offset:25120
	v_mfma_f32_32x32x16_bf16 v[32:47], v[190:193], v[194:197], v[32:47]
	ds_read_b128 v[190:193], v199 offset:4640
	v_mfma_f32_32x32x16_bf16 v[80:95], v[202:205], v[180:183], v[80:95]
	v_mfma_f32_32x32x16_bf16 v[16:31], v[202:205], v[194:197], v[16:31]
	ds_read_b128 v[202:205], v199 offset:7200
	v_mfma_f32_32x32x16_bf16 v[64:79], v[176:179], v[180:183], v[64:79]
	v_mfma_f32_32x32x16_bf16 v[0:15], v[176:179], v[194:197], v[0:15]
	ds_read_b128 v[176:179], v199 offset:9760
	s_waitcnt lgkmcnt(4)
	v_mfma_f32_32x32x16_bf16 v[112:127], v[186:189], v[206:209], v[112:127]
	ds_read_b128 v[180:183], v201 offset:63488
	s_waitcnt lgkmcnt(4)
	v_mfma_f32_32x32x16_bf16 v[48:63], v[186:189], v[210:213], v[48:63]
	ds_read_b128 v[186:189], v199 offset:43008
	s_waitcnt lgkmcnt(4)
	v_mfma_f32_32x32x16_bf16 v[96:111], v[190:193], v[206:209], v[96:111]
	ds_read_b128 v[194:197], v200 offset:43520
	v_mfma_f32_32x32x16_bf16 v[32:47], v[190:193], v[210:213], v[32:47]
	ds_read_b128 v[190:193], v199 offset:45568
	s_waitcnt lgkmcnt(5)
	v_mfma_f32_32x32x16_bf16 v[80:95], v[202:205], v[206:209], v[80:95]
	v_mfma_f32_32x32x16_bf16 v[16:31], v[202:205], v[210:213], v[16:31]
	ds_read_b128 v[202:205], v199 offset:48128
	s_waitcnt lgkmcnt(5)
	v_mfma_f32_32x32x16_bf16 v[64:79], v[176:179], v[206:209], v[64:79]
	v_mfma_f32_32x32x16_bf16 v[0:15], v[176:179], v[210:213], v[0:15]
	ds_read_b128 v[176:179], v199 offset:50688
	s_waitcnt lgkmcnt(0)
	s_barrier
	v_mfma_f32_32x32x16_bf16 v[112:127], v[186:189], v[180:183], v[112:127]
	ds_read_b128 v[206:209], v201 offset:63520
	v_mfma_f32_32x32x16_bf16 v[48:63], v[186:189], v[194:197], v[48:63]
	ds_read_b128 v[186:189], v199 offset:43040
	v_mfma_f32_32x32x16_bf16 v[96:111], v[190:193], v[180:183], v[96:111]
	ds_read_b128 v[210:213], v200 offset:43552
	v_mfma_f32_32x32x16_bf16 v[32:47], v[190:193], v[194:197], v[32:47]
	ds_read_b128 v[190:193], v199 offset:45600
	v_mfma_f32_32x32x16_bf16 v[80:95], v[202:205], v[180:183], v[80:95]
	v_mfma_f32_32x32x16_bf16 v[16:31], v[202:205], v[194:197], v[16:31]
	ds_read_b128 v[200:203], v199 offset:48160
	v_mfma_f32_32x32x16_bf16 v[64:79], v[176:179], v[180:183], v[64:79]
	v_mfma_f32_32x32x16_bf16 v[0:15], v[176:179], v[194:197], v[0:15]
	ds_read_b128 v[176:179], v199 offset:50720
	s_waitcnt lgkmcnt(4)
	v_mfma_f32_32x32x16_bf16 v[112:127], v[186:189], v[206:209], v[112:127]
	s_waitcnt lgkmcnt(3)
	v_mfma_f32_32x32x16_bf16 v[48:63], v[186:189], v[210:213], v[48:63]
	s_waitcnt lgkmcnt(2)
	v_mfma_f32_32x32x16_bf16 v[96:111], v[190:193], v[206:209], v[96:111]
	v_mfma_f32_32x32x16_bf16 v[32:47], v[190:193], v[210:213], v[32:47]
	s_waitcnt lgkmcnt(1)
	v_mfma_f32_32x32x16_bf16 v[80:95], v[200:203], v[206:209], v[80:95]
	v_mfma_f32_32x32x16_bf16 v[16:31], v[200:203], v[210:213], v[16:31]
	s_waitcnt lgkmcnt(0)
	v_mfma_f32_32x32x16_bf16 v[64:79], v[176:179], v[206:209], v[64:79]
	v_mfma_f32_32x32x16_bf16 v[0:15], v[176:179], v[210:213], v[0:15]
	s_add_i32 s38, s14, s2
	s_add_i32 s22, s38, s17
	s_max_i32 s23, s38, s22
	s_cmpk_lt_i32 s23, 0x400
	s_cselect_b64 s[20:21], -1, 0
	s_cmpk_gt_i32 s23, 0x3ff
	s_barrier
	s_cbranch_scc1 .LBB0_924
	s_lshr_b32 s8, s22, 3
	s_and_b32 s6, s8, 60
	s_and_b32 s7, s22, 3
	s_or_b32 s9, s6, s7
	s_cmpk_lt_u32 s22, 0x200
	s_cselect_b32 s6, s28, 0xdcfc00
	s_add_u32 s6, s56, s6
	s_addc_u32 s7, s57, 0
	s_lshl_b32 s22, s22, 17
	s_and_b32 s22, s22, 0x380000
	s_add_u32 s6, s6, s22
	s_addc_u32 s7, s7, 0
	s_bfe_u32 s8, s8, 0x20004
	s_lshl_b32 s9, s9, 8
	s_mulk_i32 s8, 0x1010
	s_and_b32 s9, s9, 0xf00
	s_add_i32 s8, s8, s9
	s_lshl_b32 s8, s8, 11
	s_add_i32 s8, s8, 0x8000
	s_add_u32 s8, s3, s8
	s_addc_u32 s9, s16, 0

; #define G_LOAD(pr, qr, kt_) if (MODE != 1) { _Pragma("unroll") for (int r = 0; r < NP; ++r) pr[r] = *(const u32x4*)(pp + (size_t)(r * 128) * ldp + (kt_) * BK); \
;                               _Pragma("unroll") for (int r = 0; r < NQ; ++r) qr[r] = *(const u32x4*)(qp + (size_t)(r * 128) * ldq + (kt_) * BK); }
; #define G_STORE(pr, qr, so_) { unsigned char* w_ = wP + (so_); \
;                               _Pragma("unroll") for (int r = 0; r < NP; ++r) *(u32x4*)(w_ + r * 128 * LROW) = pr[r]; \
;                               _Pragma("unroll") for (int r = 0; r < NQ; ++r) *(u32x4*)(w_ + BI * LROW + r * 128 * LROW) = qr[r]; }
;     ...
;     const bf16_t* pp = P + (size_t)lrow * ldp + lch * 8;
;     const bf16_t* qp = Q + (size_t)lrow * ldq + lch * 8;
;     unsigned char* wP = lds + lrow * LROW + lch * 16;
;     const unsigned char* rP = lds + (wi * WI * 32 + (lane & 31)) * LROW + (lane >> 5) * 16;
;     const unsigned char* rQ = lds + BI * LROW + (wj * 64 + (lane & 31)) * LROW + (lane >> 5) * 16;
;     u32x4 p0[NP], q0[NQ], p1[NP], q1[NQ], p2[NP], q2[NQ];
;     bf16x8 fa0[WI], fb0[2], fb1[2];
;     if (ZERO) {
; #pragma unroll
;         for (int it = 0; it < WI; ++it)
; #pragma unroll
;             for (int jt = 0; jt < 2; ++jt)
; #pragma unroll
;                 for (int r = 0; r < 16; ++r) acc[it][jt][r] = 0.f;
;     }
;     const int nk = K / BK;
;     ...
;     if (MODE == 1) {
; #pragma unroll
;         for (int r = 0; r < NP; ++r) { p0[r] = *(const u32x4*)(pp + (size_t)(r * 128) * ldp); p1[r] = p0[r]; p2[r] = p0[r]; }
; #pragma unroll
;         for (int r = 0; r < NQ; ++r) { q0[r] = *(const u32x4*)(qp + (size_t)(r * 128) * ldq); q1[r] = q0[r]; q2[r] = q0[r]; }
;     }
;     G_LOAD(p0, q0, 0)
;     G_LOAD(p1, q1, 1)
;     G_LOAD(p2, q2, 2)
;     G_STORE(p0, q0, 0)
;     G_LOAD(p0, q0, 3)
;     G_STORE(p1, q1, STAGE)
;     __syncthreads();
; DI void phase4(const Params& p, unsigned char* smem, int tid) {
;     ...
;         const int idp = rb + xcd * (per_round >> 3) + cu;
;         if (idp >= 4 * 64) continue;
;         const int f = (idp & 31) >> 3, tt = (idp >> 5) * 8 + (idp & 7);
;         const int r0 = real_tile_row256(tt);
;         f32x16 acc[4][2];
;         { int tl = tid; asm volatile("" : "+v"(tl));
;           gemm_tile3r<4, 4>((const bf16_t*)(ws + OFF_WBM) + (size_t)f * 256 * 1024, 1024, (const bf16_t*)(ws + OFF_QN) + (size_t)r0 * 1024, 1024, 1024, lds, acc, tl); }
.LBB0_991:
	s_add_i32 s6, s17, s52
	s_cmpk_gt_i32 s6, 0xff
	s_cbranch_scc1 .LBB0_990
	s_lshl_b32 s10, s51, 16
	s_and_b32 s54, s10, 0x180000
	s_and_b32 s10, s30, 7
	s_ashr_i32 s60, s6, 2
	s_lshl_b32 s15, s10, 8
	s_and_b32 s10, s60, -8
	s_and_b32 s11, s6, 7
	s_bfe_u32 s53, s6, 0x20003
	s_or_b32 s14, s10, s11
	s_ashr_i32 s6, s6, 6
	s_mulk_i32 s6, 0x1010
	s_lshl_b32 s10, s14, 8
	s_add_i32 s6, s6, 16
	s_and_b32 s10, s10, 0xf00
	s_add_i32 s10, s6, s10
	v_mov_b32_e32 v40, v220
	s_lshl_b32 s55, s53, 19
	s_add_u32 s12, s20, s55
	v_ashrrev_i32_e32 v32, 2, v40
	s_addc_u32 s13, s21, 0
	s_ashr_i32 s11, s10, 31
	v_ashrrev_i32_e32 v33, 31, v32
	s_lshl_b64 s[18:19], s[10:11], 11
	v_lshlrev_b64 v[34:35], 11, v[32:33]
	v_lshlrev_b32_e32 v2, 4, v40
	s_add_u32 s58, s22, s18
	v_and_b32_e32 v212, 48, v2
	v_lshl_add_u64 v[2:3], s[12:13], 0, v[34:35]
	s_mov_b64 s[98:99], s[12:13]
	s_addc_u32 s59, s23, s19
	v_lshl_add_u64 v[184:185], v[2:3], 0, v[212:213]
	v_add_u32_e32 v250, v34, v212
	v_add_u32_e32 v251, 0x40000, v250
	v_lshl_add_u64 v[0:1], s[58:59], 0, v[34:35]
	s_mov_b64 s[100:101], s[58:59]
	v_add_co_u32_e32 v36, vcc, s34, v184
	v_lshl_add_u64 v[186:187], v[0:1], 0, v[212:213]
	s_nop 0
	v_addc_co_u32_e32 v37, vcc, 0, v185, vcc
	v_add_co_u32_e32 v38, vcc, s34, v186
	v_ashrrev_i32_e32 v33, 6, v40
	s_nop 0
	v_addc_co_u32_e32 v39, vcc, 0, v187, vcc
	global_load_dwordx4 v[0:3], v[184:185], off
	global_load_dwordx4 v[4:7], v[184:185], off offset:64
	global_load_dwordx4 v[8:11], v[36:37], off
	global_load_dwordx4 v[12:15], v[36:37], off offset:64
	global_load_dwordx4 v[16:19], v[186:187], off
	global_load_dwordx4 v[20:23], v[186:187], off offset:64
	global_load_dwordx4 v[24:27], v[38:39], off
	global_load_dwordx4 v[28:31], v[38:39], off offset:64
	global_load_dwordx4 v[156:159], v[184:185], off offset:128
	global_load_dwordx4 v[140:143], v[184:185], off offset:192
	global_load_dwordx4 v[152:155], v[36:37], off offset:128
	global_load_dwordx4 v[136:139], v[36:37], off offset:192
	global_load_dwordx4 v[148:151], v[186:187], off offset:128
	global_load_dwordx4 v[132:135], v[186:187], off offset:192
	global_load_dwordx4 v[144:147], v[38:39], off offset:128
	global_load_dwordx4 v[128:131], v[38:39], off offset:192
	v_lshrrev_b32_e32 v42, 30, v33
	v_mul_lo_u32 v32, v32, s31
	v_add_u32_e32 v42, v33, v42
	v_and_b32_e32 v41, 31, v40
	v_add3_u32 v192, 0, v32, v212
	v_and_b32_e32 v32, 0x3ffffc, v42
	v_lshlrev_b32_e32 v42, 5, v42
	v_lshrrev_b32_e32 v40, 1, v40
	v_sub_u32_e32 v32, v33, v32
	v_and_or_b32 v33, v42, s33, v41
	v_and_b32_e32 v40, 16, v40
	v_mul_lo_u32 v33, v33, s31
	v_lshl_or_b32 v32, v32, 6, v41
	s_add_u32 s12, s56, s54
	v_mul_lo_u32 v32, v32, s31
	v_add3_u32 v193, 0, v33, v40
	s_addc_u32 s13, s57, 0
	v_add_u32_e32 v197, 0x12000, v192
	v_add3_u32 v195, 0, v32, v40
	v_lshl_add_u64 v[188:189], s[12:13], 0, v[34:35]
	s_lshl_b32 s12, s60, 8
	s_and_b32 s12, s12, 0x800
	s_or_b32 s12, s12, s15
	s_add_i32 s12, s6, s12
	s_ashr_i32 s13, s12, 31
	s_lshl_b64 s[12:13], s[12:13], 11
	s_add_u32 s58, s56, s12
	s_addc_u32 s59, s57, s13
	s_mov_b32 s11, 0
	v_add_u32_e32 v196, 0x19800, v192
	v_add_u32_e32 v194, 0x5800, v195
	v_add_u32_e32 v200, 0x14800, v192
	v_add_u32_e32 v201, 0x14800, v193
	v_add_u32_e32 v202, 0x19800, v195
	v_add_u32_e32 v199, 0x17000, v192
	v_add_u32_e32 v198, 0x1c000, v192
	v_add_u32_e32 v203, 0x1a200, v195
	v_add_u32_e32 v204, 0x15200, v193
	v_add_u32_e32 v205, 0x15c00, v193
	v_add_u32_e32 v206, 0x16600, v193
	v_add_u32_e32 v207, 0x19820, v195
	v_add_u32_e32 v208, 0x14820, v193
	v_add_u32_e32 v209, 0x1a220, v195
	v_add_u32_e32 v210, 0x15220, v193
	v_add_u32_e32 v211, 0x15c20, v193
	v_add_u32_e32 v214, 0x16620, v193
	v_lshl_add_u64 v[190:191], s[58:59], 0, v[34:35]
	s_waitcnt vmcnt(15)
	ds_write_b128 v192, v[0:3] offset:2048
	s_waitcnt vmcnt(14)
	ds_write_b128 v192, v[4:7] offset:43008
	s_waitcnt vmcnt(13)
	ds_write_b128 v192, v[8:11] offset:12288
	s_waitcnt vmcnt(12)
	ds_write_b128 v192, v[12:15] offset:53248
	s_waitcnt vmcnt(11)
	ds_write_b128 v192, v[16:19] offset:22528
	s_waitcnt vmcnt(10)
	ds_write_b128 v192, v[20:23] offset:63488
	s_waitcnt vmcnt(9)
	ds_write_b128 v192, v[24:27] offset:32768
	s_waitcnt vmcnt(8)
	ds_write_b128 v197, v[28:31]
	s_waitcnt lgkmcnt(0)
	s_barrier
; #define G_LOAD(pr, qr, kt_) if (MODE != 1) { _Pragma("unroll") for (int r = 0; r < NP; ++r) pr[r] = *(const u32x4*)(pp + (size_t)(r * 128) * ldp + (kt_) * BK); \
;                               _Pragma("unroll") for (int r = 0; r < NQ; ++r) qr[r] = *(const u32x4*)(qp + (size_t)(r * 128) * ldq + (kt_) * BK); }
; #define G_STORE(pr, qr, so_) { unsigned char* w_ = wP + (so_); \
;                               _Pragma("unroll") for (int r = 0; r < NP; ++r) *(u32x4*)(w_ + r * 128 * LROW) = pr[r]; \
;                               _Pragma("unroll") for (int r = 0; r < NQ; ++r) *(u32x4*)(w_ + BI * LROW + r * 128 * LROW) = qr[r]; }
; #define F_LOAD(fa, fb, so_, ks_) { _Pragma("unroll") for (int it = 0; it < WI; ++it) fa[it] = *(const bf16x8*)(rP + (so_) + it * 32 * LROW + (ks_) * 32); \
;                                   _Pragma("unroll") for (int jt = 0; jt < 2; ++jt) fb[jt] = *(const bf16x8*)(rQ + (so_) + jt * 32 * LROW + (ks_) * 32); }
; #define G_LOAD(pr, qr, kt_) if (MODE != 1) { _Pragma("unroll") for (int r = 0; r < NP; ++r) pr[r] = *(const u32x4*)(pp + (size_t)(r * 128) * ldp + (kt_) * BK); \
;                               _Pragma("unroll") for (int r = 0; r < NQ; ++r) qr[r] = *(const u32x4*)(qp + (size_t)(r * 128) * ldq + (kt_) * BK); }
;     ...
; #pragma unroll
;         for (int it = 0; it < WI; ++it)
; #pragma unroll
;             for (int jt = 0; jt < 2; ++jt)
; #pragma unroll
;                 for (int r = 0; r < 16; ++r) acc[it][jt][r] = 0.f;
;     }
;     const int nk = K / BK;
;     ...
;     if (MODE == 1) {
; #pragma unroll
;         for (int r = 0; r < NP; ++r) { p0[r] = *(const u32x4*)(pp + (size_t)(r * 128) * ldp); p1[r] = p0[r]; p2[r] = p0[r]; }
; #pragma unroll
;         for (int r = 0; r < NQ; ++r) { q0[r] = *(const u32x4*)(qp + (size_t)(r * 128) * ldq); q1[r] = q0[r]; q2[r] = q0[r]; }
;     }
;     G_LOAD(p0, q0, 0)
;     G_LOAD(p1, q1, 1)
;     G_LOAD(p2, q2, 2)
;     G_STORE(p0, q0, 0)
;     G_LOAD(p0, q0, 3)
;     G_STORE(p1, q1, STAGE)
;     __syncthreads();
;     F_LOAD(fa0, fb0, 0, 0)
;     int cur = 0, nxt = STAGE, wr = 2 * STAGE;
;     int kt = 0;
; #pragma unroll 1
;     for (; kt + 3 <= nk; kt += 3) {
;         G_HALF(p1, q1, p2, q2, kt)
;         G_HALF(p2, q2, p0, q0, kt + 1)
;         G_HALF(p0, q0, p1, q1, kt + 2)
	ds_read_b128 v[180:183], v193 offset:2048
	ds_read_b128 v[176:179], v193 offset:4608
	ds_read_b128 v[172:175], v193 offset:7168
	ds_read_b128 v[168:171], v193 offset:9728
	ds_read_b128 v[160:163], v195 offset:22528
	ds_read_b128 v[164:167], v195 offset:25088
	v_mov_b32_e32 v16, 0
	v_mov_b32_e32 v17, v16
	v_mov_b32_e32 v18, v16
	v_mov_b32_e32 v19, v16
	v_mov_b32_e32 v20, v16
	v_mov_b32_e32 v21, v16
	v_mov_b32_e32 v22, v16
	v_mov_b32_e32 v23, v16
	v_mov_b32_e32 v24, v16
	v_mov_b32_e32 v25, v16
	v_mov_b32_e32 v26, v16
	v_mov_b32_e32 v27, v16
	v_mov_b32_e32 v28, v16
	v_mov_b32_e32 v29, v16
	v_mov_b32_e32 v30, v16
	v_mov_b32_e32 v31, v16
	v_mov_b32_e32 v64, v16
	v_mov_b32_e32 v65, v16
	v_mov_b32_e32 v66, v16
	v_mov_b32_e32 v67, v16
	v_mov_b32_e32 v68, v16
	v_mov_b32_e32 v69, v16
	v_mov_b32_e32 v70, v16
	v_mov_b32_e32 v71, v16
	v_mov_b32_e32 v72, v16
	v_mov_b32_e32 v73, v16
	v_mov_b32_e32 v74, v16
	v_mov_b32_e32 v75, v16
	v_mov_b32_e32 v76, v16
	v_mov_b32_e32 v77, v16
	v_mov_b32_e32 v78, v16
	v_mov_b32_e32 v79, v16
	v_mov_b32_e32 v48, v16
	v_mov_b32_e32 v49, v16
	v_mov_b32_e32 v50, v16
	v_mov_b32_e32 v51, v16
	v_mov_b32_e32 v52, v16
	v_mov_b32_e32 v53, v16
	v_mov_b32_e32 v54, v16
	v_mov_b32_e32 v55, v16
	v_mov_b32_e32 v56, v16
	v_mov_b32_e32 v57, v16
	v_mov_b32_e32 v58, v16
	v_mov_b32_e32 v59, v16
	v_mov_b32_e32 v60, v16
	v_mov_b32_e32 v61, v16
	v_mov_b32_e32 v62, v16
	v_mov_b32_e32 v63, v16
	v_mov_b32_e32 v80, v16
	v_mov_b32_e32 v81, v16
	v_mov_b32_e32 v82, v16
	v_mov_b32_e32 v83, v16
	v_mov_b32_e32 v84, v16
	v_mov_b32_e32 v85, v16
	v_mov_b32_e32 v86, v16
	v_mov_b32_e32 v87, v16
	v_mov_b32_e32 v88, v16
	v_mov_b32_e32 v89, v16
	v_mov_b32_e32 v90, v16
	v_mov_b32_e32 v91, v16
	v_mov_b32_e32 v92, v16
	v_mov_b32_e32 v93, v16
	v_mov_b32_e32 v94, v16
	v_mov_b32_e32 v95, v16
	v_mov_b32_e32 v32, v16
	v_mov_b32_e32 v33, v16
	v_mov_b32_e32 v34, v16
	v_mov_b32_e32 v35, v16
	v_mov_b32_e32 v36, v16
	v_mov_b32_e32 v37, v16
	v_mov_b32_e32 v38, v16
	v_mov_b32_e32 v39, v16
	v_mov_b32_e32 v40, v16
	v_mov_b32_e32 v41, v16
	v_mov_b32_e32 v42, v16
	v_mov_b32_e32 v43, v16
	v_mov_b32_e32 v44, v16
	v_mov_b32_e32 v45, v16
	v_mov_b32_e32 v46, v16
	v_mov_b32_e32 v47, v16
	v_mov_b32_e32 v96, v16
	v_mov_b32_e32 v97, v16
	v_mov_b32_e32 v98, v16
	v_mov_b32_e32 v99, v16
	v_mov_b32_e32 v100, v16
	v_mov_b32_e32 v101, v16
	v_mov_b32_e32 v102, v16
	v_mov_b32_e32 v103, v16
	v_mov_b32_e32 v104, v16
	v_mov_b32_e32 v105, v16
	v_mov_b32_e32 v106, v16
	v_mov_b32_e32 v107, v16
	v_mov_b32_e32 v108, v16
	v_mov_b32_e32 v109, v16
	v_mov_b32_e32 v110, v16
	v_mov_b32_e32 v111, v16
	v_mov_b32_e32 v0, v16
	v_mov_b32_e32 v1, v16
	v_mov_b32_e32 v2, v16
	v_mov_b32_e32 v3, v16
	v_mov_b32_e32 v4, v16
	v_mov_b32_e32 v5, v16
	v_mov_b32_e32 v6, v16
	v_mov_b32_e32 v7, v16
	v_mov_b32_e32 v8, v16
	v_mov_b32_e32 v9, v16
	v_mov_b32_e32 v10, v16
	v_mov_b32_e32 v11, v16
	v_mov_b32_e32 v12, v16
	v_mov_b32_e32 v13, v16
	v_mov_b32_e32 v14, v16
	v_mov_b32_e32 v15, v16
	v_mov_b32_e32 v112, v16
	v_mov_b32_e32 v113, v16
	v_mov_b32_e32 v114, v16
	v_mov_b32_e32 v115, v16
	v_mov_b32_e32 v116, v16
	v_mov_b32_e32 v117, v16
	v_mov_b32_e32 v118, v16
	v_mov_b32_e32 v119, v16
	v_mov_b32_e32 v120, v16
	v_mov_b32_e32 v121, v16
	v_mov_b32_e32 v122, v16
	v_mov_b32_e32 v123, v16
	v_mov_b32_e32 v124, v16
	v_mov_b32_e32 v125, v16
	v_mov_b32_e32 v126, v16
	v_mov_b32_e32 v127, v16
	s_waitcnt lgkmcnt(0)
.LBB0_993:
	s_nop 0
	s_waitcnt lgkmcnt(4)
	v_mfma_f32_32x32x16_bf16 v[112:127], v[180:183], v[160:163], v[112:127]
	ds_read_b128 v[216:219], v195 offset:22560
	s_waitcnt vmcnt(7)
	ds_write_b128 v200, v[156:159]
	s_waitcnt lgkmcnt(5)
	v_mfma_f32_32x32x16_bf16 v[0:15], v[180:183], v[164:167], v[0:15]
	global_load_dwordx4 v[180:183], v250, s[98:99] offset:256
	ds_read_b128 v[156:159], v193 offset:2080
	s_waitcnt lgkmcnt(5)
	v_mfma_f32_32x32x16_bf16 v[96:111], v[176:179], v[160:163], v[96:111]
	ds_read_b128 v[222:225], v195 offset:25120
	s_waitcnt vmcnt(6)
	ds_write_b128 v199, v[152:155]
	v_mfma_f32_32x32x16_bf16 v[32:47], v[176:179], v[164:167], v[32:47]
	global_load_dwordx4 v[176:179], v251, s[98:99] offset:256
	ds_read_b128 v[152:155], v193 offset:4640
	s_waitcnt lgkmcnt(7)
	v_mfma_f32_32x32x16_bf16 v[80:95], v[172:175], v[160:163], v[80:95]
	s_waitcnt vmcnt(5)
	ds_write_b128 v196, v[148:151]
	v_mfma_f32_32x32x16_bf16 v[48:63], v[172:175], v[164:167], v[48:63]
	global_load_dwordx4 v[172:175], v250, s[100:101] offset:256
	ds_read_b128 v[148:151], v193 offset:7200
	s_waitcnt lgkmcnt(8)
	v_mfma_f32_32x32x16_bf16 v[64:79], v[168:171], v[160:163], v[64:79]
	s_waitcnt vmcnt(4)
	ds_write_b128 v198, v[144:147]
	v_mfma_f32_32x32x16_bf16 v[16:31], v[168:171], v[164:167], v[16:31]
	global_load_dwordx4 v[160:163], v251, s[100:101] offset:256
	ds_read_b128 v[144:147], v193 offset:9760
	s_waitcnt lgkmcnt(7)
	v_mfma_f32_32x32x16_bf16 v[112:127], v[156:159], v[216:219], v[112:127]
	ds_read_b128 v[164:167], v195 offset:63488
	s_waitcnt lgkmcnt(7)
	v_mfma_f32_32x32x16_bf16 v[0:15], v[156:159], v[222:225], v[0:15]
	ds_read_b128 v[156:159], v193 offset:43008
	s_waitcnt lgkmcnt(6)
	v_mfma_f32_32x32x16_bf16 v[96:111], v[152:155], v[216:219], v[96:111]
	ds_read_b128 v[168:171], v194 offset:43520
	v_mfma_f32_32x32x16_bf16 v[32:47], v[152:155], v[222:225], v[32:47]
	ds_read_b128 v[152:155], v193 offset:45568
	s_waitcnt lgkmcnt(6)
	v_mfma_f32_32x32x16_bf16 v[80:95], v[148:151], v[216:219], v[80:95]
	v_mfma_f32_32x32x16_bf16 v[48:63], v[148:151], v[222:225], v[48:63]
	ds_read_b128 v[148:151], v193 offset:48128
	s_waitcnt lgkmcnt(5)
	v_mfma_f32_32x32x16_bf16 v[64:79], v[144:147], v[216:219], v[64:79]
	v_mfma_f32_32x32x16_bf16 v[16:31], v[144:147], v[222:225], v[16:31]
	ds_read_b128 v[144:147], v193 offset:50688
	s_barrier
; #define G_LOAD(pr, qr, kt_) if (MODE != 1) { _Pragma("unroll") for (int r = 0; r < NP; ++r) pr[r] = *(const u32x4*)(pp + (size_t)(r * 128) * ldp + (kt_) * BK); \
;                               _Pragma("unroll") for (int r = 0; r < NQ; ++r) qr[r] = *(const u32x4*)(qp + (size_t)(r * 128) * ldq + (kt_) * BK); }
; #define G_STORE(pr, qr, so_) { unsigned char* w_ = wP + (so_); \
;                               _Pragma("unroll") for (int r = 0; r < NP; ++r) *(u32x4*)(w_ + r * 128 * LROW) = pr[r]; \
;                               _Pragma("unroll") for (int r = 0; r < NQ; ++r) *(u32x4*)(w_ + BI * LROW + r * 128 * LROW) = qr[r]; }
; #define F_LOAD(fa, fb, so_, ks_) { _Pragma("unroll") for (int it = 0; it < WI; ++it) fa[it] = *(const bf16x8*)(rP + (so_) + it * 32 * LROW + (ks_) * 32); \
;                                   _Pragma("unroll") for (int jt = 0; jt < 2; ++jt) fb[jt] = *(const bf16x8*)(rQ + (so_) + jt * 32 * LROW + (ks_) * 32); }
; #define G_LOAD(pr, qr, kt_) if (MODE != 1) { _Pragma("unroll") for (int r = 0; r < NP; ++r) pr[r] = *(const u32x4*)(pp + (size_t)(r * 128) * ldp + (kt_) * BK); \
;                               _Pragma("unroll") for (int r = 0; r < NQ; ++r) qr[r] = *(const u32x4*)(qp + (size_t)(r * 128) * ldq + (kt_) * BK); }
; #define G_STORE(pr, qr, so_) { unsigned char* w_ = wP + (so_); \
;                               _Pragma("unroll") for (int r = 0; r < NP; ++r) *(u32x4*)(w_ + r * 128 * LROW) = pr[r]; \
;                               _Pragma("unroll") for (int r = 0; r < NQ; ++r) *(u32x4*)(w_ + BI * LROW + r * 128 * LROW) = qr[r]; }
;     ...
;     if (MODE == 1) {
; #pragma unroll
;         for (int r = 0; r < NP; ++r) { p0[r] = *(const u32x4*)(pp + (size_t)(r * 128) * ldp); p1[r] = p0[r]; p2[r] = p0[r]; }
; #pragma unroll
;         for (int r = 0; r < NQ; ++r) { q0[r] = *(const u32x4*)(qp + (size_t)(r * 128) * ldq); q1[r] = q0[r]; q2[r] = q0[r]; }
;     }
;     G_LOAD(p0, q0, 0)
;     G_LOAD(p1, q1, 1)
;     G_LOAD(p2, q2, 2)
;     G_STORE(p0, q0, 0)
;     G_LOAD(p0, q0, 3)
;     G_STORE(p1, q1, STAGE)
;     __syncthreads();
;     F_LOAD(fa0, fb0, 0, 0)
;     int cur = 0, nxt = STAGE, wr = 2 * STAGE;
;     int kt = 0;
; #pragma unroll 1
;     for (; kt + 3 <= nk; kt += 3) {
;         G_HALF(p1, q1, p2, q2, kt)
;         G_HALF(p2, q2, p0, q0, kt + 1)
;         G_HALF(p0, q0, p1, q1, kt + 2)
;     }
	s_min_u32 s6, s11, 26
	s_waitcnt lgkmcnt(4)
	v_mfma_f32_32x32x16_bf16 v[112:127], v[156:159], v[164:167], v[112:127]
	ds_read_b128 v[216:219], v195 offset:63520
	ds_write_b128 v192, v[140:143] offset:2048
	s_waitcnt lgkmcnt(5)
	v_mfma_f32_32x32x16_bf16 v[0:15], v[156:159], v[168:171], v[0:15]
	global_load_dwordx4 v[156:159], v250, s[98:99] offset:320
	ds_read_b128 v[140:143], v193 offset:43040
	s_waitcnt lgkmcnt(5)
	v_mfma_f32_32x32x16_bf16 v[96:111], v[152:155], v[164:167], v[96:111]
	ds_read_b128 v[222:225], v194 offset:43552
	ds_write_b128 v192, v[136:139] offset:12288
	v_mfma_f32_32x32x16_bf16 v[32:47], v[152:155], v[168:171], v[32:47]
	global_load_dwordx4 v[152:155], v251, s[98:99] offset:320
	ds_read_b128 v[136:139], v193 offset:45600
	s_waitcnt lgkmcnt(7)
	v_mfma_f32_32x32x16_bf16 v[80:95], v[148:151], v[164:167], v[80:95]
	ds_write_b128 v192, v[132:135] offset:22528
	v_mfma_f32_32x32x16_bf16 v[48:63], v[148:151], v[168:171], v[48:63]
	global_load_dwordx4 v[148:151], v250, s[100:101] offset:320
	ds_read_b128 v[132:135], v193 offset:48160
	s_waitcnt lgkmcnt(8)
	v_mfma_f32_32x32x16_bf16 v[64:79], v[144:147], v[164:167], v[64:79]
	s_waitcnt vmcnt(7)
	ds_write_b128 v192, v[128:131] offset:32768
	v_mfma_f32_32x32x16_bf16 v[16:31], v[144:147], v[168:171], v[16:31]
	global_load_dwordx4 v[144:147], v251, s[100:101] offset:320
	ds_read_b128 v[128:131], v193 offset:50720
	s_waitcnt lgkmcnt(7)
	v_mfma_f32_32x32x16_bf16 v[112:127], v[140:143], v[216:219], v[112:127]
	ds_read_b128 v[164:167], v202
	s_waitcnt lgkmcnt(7)
	v_mfma_f32_32x32x16_bf16 v[0:15], v[140:143], v[222:225], v[0:15]
	ds_read_b128 v[140:143], v201
	s_waitcnt lgkmcnt(6)
	v_mfma_f32_32x32x16_bf16 v[96:111], v[136:139], v[216:219], v[96:111]
	ds_read_b128 v[168:171], v203
	v_mfma_f32_32x32x16_bf16 v[32:47], v[136:139], v[222:225], v[32:47]
	ds_read_b128 v[136:139], v204
	s_waitcnt lgkmcnt(6)
	v_mfma_f32_32x32x16_bf16 v[80:95], v[132:135], v[216:219], v[80:95]
	v_mfma_f32_32x32x16_bf16 v[48:63], v[132:135], v[222:225], v[48:63]
	ds_read_b128 v[132:135], v205
	s_waitcnt lgkmcnt(5)
	v_mfma_f32_32x32x16_bf16 v[64:79], v[128:131], v[216:219], v[64:79]
	v_mfma_f32_32x32x16_bf16 v[16:31], v[128:131], v[222:225], v[16:31]
	ds_read_b128 v[128:131], v206
	s_barrier
	s_min_u32 s6, s11, 25
	s_waitcnt lgkmcnt(4)
	v_mfma_f32_32x32x16_bf16 v[112:127], v[140:143], v[164:167], v[112:127]
	ds_read_b128 v[216:219], v207
	s_waitcnt vmcnt(7)
	ds_write_b128 v192, v[180:183] offset:43008
	s_waitcnt lgkmcnt(5)
	v_mfma_f32_32x32x16_bf16 v[0:15], v[140:143], v[168:171], v[0:15]
	global_load_dwordx4 v[140:143], v250, s[98:99] offset:384
	ds_read_b128 v[180:183], v208
	s_waitcnt lgkmcnt(5)
	v_mfma_f32_32x32x16_bf16 v[96:111], v[136:139], v[164:167], v[96:111]
	ds_read_b128 v[222:225], v209
	s_waitcnt vmcnt(7)
	ds_write_b128 v192, v[176:179] offset:53248
	v_mfma_f32_32x32x16_bf16 v[32:47], v[136:139], v[168:171], v[32:47]
	ds_read_b128 v[176:179], v210
	global_load_dwordx4 v[136:139], v251, s[98:99] offset:384
	s_waitcnt lgkmcnt(7)
	v_mfma_f32_32x32x16_bf16 v[80:95], v[132:135], v[164:167], v[80:95]
	s_waitcnt vmcnt(7)
	ds_write_b128 v192, v[172:175] offset:63488
	v_mfma_f32_32x32x16_bf16 v[48:63], v[132:135], v[168:171], v[48:63]
	global_load_dwordx4 v[132:135], v250, s[100:101] offset:384
	ds_read_b128 v[172:175], v211
	s_waitcnt lgkmcnt(8)
	v_mfma_f32_32x32x16_bf16 v[64:79], v[128:131], v[164:167], v[64:79]
	s_waitcnt vmcnt(7)
	ds_write_b128 v197, v[160:163]
	v_mfma_f32_32x32x16_bf16 v[16:31], v[128:131], v[168:171], v[16:31]
	ds_read_b128 v[168:171], v214
	global_load_dwordx4 v[128:131], v251, s[100:101] offset:384
	s_waitcnt lgkmcnt(7)
	v_mfma_f32_32x32x16_bf16 v[112:127], v[180:183], v[216:219], v[112:127]
	ds_read_b128 v[160:163], v195 offset:22528
	s_waitcnt lgkmcnt(7)
	v_mfma_f32_32x32x16_bf16 v[0:15], v[180:183], v[222:225], v[0:15]
	ds_read_b128 v[180:183], v193 offset:2048
	s_waitcnt lgkmcnt(6)
	v_mfma_f32_32x32x16_bf16 v[96:111], v[176:179], v[216:219], v[96:111]
	ds_read_b128 v[164:167], v195 offset:25088
	v_mfma_f32_32x32x16_bf16 v[32:47], v[176:179], v[222:225], v[32:47]
	ds_read_b128 v[176:179], v193 offset:4608
	s_waitcnt lgkmcnt(6)
	v_mfma_f32_32x32x16_bf16 v[80:95], v[172:175], v[216:219], v[80:95]
	v_mfma_f32_32x32x16_bf16 v[48:63], v[172:175], v[222:225], v[48:63]
	ds_read_b128 v[172:175], v193 offset:7168
	s_waitcnt lgkmcnt(5)
	v_mfma_f32_32x32x16_bf16 v[64:79], v[168:171], v[216:219], v[64:79]
	v_mfma_f32_32x32x16_bf16 v[16:31], v[168:171], v[222:225], v[16:31]
	ds_read_b128 v[168:171], v193 offset:9728
	s_add_i32 s11, s11, 3
	v_add_u32_e32 v250, 0xc0, v250
	s_cmp_lt_u32 s11, 30
	v_add_u32_e32 v251, 0xc0, v251
	s_barrier
	s_cbranch_scc1 .LBB0_993
; DI float bf_lo(unsigned u) { return __uint_as_float(u << 16); }
; DI float bf_hi(unsigned u) { return __uint_as_float(u & 0xffff0000u); }
; #define G_HALF(pl, ql, ps, qs, kt_) { const int k4_ = min((kt_) + 4, nk - 1); \
;         SB R_BURST1(fb0, fb1, cur, 1, pl, ql, k4_, ps, qs, wr) R_BURST2(fb1, fb0, nxt, 0, ps, qs, wr) \
;         __syncthreads(); { const int t_ = cur; cur = nxt; nxt = wr; wr = t_; } }
;     ...
;     if (MODE == 1) {
; #pragma unroll
;         for (int r = 0; r < NP; ++r) { p0[r] = *(const u32x4*)(pp + (size_t)(r * 128) * ldp); p1[r] = p0[r]; p2[r] = p0[r]; }
; #pragma unroll
;         for (int r = 0; r < NQ; ++r) { q0[r] = *(const u32x4*)(qp + (size_t)(r * 128) * ldq); q1[r] = q0[r]; q2[r] = q0[r]; }
;     }
;     G_LOAD(p0, q0, 0)
;     G_LOAD(p1, q1, 1)
;     G_LOAD(p2, q2, 2)
;     G_STORE(p0, q0, 0)
;     G_LOAD(p0, q0, 3)
;     G_STORE(p1, q1, STAGE)
;     __syncthreads();
;     F_LOAD(fa0, fb0, 0, 0)
;     int cur = 0, nxt = STAGE, wr = 2 * STAGE;
;     int kt = 0;
; #pragma unroll 1
;     for (; kt + 3 <= nk; kt += 3) {
;         G_HALF(p1, q1, p2, q2, kt)
;         G_HALF(p2, q2, p0, q0, kt + 1)
;         G_HALF(p0, q0, p1, q1, kt + 2)
;     }
;     if (kt < nk) G_HALF(p1, q1, p2, q2, kt)
;     if (kt + 1 < nk) G_HALF(p2, q2, p0, q0, kt + 1)
; DI void phase4(const Params& p, unsigned char* smem, int tid) {
;     ...
;         {
;             int te = tid; asm volatile("" : "+v"(te));
;             const unsigned char* ga = ws + OFF_G + ((size_t)(f * 64 + tt) * 8 + (te >> 6)) * 16384 + (te & 63) * 16;
;             const unsigned char* gb = ga + (size_t)4 * 64 * 8 * 16384;
; #pragma unroll
;             for (int it = 0; it < 4; ++it)
; #pragma unroll
;                 for (int jt = 0; jt < 2; ++jt)
; #pragma unroll
;                     for (int gp = 0; gp < 2; ++gp) {
;                         const u32x4 a4 = *(const u32x4*)(ga + ((it * 2 + jt) * 2 + gp) * 1024), b4 = *(const u32x4*)(gb + ((it * 2 + jt) * 2 + gp) * 1024);
; #pragma unroll
;                         for (int e = 0; e < 4; ++e) {
;                             acc[it][jt][8 * gp + 2 * e] *= bf_lo(a4[e]) * __builtin_amdgcn_rcpf(fmaxf(bf_lo(b4[e]), 8.6736174e-19f));
;                             acc[it][jt][8 * gp + 2 * e + 1] *= bf_hi(a4[e]) * __builtin_amdgcn_rcpf(fmaxf(bf_hi(b4[e]), 8.6736174e-19f));
;                         }
;                     }
;         }
	s_waitcnt lgkmcnt(0)
	v_mfma_f32_32x32x16_bf16 v[112:127], v[180:183], v[160:163], v[112:127]
	ds_read_b128 v[184:187], v195 offset:22560
	s_waitcnt vmcnt(7)
	ds_write_b128 v200, v[156:159]
	v_mfma_f32_32x32x16_bf16 v[0:15], v[180:183], v[164:167], v[0:15]
	ds_read_b128 v[156:159], v193 offset:2080
	v_mfma_f32_32x32x16_bf16 v[96:111], v[176:179], v[160:163], v[96:111]
	ds_read_b128 v[180:183], v195 offset:25120
	s_waitcnt vmcnt(6)
	ds_write_b128 v199, v[152:155]
	v_mfma_f32_32x32x16_bf16 v[32:47], v[176:179], v[164:167], v[32:47]
	ds_read_b128 v[152:155], v193 offset:4640
	v_mfma_f32_32x32x16_bf16 v[80:95], v[172:175], v[160:163], v[80:95]
	s_waitcnt vmcnt(5)
	ds_write_b128 v196, v[148:151]
	v_mfma_f32_32x32x16_bf16 v[48:63], v[172:175], v[164:167], v[48:63]
	ds_read_b128 v[148:151], v193 offset:7200
	v_mfma_f32_32x32x16_bf16 v[64:79], v[168:171], v[160:163], v[64:79]
	s_waitcnt vmcnt(4)
	ds_write_b128 v198, v[144:147]
	v_mfma_f32_32x32x16_bf16 v[16:31], v[168:171], v[164:167], v[16:31]
	ds_read_b128 v[144:147], v193 offset:9760
	s_waitcnt lgkmcnt(7)
	v_mfma_f32_32x32x16_bf16 v[112:127], v[156:159], v[184:187], v[112:127]
	ds_read_b128 v[160:163], v195 offset:63488
	s_waitcnt lgkmcnt(7)
	v_mfma_f32_32x32x16_bf16 v[0:15], v[156:159], v[180:183], v[0:15]
	ds_read_b128 v[156:159], v193 offset:43008
	s_waitcnt lgkmcnt(6)
	v_mfma_f32_32x32x16_bf16 v[96:111], v[152:155], v[184:187], v[96:111]
	ds_read_b128 v[164:167], v194 offset:43520
	v_mfma_f32_32x32x16_bf16 v[32:47], v[152:155], v[180:183], v[32:47]
	ds_read_b128 v[152:155], v193 offset:45568
	s_waitcnt lgkmcnt(6)
	v_mfma_f32_32x32x16_bf16 v[80:95], v[148:151], v[184:187], v[80:95]
	v_mfma_f32_32x32x16_bf16 v[48:63], v[148:151], v[180:183], v[48:63]
	ds_read_b128 v[148:151], v193 offset:48128
	s_waitcnt lgkmcnt(5)
	v_mfma_f32_32x32x16_bf16 v[64:79], v[144:147], v[184:187], v[64:79]
	v_mfma_f32_32x32x16_bf16 v[16:31], v[144:147], v[180:183], v[16:31]
	ds_read_b128 v[144:147], v193 offset:50688
	s_waitcnt lgkmcnt(0)
	s_barrier
	v_mfma_f32_32x32x16_bf16 v[112:127], v[156:159], v[160:163], v[112:127]
	ds_read_b128 v[168:171], v195 offset:63520
	s_waitcnt vmcnt(3)
	ds_write_b128 v192, v[140:143] offset:2048
	v_mfma_f32_32x32x16_bf16 v[0:15], v[156:159], v[164:167], v[0:15]
	ds_read_b128 v[140:143], v193 offset:43040
	v_mfma_f32_32x32x16_bf16 v[96:111], v[152:155], v[160:163], v[96:111]
	ds_read_b128 v[156:159], v194 offset:43552
	s_waitcnt vmcnt(2)
	ds_write_b128 v192, v[136:139] offset:12288
	v_mfma_f32_32x32x16_bf16 v[32:47], v[152:155], v[164:167], v[32:47]
	ds_read_b128 v[136:139], v193 offset:45600
	v_mfma_f32_32x32x16_bf16 v[80:95], v[148:151], v[160:163], v[80:95]
	s_waitcnt vmcnt(1)
	ds_write_b128 v192, v[132:135] offset:22528
	v_mfma_f32_32x32x16_bf16 v[48:63], v[148:151], v[164:167], v[48:63]
	ds_read_b128 v[132:135], v193 offset:48160
	v_mfma_f32_32x32x16_bf16 v[64:79], v[144:147], v[160:163], v[64:79]
	s_waitcnt vmcnt(0)
	ds_write_b128 v192, v[128:131] offset:32768
	v_mfma_f32_32x32x16_bf16 v[16:31], v[144:147], v[164:167], v[16:31]
	ds_read_b128 v[128:131], v193 offset:50720
	s_waitcnt lgkmcnt(7)
	v_mfma_f32_32x32x16_bf16 v[112:127], v[140:143], v[168:171], v[112:127]
	s_waitcnt lgkmcnt(6)
	v_mfma_f32_32x32x16_bf16 v[0:15], v[140:143], v[156:159], v[0:15]
	s_waitcnt lgkmcnt(4)
	v_mfma_f32_32x32x16_bf16 v[96:111], v[136:139], v[168:171], v[96:111]
	v_mfma_f32_32x32x16_bf16 v[32:47], v[136:139], v[156:159], v[32:47]
	s_waitcnt lgkmcnt(2)
	v_mfma_f32_32x32x16_bf16 v[80:95], v[132:135], v[168:171], v[80:95]
	v_mfma_f32_32x32x16_bf16 v[48:63], v[132:135], v[156:159], v[48:63]
	s_waitcnt lgkmcnt(0)
	v_mfma_f32_32x32x16_bf16 v[64:79], v[128:131], v[168:171], v[64:79]
	v_mfma_f32_32x32x16_bf16 v[16:31], v[128:131], v[156:159], v[16:31]
	s_lshl_b32 s6, s53, 6
	s_add_i32 s14, s6, s14
	v_mov_b32_e32 v130, v220
	s_ashr_i32 s15, s14, 31
	s_barrier
	s_lshl_b64 s[58:59], s[14:15], 17
	v_ashrrev_i32_e32 v128, 6, v130
	v_ashrrev_i32_e32 v129, 31, v128
	s_add_u32 s58, s24, s58
	v_lshlrev_b64 v[128:129], 14, v[128:129]
	s_addc_u32 s59, s25, s59
	v_lshlrev_b32_e32 v130, 4, v130
	v_lshl_add_u64 v[128:129], s[58:59], 0, v[128:129]
	v_and_b32_e32 v212, 0x3f0, v130
	v_lshl_add_u64 v[152:153], v[128:129], 0, v[212:213]
	v_add_co_u32_e32 v154, vcc, s41, v152
	global_load_dwordx4 v[132:135], v[152:153], off
	global_load_dwordx4 v[128:131], v[152:153], off offset:1024
	v_addc_co_u32_e32 v155, vcc, 0, v153, vcc
	global_load_dwordx4 v[144:147], v[154:155], off offset:-4096
	global_load_dwordx4 v[140:143], v[152:153], off offset:2048
	v_add_co_u32_e32 v156, vcc, s39, v152
	v_mov_b32_e32 v210, v220
	s_nop 0
	v_addc_co_u32_e32 v157, vcc, 0, v153, vcc
	global_load_dwordx4 v[136:139], v[156:157], off offset:1024
	v_add_co_u32_e32 v158, vcc, s44, v152
	s_add_u32 s58, s26, s55
	s_nop 0
	v_addc_co_u32_e32 v159, vcc, 0, v153, vcc
	global_load_dwordx4 v[148:151], v[156:157], off offset:2048
	global_load_dwordx4 v[178:181], v[158:159], off offset:3072
	s_addc_u32 s59, s27, 0
	s_add_u32 s18, s28, s18
	s_addc_u32 s19, s29, s19
	s_mov_b32 s11, 0
	s_waitcnt vmcnt(6)
	v_lshlrev_b32_e32 v160, 16, v132
	s_waitcnt vmcnt(5)
	v_lshlrev_b32_e32 v164, 16, v128
	v_and_b32_e32 v165, 0xffff0000, v128
	v_and_b32_e32 v161, 0xffff0000, v132
	s_waitcnt vmcnt(4)
	v_lshlrev_b32_e32 v166, 16, v145
	v_and_b32_e32 v145, 0xffff0000, v145
	v_lshlrev_b32_e32 v167, 16, v146
	v_and_b32_e32 v146, 0xffff0000, v146
	v_lshlrev_b32_e32 v168, 16, v147
	v_and_b32_e32 v147, 0xffff0000, v147
	v_max_f32_e32 v166, v166, v166
	v_max_f32_e32 v145, v145, v145
	v_max_f32_e32 v146, v146, v146
	v_max_f32_e32 v147, v147, v147
	v_max_f32_e32 v166, 0x21800000, v166
	v_max_f32_e32 v171, 0x21800000, v145
	v_lshlrev_b32_e32 v128, 16, v144
	v_max_f32_e32 v173, 0x21800000, v146
	v_max_f32_e32 v174, 0x21800000, v147
	v_rcp_f32_e32 v146, v166
	v_rcp_f32_e32 v147, v171
	v_and_b32_e32 v144, 0xffff0000, v144
	v_max_f32_e32 v128, v128, v128
	s_waitcnt vmcnt(2)
; DI float bf_lo(unsigned u) { return __uint_as_float(u << 16); }
; DI float bf_hi(unsigned u) { return __uint_as_float(u & 0xffff0000u); }
; DI void phase4(const Params& p, unsigned char* smem, int tid) {
;     ...
;             const unsigned char* ga = ws + OFF_G + ((size_t)(f * 64 + tt) * 8 + (te >> 6)) * 16384 + (te & 63) * 16;
;             const unsigned char* gb = ga + (size_t)4 * 64 * 8 * 16384;
; #pragma unroll
;             for (int it = 0; it < 4; ++it)
; #pragma unroll
;                 for (int jt = 0; jt < 2; ++jt)
; #pragma unroll
;                     for (int gp = 0; gp < 2; ++gp) {
;                         const u32x4 a4 = *(const u32x4*)(ga + ((it * 2 + jt) * 2 + gp) * 1024), b4 = *(const u32x4*)(gb + ((it * 2 + jt) * 2 + gp) * 1024);
; #pragma unroll
;                         for (int e = 0; e < 4; ++e) {
;                             acc[it][jt][8 * gp + 2 * e] *= bf_lo(a4[e]) * __builtin_amdgcn_rcpf(fmaxf(bf_lo(b4[e]), 8.6736174e-19f));
;                             acc[it][jt][8 * gp + 2 * e + 1] *= bf_hi(a4[e]) * __builtin_amdgcn_rcpf(fmaxf(bf_hi(b4[e]), 8.6736174e-19f));
;                         }
;                     }
;         }
	v_lshlrev_b32_e32 v172, 16, v137
	v_max_f32_e32 v144, v144, v144
	v_max_f32_e32 v128, 0x21800000, v128
	v_lshlrev_b32_e32 v132, 16, v133
	v_and_b32_e32 v133, 0xffff0000, v133
	v_max_f32_e32 v170, 0x21800000, v144
	v_rcp_f32_e32 v144, v128
	v_max_f32_e32 v128, v172, v172
	v_pk_mul_f32 v[132:133], v[146:147], v[132:133]
	v_max_f32_e32 v128, 0x21800000, v128
	v_pk_mul_f32 v[114:115], v[114:115], v[132:133]
	v_rcp_f32_e32 v132, v128
	v_and_b32_e32 v128, 0xffff0000, v137
	v_max_f32_e32 v128, v128, v128
	v_max_f32_e32 v128, 0x21800000, v128
	v_lshlrev_b32_e32 v169, 16, v136
	v_max_f32_e32 v168, v168, v168
	v_rcp_f32_e32 v133, v128
	v_max_f32_e32 v169, v169, v169
	v_max_f32_e32 v168, 0x21800000, v168
	v_max_f32_e32 v175, 0x21800000, v169
	v_rcp_f32_e32 v168, v168
	v_rcp_f32_e32 v169, v174
	v_lshlrev_b32_e32 v128, 16, v129
	v_and_b32_e32 v129, 0xffff0000, v129
	v_and_b32_e32 v136, 0xffff0000, v136
	v_pk_mul_f32 v[128:129], v[132:133], v[128:129]
	v_lshlrev_b32_e32 v132, 16, v138
	v_lshlrev_b32_e32 v162, 16, v134
	v_and_b32_e32 v163, 0xffff0000, v134
	v_lshlrev_b32_e32 v134, 16, v135
	v_and_b32_e32 v135, 0xffff0000, v135
	v_max_f32_e32 v136, v136, v136
	v_max_f32_e32 v132, v132, v132
	v_max_f32_e32 v167, v167, v167
	v_max_f32_e32 v136, 0x21800000, v136
	v_pk_mul_f32 v[134:135], v[168:169], v[134:135]
	v_max_f32_e32 v132, 0x21800000, v132
	v_max_f32_e32 v167, 0x21800000, v167
	v_rcp_f32_e32 v171, v136
	v_pk_mul_f32 v[118:119], v[118:119], v[134:135]
	v_rcp_f32_e32 v136, v132
	global_load_dwordx4 v[132:135], v[156:157], off offset:3072
	v_rcp_f32_e32 v145, v170
	v_rcp_f32_e32 v166, v167
	v_rcp_f32_e32 v167, v173
	v_and_b32_e32 v137, 0xffff0000, v138
	v_pk_mul_f32 v[144:145], v[144:145], v[160:161]
	v_max_f32_e32 v137, v137, v137
	v_pk_mul_f32 v[146:147], v[166:167], v[162:163]
	v_pk_mul_f32 v[112:113], v[112:113], v[144:145]
	v_pk_mul_f32 v[116:117], v[116:117], v[146:147]
	global_load_dwordx4 v[144:147], v[152:153], off offset:3072
	v_max_f32_e32 v137, 0x21800000, v137
	v_rcp_f32_e32 v137, v137
	v_pk_mul_f32 v[122:123], v[122:123], v[128:129]
	v_lshlrev_b32_e32 v128, 16, v130
	v_and_b32_e32 v129, 0xffff0000, v130
	v_lshlrev_b32_e32 v130, 16, v139
	v_max_f32_e32 v130, v130, v130
	v_max_f32_e32 v130, 0x21800000, v130
	v_pk_mul_f32 v[128:129], v[136:137], v[128:129]
	v_rcp_f32_e32 v136, v130
	v_and_b32_e32 v130, 0xffff0000, v139
	v_max_f32_e32 v130, v130, v130
	v_max_f32_e32 v130, 0x21800000, v130
	v_rcp_f32_e32 v137, v130
	v_pk_mul_f32 v[124:125], v[124:125], v[128:129]
	v_lshlrev_b32_e32 v128, 16, v131
	v_and_b32_e32 v129, 0xffff0000, v131
	s_waitcnt vmcnt(3)
	v_lshlrev_b32_e32 v130, 16, v148
	v_and_b32_e32 v131, 0xffff0000, v148
	v_max_f32_e32 v130, v130, v130
	v_max_f32_e32 v131, v131, v131
	v_max_f32_e32 v130, 0x21800000, v130
	v_max_f32_e32 v131, 0x21800000, v131
	v_rcp_f32_e32 v130, v130
	v_rcp_f32_e32 v131, v131
	v_pk_mul_f32 v[128:129], v[136:137], v[128:129]
	global_load_dwordx4 v[136:139], v[154:155], off
	v_pk_mul_f32 v[126:127], v[126:127], v[128:129]
	v_lshlrev_b32_e32 v128, 16, v140
	v_and_b32_e32 v129, 0xffff0000, v140
	v_pk_mul_f32 v[128:129], v[130:131], v[128:129]
	v_lshlrev_b32_e32 v130, 16, v149
	v_and_b32_e32 v131, 0xffff0000, v149
	v_max_f32_e32 v130, v130, v130
	v_max_f32_e32 v131, v131, v131
	v_max_f32_e32 v130, 0x21800000, v130
	v_max_f32_e32 v131, 0x21800000, v131
	v_rcp_f32_e32 v130, v130
	v_rcp_f32_e32 v131, v131
	v_rcp_f32_e32 v170, v175
	v_pk_mul_f32 v[0:1], v[0:1], v[128:129]
	v_lshlrev_b32_e32 v128, 16, v141
	v_and_b32_e32 v129, 0xffff0000, v141
	v_pk_mul_f32 v[128:129], v[130:131], v[128:129]
	v_add_co_u32_e32 v130, vcc, s42, v152
	v_pk_mul_f32 v[160:161], v[170:171], v[164:165]
	s_nop 0
	v_addc_co_u32_e32 v131, vcc, 0, v153, vcc
	v_pk_mul_f32 v[120:121], v[120:121], v[160:161]
	global_load_dwordx4 v[160:163], v[130:131], off offset:-4096
	v_pk_mul_f32 v[2:3], v[2:3], v[128:129]
	v_lshlrev_b32_e32 v128, 16, v150
	v_and_b32_e32 v129, 0xffff0000, v150
	v_max_f32_e32 v128, v128, v128
	v_max_f32_e32 v129, v129, v129
	v_max_f32_e32 v128, 0x21800000, v128
	v_max_f32_e32 v129, 0x21800000, v129
	v_rcp_f32_e32 v128, v128
	v_rcp_f32_e32 v129, v129
	v_lshlrev_b32_e32 v140, 16, v142
	v_and_b32_e32 v141, 0xffff0000, v142
	v_add_co_u32_e32 v156, vcc, s40, v152
	v_pk_mul_f32 v[128:129], v[128:129], v[140:141]
	v_lshlrev_b32_e32 v140, 16, v151
	v_and_b32_e32 v141, 0xffff0000, v151
	v_max_f32_e32 v140, v140, v140
	v_max_f32_e32 v141, v141, v141
	v_max_f32_e32 v140, 0x21800000, v140
	v_max_f32_e32 v141, 0x21800000, v141
	s_waitcnt vmcnt(3)
	v_lshlrev_b32_e32 v148, 16, v132
	v_and_b32_e32 v132, 0xffff0000, v132
	v_rcp_f32_e32 v140, v140
	v_rcp_f32_e32 v141, v141
	v_max_f32_e32 v148, v148, v148
	v_max_f32_e32 v132, v132, v132
	v_max_f32_e32 v148, 0x21800000, v148
	v_max_f32_e32 v132, 0x21800000, v132
	v_rcp_f32_e32 v148, v148
	v_rcp_f32_e32 v149, v132
	v_pk_mul_f32 v[4:5], v[4:5], v[128:129]
	v_lshlrev_b32_e32 v128, 16, v143
	v_and_b32_e32 v129, 0xffff0000, v143
	v_pk_mul_f32 v[128:129], v[140:141], v[128:129]
	v_addc_co_u32_e32 v157, vcc, 0, v153, vcc
	v_pk_mul_f32 v[6:7], v[6:7], v[128:129]
	s_waitcnt vmcnt(2)
; DI float bf_lo(unsigned u) { return __uint_as_float(u << 16); }
; DI float bf_hi(unsigned u) { return __uint_as_float(u & 0xffff0000u); }
; DI void phase4(const Params& p, unsigned char* smem, int tid) {
;     ...
;             const unsigned char* ga = ws + OFF_G + ((size_t)(f * 64 + tt) * 8 + (te >> 6)) * 16384 + (te & 63) * 16;
;             const unsigned char* gb = ga + (size_t)4 * 64 * 8 * 16384;
; #pragma unroll
;             for (int it = 0; it < 4; ++it)
; #pragma unroll
;                 for (int jt = 0; jt < 2; ++jt)
; #pragma unroll
;                     for (int gp = 0; gp < 2; ++gp) {
;                         const u32x4 a4 = *(const u32x4*)(ga + ((it * 2 + jt) * 2 + gp) * 1024), b4 = *(const u32x4*)(gb + ((it * 2 + jt) * 2 + gp) * 1024);
; #pragma unroll
;                         for (int e = 0; e < 4; ++e) {
;                             acc[it][jt][8 * gp + 2 * e] *= bf_lo(a4[e]) * __builtin_amdgcn_rcpf(fmaxf(bf_lo(b4[e]), 8.6736174e-19f));
;                             acc[it][jt][8 * gp + 2 * e + 1] *= bf_hi(a4[e]) * __builtin_amdgcn_rcpf(fmaxf(bf_hi(b4[e]), 8.6736174e-19f));
;                         }
;                     }
;         }
	v_lshlrev_b32_e32 v128, 16, v144
	v_and_b32_e32 v129, 0xffff0000, v144
	v_pk_mul_f32 v[128:129], v[148:149], v[128:129]
	global_load_dwordx4 v[148:151], v[154:155], off offset:1024
	global_load_dwordx4 v[140:143], v[156:157], off offset:1024
	global_load_dwordx4 v[164:167], v[156:157], off offset:2048
	v_lshlrev_b32_e32 v132, 16, v133
	v_and_b32_e32 v133, 0xffff0000, v133
	v_max_f32_e32 v132, v132, v132
	v_max_f32_e32 v133, v133, v133
	v_max_f32_e32 v132, 0x21800000, v132
	v_max_f32_e32 v133, 0x21800000, v133
	v_rcp_f32_e32 v132, v132
	v_rcp_f32_e32 v133, v133
	v_pk_mul_f32 v[8:9], v[8:9], v[128:129]
	v_lshlrev_b32_e32 v128, 16, v145
	v_and_b32_e32 v129, 0xffff0000, v145
	v_pk_mul_f32 v[128:129], v[132:133], v[128:129]
	v_lshlrev_b32_e32 v132, 16, v134
	v_and_b32_e32 v133, 0xffff0000, v134
	v_max_f32_e32 v132, v132, v132
	v_max_f32_e32 v133, v133, v133
	v_max_f32_e32 v132, 0x21800000, v132
	v_max_f32_e32 v133, 0x21800000, v133
	v_rcp_f32_e32 v132, v132
	v_rcp_f32_e32 v133, v133
	v_pk_mul_f32 v[10:11], v[10:11], v[128:129]
	v_lshlrev_b32_e32 v128, 16, v146
	v_and_b32_e32 v129, 0xffff0000, v146
	v_pk_mul_f32 v[128:129], v[132:133], v[128:129]
	v_lshlrev_b32_e32 v132, 16, v135
	v_and_b32_e32 v133, 0xffff0000, v135
	v_max_f32_e32 v132, v132, v132
	v_max_f32_e32 v133, v133, v133
	v_max_f32_e32 v132, 0x21800000, v132
	v_max_f32_e32 v133, 0x21800000, v133
	v_rcp_f32_e32 v132, v132
	v_rcp_f32_e32 v133, v133
	v_pk_mul_f32 v[12:13], v[12:13], v[128:129]
	v_lshlrev_b32_e32 v128, 16, v147
	v_and_b32_e32 v129, 0xffff0000, v147
	v_pk_mul_f32 v[128:129], v[132:133], v[128:129]
	s_waitcnt vmcnt(3)
	v_lshlrev_b32_e32 v144, 16, v160
	v_pk_mul_f32 v[14:15], v[14:15], v[128:129]
	v_lshlrev_b32_e32 v128, 16, v136
	v_and_b32_e32 v129, 0xffff0000, v136
	v_max_f32_e32 v128, v128, v128
	v_max_f32_e32 v129, v129, v129
	v_max_f32_e32 v128, 0x21800000, v128
	v_max_f32_e32 v129, 0x21800000, v129
	v_rcp_f32_e32 v128, v128
	v_rcp_f32_e32 v129, v129
	v_and_b32_e32 v145, 0xffff0000, v160
	v_lshlrev_b32_e32 v136, 16, v137
	v_and_b32_e32 v137, 0xffff0000, v137
	v_pk_mul_f32 v[128:129], v[128:129], v[144:145]
	global_load_dwordx4 v[144:147], v[154:155], off offset:2048
	v_max_f32_e32 v136, v136, v136
	v_max_f32_e32 v137, v137, v137
	v_max_f32_e32 v136, 0x21800000, v136
	v_max_f32_e32 v137, 0x21800000, v137
	v_rcp_f32_e32 v136, v136
	v_rcp_f32_e32 v137, v137
	v_pk_mul_f32 v[96:97], v[96:97], v[128:129]
	v_lshlrev_b32_e32 v128, 16, v161
	v_and_b32_e32 v129, 0xffff0000, v161
	v_pk_mul_f32 v[128:129], v[136:137], v[128:129]
	v_lshlrev_b32_e32 v136, 16, v138
	v_and_b32_e32 v137, 0xffff0000, v138
	v_max_f32_e32 v136, v136, v136
	v_max_f32_e32 v137, v137, v137
	v_max_f32_e32 v136, 0x21800000, v136
	v_max_f32_e32 v137, 0x21800000, v137
	v_rcp_f32_e32 v136, v136
	v_rcp_f32_e32 v137, v137
	v_pk_mul_f32 v[98:99], v[98:99], v[128:129]
	v_lshlrev_b32_e32 v128, 16, v162
	v_and_b32_e32 v129, 0xffff0000, v162
	v_pk_mul_f32 v[128:129], v[136:137], v[128:129]
	v_lshlrev_b32_e32 v136, 16, v139
	v_and_b32_e32 v137, 0xffff0000, v139
	v_max_f32_e32 v136, v136, v136
	v_max_f32_e32 v137, v137, v137
	v_max_f32_e32 v136, 0x21800000, v136
	v_max_f32_e32 v137, 0x21800000, v137
	v_rcp_f32_e32 v136, v136
	v_rcp_f32_e32 v137, v137
	v_pk_mul_f32 v[100:101], v[100:101], v[128:129]
	v_lshlrev_b32_e32 v128, 16, v163
	v_and_b32_e32 v129, 0xffff0000, v163
	v_pk_mul_f32 v[128:129], v[136:137], v[128:129]
	s_waitcnt vmcnt(3)
	v_lshlrev_b32_e32 v136, 16, v148
	v_and_b32_e32 v137, 0xffff0000, v148
	v_max_f32_e32 v136, v136, v136
	v_max_f32_e32 v137, v137, v137
	v_max_f32_e32 v136, 0x21800000, v136
	v_max_f32_e32 v137, 0x21800000, v137
	v_rcp_f32_e32 v136, v136
	v_rcp_f32_e32 v137, v137
	v_pk_mul_f32 v[102:103], v[102:103], v[128:129]
	s_waitcnt vmcnt(2)
	v_lshlrev_b32_e32 v128, 16, v140
	v_and_b32_e32 v129, 0xffff0000, v140
	v_pk_mul_f32 v[128:129], v[136:137], v[128:129]
	global_load_dwordx4 v[136:139], v[154:155], off offset:3072
	v_pk_mul_f32 v[104:105], v[104:105], v[128:129]
	global_load_dwordx4 v[154:157], v[156:157], off offset:3072
	v_lshlrev_b32_e32 v128, 16, v149
	v_and_b32_e32 v129, 0xffff0000, v149
	v_max_f32_e32 v128, v128, v128
	v_max_f32_e32 v129, v129, v129
	v_max_f32_e32 v128, 0x21800000, v128
	v_max_f32_e32 v129, 0x21800000, v129
	v_rcp_f32_e32 v128, v128
	v_rcp_f32_e32 v129, v129
	v_lshlrev_b32_e32 v140, 16, v141
	v_and_b32_e32 v141, 0xffff0000, v141
	global_load_dwordx4 v[132:135], v[130:131], off
	v_pk_mul_f32 v[128:129], v[128:129], v[140:141]
	v_lshlrev_b32_e32 v140, 16, v150
	v_and_b32_e32 v141, 0xffff0000, v150
	v_max_f32_e32 v140, v140, v140
	v_max_f32_e32 v141, v141, v141
	v_max_f32_e32 v140, 0x21800000, v140
	v_max_f32_e32 v141, 0x21800000, v141
	v_rcp_f32_e32 v140, v140
	v_rcp_f32_e32 v141, v141
	v_pk_mul_f32 v[106:107], v[106:107], v[128:129]
	v_lshlrev_b32_e32 v128, 16, v142
	v_and_b32_e32 v129, 0xffff0000, v142
	v_pk_mul_f32 v[128:129], v[140:141], v[128:129]
	v_lshlrev_b32_e32 v140, 16, v151
	v_and_b32_e32 v141, 0xffff0000, v151
	v_max_f32_e32 v140, v140, v140
	v_max_f32_e32 v141, v141, v141
	v_max_f32_e32 v140, 0x21800000, v140
	v_max_f32_e32 v141, 0x21800000, v141
	v_rcp_f32_e32 v140, v140
	v_rcp_f32_e32 v141, v141
	v_pk_mul_f32 v[108:109], v[108:109], v[128:129]
	v_lshlrev_b32_e32 v128, 16, v143
	v_and_b32_e32 v129, 0xffff0000, v143
	v_pk_mul_f32 v[128:129], v[140:141], v[128:129]
	s_waitcnt vmcnt(3)
; DI float bf_lo(unsigned u) { return __uint_as_float(u << 16); }
; DI float bf_hi(unsigned u) { return __uint_as_float(u & 0xffff0000u); }
; DI void phase4(const Params& p, unsigned char* smem, int tid) {
;     ...
;             const unsigned char* ga = ws + OFF_G + ((size_t)(f * 64 + tt) * 8 + (te >> 6)) * 16384 + (te & 63) * 16;
;             const unsigned char* gb = ga + (size_t)4 * 64 * 8 * 16384;
; #pragma unroll
;             for (int it = 0; it < 4; ++it)
; #pragma unroll
;                 for (int jt = 0; jt < 2; ++jt)
; #pragma unroll
;                     for (int gp = 0; gp < 2; ++gp) {
;                         const u32x4 a4 = *(const u32x4*)(ga + ((it * 2 + jt) * 2 + gp) * 1024), b4 = *(const u32x4*)(gb + ((it * 2 + jt) * 2 + gp) * 1024);
; #pragma unroll
;                         for (int e = 0; e < 4; ++e) {
;                             acc[it][jt][8 * gp + 2 * e] *= bf_lo(a4[e]) * __builtin_amdgcn_rcpf(fmaxf(bf_lo(b4[e]), 8.6736174e-19f));
;                             acc[it][jt][8 * gp + 2 * e + 1] *= bf_hi(a4[e]) * __builtin_amdgcn_rcpf(fmaxf(bf_hi(b4[e]), 8.6736174e-19f));
;                         }
;                     }
;         }
	v_lshlrev_b32_e32 v140, 16, v144
	v_and_b32_e32 v141, 0xffff0000, v144
	v_max_f32_e32 v140, v140, v140
	v_max_f32_e32 v141, v141, v141
	v_max_f32_e32 v140, 0x21800000, v140
	v_max_f32_e32 v141, 0x21800000, v141
	v_rcp_f32_e32 v140, v140
	v_rcp_f32_e32 v141, v141
	v_pk_mul_f32 v[110:111], v[110:111], v[128:129]
	v_lshlrev_b32_e32 v128, 16, v164
	v_and_b32_e32 v129, 0xffff0000, v164
	v_pk_mul_f32 v[128:129], v[140:141], v[128:129]
	v_lshlrev_b32_e32 v140, 16, v145
	v_and_b32_e32 v141, 0xffff0000, v145
	v_max_f32_e32 v140, v140, v140
	v_max_f32_e32 v141, v141, v141
	v_max_f32_e32 v140, 0x21800000, v140
	v_max_f32_e32 v141, 0x21800000, v141
	v_rcp_f32_e32 v140, v140
	v_rcp_f32_e32 v141, v141
	v_pk_mul_f32 v[32:33], v[32:33], v[128:129]
	v_lshlrev_b32_e32 v128, 16, v165
	v_and_b32_e32 v129, 0xffff0000, v165
	v_pk_mul_f32 v[144:145], v[140:141], v[128:129]
	v_add_co_u32_e32 v128, vcc, s45, v152
	v_lshlrev_b32_e32 v148, 16, v146
	s_nop 0
	v_addc_co_u32_e32 v129, vcc, 0, v153, vcc
	global_load_dwordx4 v[140:143], v[128:129], off offset:-4096
	v_and_b32_e32 v146, 0xffff0000, v146
	v_max_f32_e32 v146, v146, v146
	v_max_f32_e32 v148, v148, v148
	v_max_f32_e32 v146, 0x21800000, v146
	v_max_f32_e32 v148, 0x21800000, v148
	v_rcp_f32_e32 v149, v146
	v_lshlrev_b32_e32 v146, 16, v147
	v_and_b32_e32 v147, 0xffff0000, v147
	v_rcp_f32_e32 v148, v148
	v_max_f32_e32 v146, v146, v146
	v_max_f32_e32 v147, v147, v147
	v_max_f32_e32 v146, 0x21800000, v146
	v_max_f32_e32 v147, 0x21800000, v147
	v_rcp_f32_e32 v146, v146
	v_rcp_f32_e32 v147, v147
	v_pk_mul_f32 v[34:35], v[34:35], v[144:145]
	v_lshlrev_b32_e32 v144, 16, v166
	v_and_b32_e32 v145, 0xffff0000, v166
	v_pk_mul_f32 v[144:145], v[148:149], v[144:145]
	v_add_co_u32_e32 v160, vcc, s43, v152
	v_pk_mul_f32 v[36:37], v[36:37], v[144:145]
	v_lshlrev_b32_e32 v144, 16, v167
	v_and_b32_e32 v145, 0xffff0000, v167
	v_pk_mul_f32 v[144:145], v[146:147], v[144:145]
	s_waitcnt vmcnt(3)
	v_lshlrev_b32_e32 v146, 16, v136
	v_and_b32_e32 v136, 0xffff0000, v136
	v_max_f32_e32 v146, v146, v146
	v_max_f32_e32 v136, v136, v136
	v_max_f32_e32 v146, 0x21800000, v146
	v_max_f32_e32 v136, 0x21800000, v136
	v_rcp_f32_e32 v146, v146
	v_rcp_f32_e32 v147, v136
	v_lshlrev_b32_e32 v136, 16, v137
	v_and_b32_e32 v137, 0xffff0000, v137
	v_max_f32_e32 v136, v136, v136
	v_max_f32_e32 v137, v137, v137
	v_pk_mul_f32 v[38:39], v[38:39], v[144:145]
	s_waitcnt vmcnt(2)
	v_lshlrev_b32_e32 v144, 16, v154
	v_and_b32_e32 v145, 0xffff0000, v154
	v_max_f32_e32 v136, 0x21800000, v136
	v_max_f32_e32 v137, 0x21800000, v137
	v_pk_mul_f32 v[144:145], v[146:147], v[144:145]
	v_rcp_f32_e32 v136, v136
	v_rcp_f32_e32 v137, v137
	v_addc_co_u32_e32 v161, vcc, 0, v153, vcc
	v_pk_mul_f32 v[40:41], v[40:41], v[144:145]
	global_load_dwordx4 v[144:147], v[160:161], off offset:1024
	v_lshlrev_b32_e32 v148, 16, v155
	v_and_b32_e32 v149, 0xffff0000, v155
	v_pk_mul_f32 v[136:137], v[136:137], v[148:149]
	v_lshlrev_b32_e32 v148, 16, v138
	v_max_f32_e32 v148, v148, v148
	v_max_f32_e32 v148, 0x21800000, v148
	v_rcp_f32_e32 v152, v148
	global_load_dwordx4 v[148:151], v[130:131], off offset:1024
	v_and_b32_e32 v138, 0xffff0000, v138
	v_max_f32_e32 v138, v138, v138
	v_max_f32_e32 v138, 0x21800000, v138
	v_rcp_f32_e32 v153, v138
	v_lshlrev_b32_e32 v138, 16, v139
	v_and_b32_e32 v139, 0xffff0000, v139
	v_max_f32_e32 v138, v138, v138
	v_max_f32_e32 v139, v139, v139
	v_max_f32_e32 v138, 0x21800000, v138
	v_max_f32_e32 v139, 0x21800000, v139
	v_rcp_f32_e32 v138, v138
	v_rcp_f32_e32 v139, v139
	v_pk_mul_f32 v[42:43], v[42:43], v[136:137]
	v_lshlrev_b32_e32 v136, 16, v156
	v_and_b32_e32 v137, 0xffff0000, v156
	v_pk_mul_f32 v[136:137], v[152:153], v[136:137]
	s_waitcnt vmcnt(2)
	v_lshlrev_b32_e32 v154, 16, v140
	v_pk_mul_f32 v[44:45], v[44:45], v[136:137]
	v_lshlrev_b32_e32 v136, 16, v157
	v_and_b32_e32 v137, 0xffff0000, v157
	v_pk_mul_f32 v[152:153], v[138:139], v[136:137]
	v_and_b32_e32 v140, 0xffff0000, v140
	v_pk_mul_f32 v[46:47], v[46:47], v[152:153]
	v_lshlrev_b32_e32 v152, 16, v132
	v_and_b32_e32 v153, 0xffff0000, v132
	v_lshlrev_b32_e32 v132, 16, v141
	v_max_f32_e32 v140, v140, v140
	v_max_f32_e32 v132, v132, v132
	v_max_f32_e32 v140, 0x21800000, v140
	v_max_f32_e32 v132, 0x21800000, v132
	v_max_f32_e32 v154, v154, v154
	v_rcp_f32_e32 v155, v140
	v_rcp_f32_e32 v140, v132
	v_and_b32_e32 v132, 0xffff0000, v141
	v_max_f32_e32 v154, 0x21800000, v154
	v_max_f32_e32 v132, v132, v132
	v_rcp_f32_e32 v154, v154
	v_max_f32_e32 v132, 0x21800000, v132
	v_rcp_f32_e32 v141, v132
	v_lshlrev_b32_e32 v132, 16, v133
	v_pk_mul_f32 v[156:157], v[154:155], v[152:153]
	global_load_dwordx4 v[152:155], v[160:161], off offset:2048
	v_and_b32_e32 v133, 0xffff0000, v133
	v_pk_mul_f32 v[140:141], v[140:141], v[132:133]
	v_lshlrev_b32_e32 v132, 16, v142
	v_max_f32_e32 v132, v132, v132
	global_load_dwordx4 v[136:139], v[130:131], off offset:3072
	v_pk_mul_f32 v[80:81], v[80:81], v[156:157]
	v_max_f32_e32 v156, 0x21800000, v132
	global_load_dwordx4 v[130:133], v[130:131], off offset:2048
	v_and_b32_e32 v142, 0xffff0000, v142
	v_max_f32_e32 v142, v142, v142
	v_max_f32_e32 v142, 0x21800000, v142
	v_rcp_f32_e32 v156, v156
	v_rcp_f32_e32 v157, v142
	v_pk_mul_f32 v[82:83], v[82:83], v[140:141]
	v_lshlrev_b32_e32 v140, 16, v134
	v_and_b32_e32 v141, 0xffff0000, v134
	v_lshlrev_b32_e32 v134, 16, v143
	v_max_f32_e32 v134, v134, v134
	v_max_f32_e32 v134, 0x21800000, v134
	v_rcp_f32_e32 v142, v134
	v_and_b32_e32 v134, 0xffff0000, v143
	v_pk_mul_f32 v[140:141], v[156:157], v[140:141]
	v_max_f32_e32 v134, v134, v134
	v_max_f32_e32 v134, 0x21800000, v134
	v_pk_mul_f32 v[84:85], v[84:85], v[140:141]
	s_waitcnt vmcnt(4)
; DI float bf_lo(unsigned u) { return __uint_as_float(u << 16); }
; DI float bf_hi(unsigned u) { return __uint_as_float(u & 0xffff0000u); }
; DI void phase4(const Params& p, unsigned char* smem, int tid) {
;     ...
;             const unsigned char* ga = ws + OFF_G + ((size_t)(f * 64 + tt) * 8 + (te >> 6)) * 16384 + (te & 63) * 16;
;             const unsigned char* gb = ga + (size_t)4 * 64 * 8 * 16384;
; #pragma unroll
;             for (int it = 0; it < 4; ++it)
; #pragma unroll
;                 for (int jt = 0; jt < 2; ++jt)
; #pragma unroll
;                     for (int gp = 0; gp < 2; ++gp) {
;                         const u32x4 a4 = *(const u32x4*)(ga + ((it * 2 + jt) * 2 + gp) * 1024), b4 = *(const u32x4*)(gb + ((it * 2 + jt) * 2 + gp) * 1024);
; #pragma unroll
;                         for (int e = 0; e < 4; ++e) {
;                             acc[it][jt][8 * gp + 2 * e] *= bf_lo(a4[e]) * __builtin_amdgcn_rcpf(fmaxf(bf_lo(b4[e]), 8.6736174e-19f));
;                             acc[it][jt][8 * gp + 2 * e + 1] *= bf_hi(a4[e]) * __builtin_amdgcn_rcpf(fmaxf(bf_hi(b4[e]), 8.6736174e-19f));
;                         }
;                     }
;         }
	v_lshlrev_b32_e32 v140, 16, v144
	v_and_b32_e32 v141, 0xffff0000, v144
	v_rcp_f32_e32 v143, v134
	v_max_f32_e32 v140, v140, v140
	v_max_f32_e32 v141, v141, v141
	v_max_f32_e32 v140, 0x21800000, v140
	v_max_f32_e32 v141, 0x21800000, v141
	v_rcp_f32_e32 v140, v140
	v_rcp_f32_e32 v141, v141
	v_lshlrev_b32_e32 v134, 16, v135
	v_and_b32_e32 v135, 0xffff0000, v135
	v_pk_mul_f32 v[134:135], v[142:143], v[134:135]
	s_nop 0
	v_pk_mul_f32 v[86:87], v[86:87], v[134:135]
	s_waitcnt vmcnt(3)
	v_lshlrev_b32_e32 v134, 16, v148
	v_and_b32_e32 v135, 0xffff0000, v148
	v_pk_mul_f32 v[134:135], v[140:141], v[134:135]
	v_lshlrev_b32_e32 v140, 16, v145
	v_max_f32_e32 v140, v140, v140
	v_max_f32_e32 v140, 0x21800000, v140
	v_rcp_f32_e32 v144, v140
	v_and_b32_e32 v140, 0xffff0000, v145
	v_max_f32_e32 v140, v140, v140
	v_max_f32_e32 v145, 0x21800000, v140
	global_load_dwordx4 v[140:143], v[160:161], off offset:3072
	v_rcp_f32_e32 v145, v145
	v_pk_mul_f32 v[88:89], v[88:89], v[134:135]
	v_lshlrev_b32_e32 v134, 16, v149
	v_and_b32_e32 v135, 0xffff0000, v149
	v_pk_mul_f32 v[134:135], v[144:145], v[134:135]
	v_lshlrev_b32_e32 v144, 16, v146
	v_and_b32_e32 v145, 0xffff0000, v146
	v_max_f32_e32 v144, v144, v144
	v_max_f32_e32 v145, v145, v145
	v_max_f32_e32 v144, 0x21800000, v144
	v_max_f32_e32 v145, 0x21800000, v145
	v_rcp_f32_e32 v144, v144
	v_rcp_f32_e32 v145, v145
	v_pk_mul_f32 v[90:91], v[90:91], v[134:135]
	v_lshlrev_b32_e32 v134, 16, v150
	v_and_b32_e32 v135, 0xffff0000, v150
	v_pk_mul_f32 v[134:135], v[144:145], v[134:135]
	v_lshlrev_b32_e32 v144, 16, v147
	v_and_b32_e32 v145, 0xffff0000, v147
	v_max_f32_e32 v144, v144, v144
	v_max_f32_e32 v145, v145, v145
	v_max_f32_e32 v144, 0x21800000, v144
	v_max_f32_e32 v145, 0x21800000, v145
	v_rcp_f32_e32 v144, v144
	v_rcp_f32_e32 v145, v145
	v_pk_mul_f32 v[92:93], v[92:93], v[134:135]
	v_lshlrev_b32_e32 v134, 16, v151
	v_and_b32_e32 v135, 0xffff0000, v151
	v_pk_mul_f32 v[134:135], v[144:145], v[134:135]
	s_waitcnt vmcnt(3)
	v_lshlrev_b32_e32 v144, 16, v152
	v_and_b32_e32 v145, 0xffff0000, v152
	v_max_f32_e32 v144, v144, v144
	v_max_f32_e32 v145, v145, v145
	v_max_f32_e32 v144, 0x21800000, v144
	v_max_f32_e32 v145, 0x21800000, v145
	v_rcp_f32_e32 v144, v144
	v_rcp_f32_e32 v145, v145
	v_pk_mul_f32 v[94:95], v[94:95], v[134:135]
	s_waitcnt vmcnt(1)
	v_lshlrev_b32_e32 v134, 16, v130
	v_and_b32_e32 v135, 0xffff0000, v130
	v_lshlrev_b32_e32 v130, 16, v153
	v_max_f32_e32 v130, v130, v130
	v_max_f32_e32 v130, 0x21800000, v130
	v_rcp_f32_e32 v148, v130
	v_and_b32_e32 v130, 0xffff0000, v153
	v_pk_mul_f32 v[134:135], v[144:145], v[134:135]
	v_max_f32_e32 v130, v130, v130
	global_load_dwordx4 v[144:147], v[128:129], off
	v_max_f32_e32 v130, 0x21800000, v130
	v_rcp_f32_e32 v149, v130
	v_lshlrev_b32_e32 v130, 16, v131
	v_and_b32_e32 v131, 0xffff0000, v131
	v_pk_mul_f32 v[48:49], v[48:49], v[134:135]
	v_pk_mul_f32 v[130:131], v[148:149], v[130:131]
	v_lshlrev_b32_e32 v134, 16, v154
	global_load_dwordx4 v[148:151], v[158:159], off
	v_and_b32_e32 v135, 0xffff0000, v154
	v_max_f32_e32 v134, v134, v134
	v_max_f32_e32 v135, v135, v135
	v_max_f32_e32 v134, 0x21800000, v134
	v_max_f32_e32 v135, 0x21800000, v135
	v_rcp_f32_e32 v134, v134
	v_rcp_f32_e32 v135, v135
	v_pk_mul_f32 v[50:51], v[50:51], v[130:131]
	v_lshlrev_b32_e32 v130, 16, v132
	v_and_b32_e32 v131, 0xffff0000, v132
	v_lshlrev_b32_e32 v132, 16, v155
	v_max_f32_e32 v132, v132, v132
	v_max_f32_e32 v132, 0x21800000, v132
	v_pk_mul_f32 v[130:131], v[134:135], v[130:131]
	v_rcp_f32_e32 v134, v132
	v_and_b32_e32 v132, 0xffff0000, v155
	v_max_f32_e32 v132, v132, v132
	v_max_f32_e32 v132, 0x21800000, v132
	v_rcp_f32_e32 v135, v132
	v_pk_mul_f32 v[52:53], v[52:53], v[130:131]
	v_lshlrev_b32_e32 v130, 16, v133
	v_and_b32_e32 v131, 0xffff0000, v133
	v_pk_mul_f32 v[130:131], v[134:135], v[130:131]
	s_waitcnt vmcnt(2)
	v_lshlrev_b32_e32 v132, 16, v140
	v_and_b32_e32 v133, 0xffff0000, v140
	v_max_f32_e32 v132, v132, v132
	v_max_f32_e32 v133, v133, v133
	v_max_f32_e32 v132, 0x21800000, v132
	v_max_f32_e32 v133, 0x21800000, v133
	v_rcp_f32_e32 v132, v132
	v_rcp_f32_e32 v133, v133
	v_pk_mul_f32 v[54:55], v[54:55], v[130:131]
	v_lshlrev_b32_e32 v130, 16, v136
	v_and_b32_e32 v131, 0xffff0000, v136
	v_pk_mul_f32 v[134:135], v[132:133], v[130:131]
	v_lshlrev_b32_e32 v130, 16, v141
	v_max_f32_e32 v130, v130, v130
	v_max_f32_e32 v130, 0x21800000, v130
	v_rcp_f32_e32 v140, v130
	v_and_b32_e32 v130, 0xffff0000, v141
	v_max_f32_e32 v130, v130, v130
	v_max_f32_e32 v130, 0x21800000, v130
	v_rcp_f32_e32 v141, v130
	global_load_dwordx4 v[130:133], v[128:129], off offset:1024
	v_pk_mul_f32 v[56:57], v[56:57], v[134:135]
	v_lshlrev_b32_e32 v134, 16, v137
	v_and_b32_e32 v135, 0xffff0000, v137
	v_pk_mul_f32 v[140:141], v[140:141], v[134:135]
	v_lshlrev_b32_e32 v134, 16, v142
	v_max_f32_e32 v134, v134, v134
	v_max_f32_e32 v134, 0x21800000, v134
	v_rcp_f32_e32 v152, v134
	global_load_dwordx4 v[134:137], v[158:159], off offset:1024
	v_and_b32_e32 v142, 0xffff0000, v142
	v_max_f32_e32 v142, v142, v142
	v_max_f32_e32 v142, 0x21800000, v142
	v_rcp_f32_e32 v153, v142
	v_pk_mul_f32 v[58:59], v[58:59], v[140:141]
	v_lshlrev_b32_e32 v140, 16, v138
	v_and_b32_e32 v141, 0xffff0000, v138
	v_lshlrev_b32_e32 v138, 16, v143
	v_max_f32_e32 v138, v138, v138
	v_max_f32_e32 v138, 0x21800000, v138
	v_rcp_f32_e32 v142, v138
	v_and_b32_e32 v138, 0xffff0000, v143
	v_pk_mul_f32 v[140:141], v[152:153], v[140:141]
	v_max_f32_e32 v138, v138, v138
	v_max_f32_e32 v138, 0x21800000, v138
	v_pk_mul_f32 v[60:61], v[60:61], v[140:141]
	v_rcp_f32_e32 v143, v138
	v_lshlrev_b32_e32 v138, 16, v139
	s_waitcnt vmcnt(3)
; DI float bf_lo(unsigned u) { return __uint_as_float(u << 16); }
; DI float bf_hi(unsigned u) { return __uint_as_float(u & 0xffff0000u); }
; DI void phase4(const Params& p, unsigned char* smem, int tid) {
;     ...
;             const unsigned char* ga = ws + OFF_G + ((size_t)(f * 64 + tt) * 8 + (te >> 6)) * 16384 + (te & 63) * 16;
;             const unsigned char* gb = ga + (size_t)4 * 64 * 8 * 16384;
; #pragma unroll
;             for (int it = 0; it < 4; ++it)
; #pragma unroll
;                 for (int jt = 0; jt < 2; ++jt)
; #pragma unroll
;                     for (int gp = 0; gp < 2; ++gp) {
;                         const u32x4 a4 = *(const u32x4*)(ga + ((it * 2 + jt) * 2 + gp) * 1024), b4 = *(const u32x4*)(gb + ((it * 2 + jt) * 2 + gp) * 1024);
; #pragma unroll
;                         for (int e = 0; e < 4; ++e) {
;                             acc[it][jt][8 * gp + 2 * e] *= bf_lo(a4[e]) * __builtin_amdgcn_rcpf(fmaxf(bf_lo(b4[e]), 8.6736174e-19f));
;                             acc[it][jt][8 * gp + 2 * e + 1] *= bf_hi(a4[e]) * __builtin_amdgcn_rcpf(fmaxf(bf_hi(b4[e]), 8.6736174e-19f));
;                         }
;                     }
;         }
	v_lshlrev_b32_e32 v140, 16, v144
	v_and_b32_e32 v141, 0xffff0000, v144
	v_max_f32_e32 v140, v140, v140
	v_max_f32_e32 v141, v141, v141
	v_max_f32_e32 v140, 0x21800000, v140
	v_max_f32_e32 v141, 0x21800000, v141
	v_rcp_f32_e32 v140, v140
	v_rcp_f32_e32 v141, v141
	v_and_b32_e32 v139, 0xffff0000, v139
	v_pk_mul_f32 v[138:139], v[142:143], v[138:139]
	s_nop 0
	v_pk_mul_f32 v[62:63], v[62:63], v[138:139]
	s_waitcnt vmcnt(2)
	v_lshlrev_b32_e32 v138, 16, v148
	v_and_b32_e32 v139, 0xffff0000, v148
	v_pk_mul_f32 v[142:143], v[140:141], v[138:139]
	v_lshlrev_b32_e32 v138, 16, v145
	v_max_f32_e32 v138, v138, v138
	v_max_f32_e32 v138, 0x21800000, v138
	v_rcp_f32_e32 v144, v138
	v_and_b32_e32 v138, 0xffff0000, v145
	v_max_f32_e32 v138, v138, v138
	v_max_f32_e32 v145, 0x21800000, v138
	global_load_dwordx4 v[138:141], v[128:129], off offset:2048
	v_rcp_f32_e32 v145, v145
	v_pk_mul_f32 v[64:65], v[64:65], v[142:143]
	v_lshlrev_b32_e32 v142, 16, v149
	v_and_b32_e32 v143, 0xffff0000, v149
	v_pk_mul_f32 v[148:149], v[144:145], v[142:143]
	v_lshlrev_b32_e32 v142, 16, v146
	v_max_f32_e32 v142, v142, v142
	v_max_f32_e32 v152, 0x21800000, v142
	global_load_dwordx4 v[142:145], v[158:159], off offset:2048
	v_and_b32_e32 v146, 0xffff0000, v146
	v_max_f32_e32 v146, v146, v146
	v_max_f32_e32 v146, 0x21800000, v146
	v_rcp_f32_e32 v153, v146
	v_lshlrev_b32_e32 v146, 16, v147
	v_and_b32_e32 v147, 0xffff0000, v147
	v_rcp_f32_e32 v152, v152
	v_max_f32_e32 v146, v146, v146
	v_max_f32_e32 v147, v147, v147
	v_max_f32_e32 v146, 0x21800000, v146
	v_max_f32_e32 v147, 0x21800000, v147
	v_rcp_f32_e32 v146, v146
	v_rcp_f32_e32 v147, v147
	v_pk_mul_f32 v[66:67], v[66:67], v[148:149]
	v_lshlrev_b32_e32 v148, 16, v150
	v_and_b32_e32 v149, 0xffff0000, v150
	v_pk_mul_f32 v[148:149], v[152:153], v[148:149]
	s_nop 0
	v_pk_mul_f32 v[68:69], v[68:69], v[148:149]
	v_lshlrev_b32_e32 v148, 16, v151
	v_and_b32_e32 v149, 0xffff0000, v151
	v_pk_mul_f32 v[146:147], v[146:147], v[148:149]
	s_waitcnt vmcnt(3)
	v_lshlrev_b32_e32 v148, 16, v130
	v_and_b32_e32 v130, 0xffff0000, v130
	v_max_f32_e32 v148, v148, v148
	v_max_f32_e32 v130, v130, v130
	v_max_f32_e32 v148, 0x21800000, v148
	v_max_f32_e32 v130, 0x21800000, v130
	v_rcp_f32_e32 v148, v148
	v_rcp_f32_e32 v149, v130
	v_lshlrev_b32_e32 v130, 16, v131
	v_max_f32_e32 v130, v130, v130
	v_pk_mul_f32 v[70:71], v[70:71], v[146:147]
	s_waitcnt vmcnt(2)
	v_lshlrev_b32_e32 v146, 16, v134
	v_and_b32_e32 v147, 0xffff0000, v134
	v_max_f32_e32 v130, 0x21800000, v130
	v_pk_mul_f32 v[146:147], v[148:149], v[146:147]
	v_rcp_f32_e32 v148, v130
	v_and_b32_e32 v134, 0xffff0000, v131
	global_load_dwordx4 v[128:131], v[128:129], off offset:3072
	v_max_f32_e32 v134, v134, v134
	v_pk_mul_f32 v[72:73], v[72:73], v[146:147]
	v_lshlrev_b32_e32 v146, 16, v132
	v_and_b32_e32 v132, 0xffff0000, v132
	v_max_f32_e32 v134, 0x21800000, v134
	v_max_f32_e32 v132, v132, v132
	v_rcp_f32_e32 v149, v134
	v_max_f32_e32 v146, v146, v146
	v_max_f32_e32 v132, 0x21800000, v132
	v_max_f32_e32 v146, 0x21800000, v146
	v_rcp_f32_e32 v147, v132
	v_lshlrev_b32_e32 v132, 16, v133
	v_and_b32_e32 v133, 0xffff0000, v133
	v_rcp_f32_e32 v146, v146
	v_max_f32_e32 v132, v132, v132
	v_max_f32_e32 v133, v133, v133
	v_lshlrev_b32_e32 v134, 16, v135
	v_and_b32_e32 v135, 0xffff0000, v135
	v_max_f32_e32 v132, 0x21800000, v132
	v_max_f32_e32 v133, 0x21800000, v133
	v_pk_mul_f32 v[134:135], v[148:149], v[134:135]
	v_rcp_f32_e32 v132, v132
	v_rcp_f32_e32 v133, v133
	v_pk_mul_f32 v[74:75], v[74:75], v[134:135]
	v_lshlrev_b32_e32 v134, 16, v136
	v_and_b32_e32 v135, 0xffff0000, v136
	v_pk_mul_f32 v[134:135], v[146:147], v[134:135]
	s_waitcnt vmcnt(0)
	v_lshlrev_b32_e32 v152, 16, v128
	v_pk_mul_f32 v[76:77], v[76:77], v[134:135]
	v_lshlrev_b32_e32 v134, 16, v137
	v_and_b32_e32 v135, 0xffff0000, v137
	v_pk_mul_f32 v[132:133], v[132:133], v[134:135]
	v_lshlrev_b32_e32 v134, 16, v138
	v_and_b32_e32 v135, 0xffff0000, v138
	v_max_f32_e32 v134, v134, v134
	v_max_f32_e32 v135, v135, v135
	v_max_f32_e32 v134, 0x21800000, v134
	v_max_f32_e32 v135, 0x21800000, v135
	v_rcp_f32_e32 v134, v134
	v_rcp_f32_e32 v135, v135
	v_pk_mul_f32 v[78:79], v[78:79], v[132:133]
	v_lshlrev_b32_e32 v132, 16, v142
	v_and_b32_e32 v133, 0xffff0000, v142
	v_pk_mul_f32 v[132:133], v[134:135], v[132:133]
	v_lshlrev_b32_e32 v134, 16, v139
	v_and_b32_e32 v135, 0xffff0000, v139
	v_max_f32_e32 v134, v134, v134
	v_max_f32_e32 v135, v135, v135
	v_max_f32_e32 v134, 0x21800000, v134
	v_max_f32_e32 v135, 0x21800000, v135
	v_rcp_f32_e32 v134, v134
	v_rcp_f32_e32 v135, v135
	v_pk_mul_f32 v[16:17], v[16:17], v[132:133]
	v_lshlrev_b32_e32 v132, 16, v143
	v_and_b32_e32 v133, 0xffff0000, v143
	v_pk_mul_f32 v[132:133], v[134:135], v[132:133]
	v_lshlrev_b32_e32 v134, 16, v140
	v_and_b32_e32 v135, 0xffff0000, v140
	v_max_f32_e32 v134, v134, v134
	v_max_f32_e32 v135, v135, v135
	v_max_f32_e32 v134, 0x21800000, v134
	v_max_f32_e32 v135, 0x21800000, v135
	v_rcp_f32_e32 v134, v134
	v_rcp_f32_e32 v135, v135
	v_pk_mul_f32 v[18:19], v[18:19], v[132:133]
	v_lshlrev_b32_e32 v132, 16, v144
	v_and_b32_e32 v133, 0xffff0000, v144
	v_pk_mul_f32 v[132:133], v[134:135], v[132:133]
	v_lshlrev_b32_e32 v134, 16, v141
	v_and_b32_e32 v135, 0xffff0000, v141
	v_max_f32_e32 v134, v134, v134
	v_max_f32_e32 v135, v135, v135
	v_max_f32_e32 v134, 0x21800000, v134
	v_max_f32_e32 v135, 0x21800000, v135
	v_rcp_f32_e32 v134, v134
	v_rcp_f32_e32 v135, v135
	v_and_b32_e32 v128, 0xffff0000, v128
	v_max_f32_e32 v128, v128, v128
	v_ashrrev_i32_e32 v182, 2, v210
	v_max_f32_e32 v152, v152, v152
	v_max_f32_e32 v128, 0x21800000, v128
	v_pk_mul_f32 v[20:21], v[20:21], v[132:133]
	v_lshlrev_b32_e32 v132, 16, v145
; DI float bf_lo(unsigned u) { return __uint_as_float(u << 16); }
; DI float bf_hi(unsigned u) { return __uint_as_float(u & 0xffff0000u); }
; #define G_LOAD(pr, qr, kt_) if (MODE != 1) { _Pragma("unroll") for (int r = 0; r < NP; ++r) pr[r] = *(const u32x4*)(pp + (size_t)(r * 128) * ldp + (kt_) * BK); \
;                               _Pragma("unroll") for (int r = 0; r < NQ; ++r) qr[r] = *(const u32x4*)(qp + (size_t)(r * 128) * ldq + (kt_) * BK); }
; #define G_STORE(pr, qr, so_) { unsigned char* w_ = wP + (so_); \
;                               _Pragma("unroll") for (int r = 0; r < NP; ++r) *(u32x4*)(w_ + r * 128 * LROW) = pr[r]; \
;                               _Pragma("unroll") for (int r = 0; r < NQ; ++r) *(u32x4*)(w_ + BI * LROW + r * 128 * LROW) = qr[r]; }
; #define F_LOAD(fa, fb, so_, ks_) { _Pragma("unroll") for (int it = 0; it < WI; ++it) fa[it] = *(const bf16x8*)(rP + (so_) + it * 32 * LROW + (ks_) * 32); \
;                                   _Pragma("unroll") for (int jt = 0; jt < 2; ++jt) fb[jt] = *(const bf16x8*)(rQ + (so_) + jt * 32 * LROW + (ks_) * 32); }
;     ...
;     G_LOAD(p0, q0, 0)
;     G_LOAD(p1, q1, 1)
;     G_LOAD(p2, q2, 2)
;     G_STORE(p0, q0, 0)
;     G_LOAD(p0, q0, 3)
;     G_STORE(p1, q1, STAGE)
;     __syncthreads();
;     F_LOAD(fa0, fb0, 0, 0)
; DI void phase4(const Params& p, unsigned char* smem, int tid) {
;     ...
;                     for (int gp = 0; gp < 2; ++gp) {
;                         const u32x4 a4 = *(const u32x4*)(ga + ((it * 2 + jt) * 2 + gp) * 1024), b4 = *(const u32x4*)(gb + ((it * 2 + jt) * 2 + gp) * 1024);
; #pragma unroll
;                         for (int e = 0; e < 4; ++e) {
;                             acc[it][jt][8 * gp + 2 * e] *= bf_lo(a4[e]) * __builtin_amdgcn_rcpf(fmaxf(bf_lo(b4[e]), 8.6736174e-19f));
;                             acc[it][jt][8 * gp + 2 * e + 1] *= bf_hi(a4[e]) * __builtin_amdgcn_rcpf(fmaxf(bf_hi(b4[e]), 8.6736174e-19f));
;                         }
;                     }
;         }
;         { int tl = tid; asm volatile("" : "+v"(tl));
;           gemm_tile3r<4, 4, 0, false>((const bf16_t*)(ws + OFF_WBF) + (size_t)f * 256 * 1024, 1024, (const bf16_t*)(ws + OFF_FQ) + (size_t)r0 * 1024, 1024, 1024, lds, acc, tl); }
	v_and_b32_e32 v133, 0xffff0000, v145
	v_ashrrev_i32_e32 v183, 31, v182
	v_max_f32_e32 v152, 0x21800000, v152
	v_rcp_f32_e32 v153, v128
	v_lshlrev_b32_e32 v128, 16, v129
	v_and_b32_e32 v129, 0xffff0000, v129
	v_pk_mul_f32 v[148:149], v[134:135], v[132:133]
	v_lshlrev_b64 v[190:191], 11, v[182:183]
	v_lshlrev_b32_e32 v134, 4, v210
	v_rcp_f32_e32 v152, v152
	v_max_f32_e32 v128, v128, v128
	v_max_f32_e32 v129, v129, v129
	v_lshl_add_u64 v[132:133], s[58:59], 0, v[190:191]
	s_mov_b64 s[98:99], s[58:59]
	v_and_b32_e32 v212, 48, v134
	v_max_f32_e32 v128, 0x21800000, v128
	v_max_f32_e32 v129, 0x21800000, v129
	v_lshl_add_u64 v[184:185], v[132:133], 0, v[212:213]
	v_add_u32_e32 v250, v190, v212
	v_add_u32_e32 v251, 0x40000, v250
	v_rcp_f32_e32 v128, v128
	v_rcp_f32_e32 v129, v129
	v_lshl_add_u64 v[140:141], s[18:19], 0, v[190:191]
	s_mov_b64 s[100:101], s[18:19]
	v_add_co_u32_e32 v150, vcc, s34, v184
	v_pk_mul_f32 v[22:23], v[22:23], v[148:149]
	v_lshlrev_b32_e32 v148, 16, v178
	v_and_b32_e32 v149, 0xffff0000, v178
	v_addc_co_u32_e32 v151, vcc, 0, v185, vcc
	v_lshl_add_u64 v[186:187], v[140:141], 0, v[212:213]
	v_pk_mul_f32 v[148:149], v[152:153], v[148:149]
	v_add_co_u32_e32 v188, vcc, s34, v186
	v_pk_mul_f32 v[24:25], v[24:25], v[148:149]
	v_lshlrev_b32_e32 v148, 16, v179
	v_and_b32_e32 v149, 0xffff0000, v179
	v_addc_co_u32_e32 v189, vcc, 0, v187, vcc
	v_pk_mul_f32 v[128:129], v[128:129], v[148:149]
	v_lshlrev_b32_e32 v148, 16, v130
	global_load_dwordx4 v[132:135], v[184:185], off
	global_load_dwordx4 v[136:139], v[150:151], off
	global_load_dwordx4 v[140:143], v[186:187], off
	global_load_dwordx4 v[144:147], v[188:189], off
	global_load_dwordx4 v[192:195], v[184:185], off offset:64
	global_load_dwordx4 v[196:199], v[150:151], off offset:64
	global_load_dwordx4 v[200:203], v[186:187], off offset:64
	v_max_f32_e32 v148, v148, v148
	global_load_dwordx4 v[204:207], v[188:189], off offset:64
	v_max_f32_e32 v148, 0x21800000, v148
	v_rcp_f32_e32 v208, v148
	global_load_dwordx4 v[176:179], v[184:185], off offset:128
	global_load_dwordx4 v[160:163], v[184:185], off offset:192
	global_load_dwordx4 v[172:175], v[150:151], off offset:128
	global_load_dwordx4 v[156:159], v[150:151], off offset:192
	global_load_dwordx4 v[168:171], v[186:187], off offset:128
	global_load_dwordx4 v[152:155], v[186:187], off offset:192
	global_load_dwordx4 v[164:167], v[188:189], off offset:128
	s_nop 0
	global_load_dwordx4 v[148:151], v[188:189], off offset:192
	v_and_b32_e32 v130, 0xffff0000, v130
	v_max_f32_e32 v130, v130, v130
	v_max_f32_e32 v130, 0x21800000, v130
	v_rcp_f32_e32 v209, v130
	v_lshlrev_b32_e32 v130, 16, v131
	v_and_b32_e32 v131, 0xffff0000, v131
	v_max_f32_e32 v130, v130, v130
	v_max_f32_e32 v131, v131, v131
	v_max_f32_e32 v130, 0x21800000, v130
	v_max_f32_e32 v131, 0x21800000, v131
	v_rcp_f32_e32 v130, v130
	v_rcp_f32_e32 v131, v131
	v_pk_mul_f32 v[26:27], v[26:27], v[128:129]
	v_lshlrev_b32_e32 v128, 16, v180
	v_and_b32_e32 v129, 0xffff0000, v180
	v_pk_mul_f32 v[128:129], v[208:209], v[128:129]
	v_lshrrev_b32_e32 v180, 1, v210
	v_pk_mul_f32 v[28:29], v[28:29], v[128:129]
	v_lshlrev_b32_e32 v128, 16, v181
	v_and_b32_e32 v129, 0xffff0000, v181
	v_pk_mul_f32 v[128:129], v[130:131], v[128:129]
	v_and_b32_e32 v131, 31, v210
	v_pk_mul_f32 v[30:31], v[30:31], v[128:129]
	v_ashrrev_i32_e32 v128, 6, v210
	v_lshrrev_b32_e32 v129, 30, v128
	v_add_u32_e32 v129, v128, v129
	v_and_b32_e32 v130, 0x3ffffc, v129
	v_lshlrev_b32_e32 v129, 5, v129
	v_sub_u32_e32 v128, v128, v130
	v_mul_lo_u32 v130, v182, s31
	v_and_or_b32 v129, v129, s33, v131
	v_mul_lo_u32 v129, v129, s31
	v_and_b32_e32 v180, 16, v180
	v_add3_u32 v209, 0, v130, v212
	v_lshl_or_b32 v128, v128, 6, v131
	v_add3_u32 v208, 0, v129, v180
	s_waitcnt vmcnt(15)
	ds_write_b128 v209, v[132:135] offset:2048
	s_waitcnt vmcnt(14)
	ds_write_b128 v209, v[136:139] offset:12288
	s_waitcnt vmcnt(13)
	ds_write_b128 v209, v[140:143] offset:22528
	s_waitcnt vmcnt(12)
	ds_write_b128 v209, v[144:147] offset:32768
	s_waitcnt vmcnt(11)
	ds_write_b128 v209, v[192:195] offset:43008
	s_waitcnt vmcnt(10)
	ds_write_b128 v209, v[196:199] offset:53248
	s_waitcnt vmcnt(9)
	ds_write_b128 v209, v[200:203] offset:63488
	v_add_u32_e32 v193, 0x12000, v209
	v_mul_lo_u32 v128, v128, s31
	s_waitcnt vmcnt(8)
	ds_write_b128 v193, v[204:207]
	s_waitcnt lgkmcnt(0)
	s_barrier
	ds_read_b128 v[144:147], v208 offset:2048
	ds_read_b128 v[140:143], v208 offset:4608
	ds_read_b128 v[136:139], v208 offset:7168
	ds_read_b128 v[132:135], v208 offset:9728
	v_add3_u32 v211, 0, v128, v180
	ds_read_b128 v[180:183], v211 offset:22528
	ds_read_b128 v[128:131], v211 offset:25088
	s_add_u32 s18, s56, s54
	s_addc_u32 s19, s57, 0
	s_add_u32 s12, s56, s12
	s_addc_u32 s13, s57, s13
	v_add_u32_e32 v210, 0x5800, v211
	v_add_u32_e32 v192, 0x19800, v209
	v_add_u32_e32 v195, 0x14800, v209
	v_add_u32_e32 v197, 0x14800, v208
	v_add_u32_e32 v198, 0x19800, v211
	v_add_u32_e32 v194, 0x17000, v209
	v_add_u32_e32 v196, 0x1c000, v209
	v_add_u32_e32 v199, 0x1a200, v211
	v_add_u32_e32 v200, 0x15200, v208
	v_add_u32_e32 v201, 0x15c00, v208
	v_add_u32_e32 v202, 0x16600, v208
	v_add_u32_e32 v203, 0x19820, v211
	v_add_u32_e32 v204, 0x14820, v208
	v_add_u32_e32 v205, 0x1a220, v211
	v_add_u32_e32 v206, 0x15220, v208
	v_add_u32_e32 v207, 0x15c20, v208
	v_add_u32_e32 v214, 0x16620, v208
	v_lshl_add_u64 v[188:189], s[18:19], 0, v[190:191]
	v_lshl_add_u64 v[190:191], s[12:13], 0, v[190:191]
	s_waitcnt lgkmcnt(0)
; #define G_LOAD(pr, qr, kt_) if (MODE != 1) { _Pragma("unroll") for (int r = 0; r < NP; ++r) pr[r] = *(const u32x4*)(pp + (size_t)(r * 128) * ldp + (kt_) * BK); \
;                               _Pragma("unroll") for (int r = 0; r < NQ; ++r) qr[r] = *(const u32x4*)(qp + (size_t)(r * 128) * ldq + (kt_) * BK); }
; #define G_STORE(pr, qr, so_) { unsigned char* w_ = wP + (so_); \
;                               _Pragma("unroll") for (int r = 0; r < NP; ++r) *(u32x4*)(w_ + r * 128 * LROW) = pr[r]; \
;                               _Pragma("unroll") for (int r = 0; r < NQ; ++r) *(u32x4*)(w_ + BI * LROW + r * 128 * LROW) = qr[r]; }
; #define F_LOAD(fa, fb, so_, ks_) { _Pragma("unroll") for (int it = 0; it < WI; ++it) fa[it] = *(const bf16x8*)(rP + (so_) + it * 32 * LROW + (ks_) * 32); \
;                                   _Pragma("unroll") for (int jt = 0; jt < 2; ++jt) fb[jt] = *(const bf16x8*)(rQ + (so_) + jt * 32 * LROW + (ks_) * 32); }
; #define G_LOAD(pr, qr, kt_) if (MODE != 1) { _Pragma("unroll") for (int r = 0; r < NP; ++r) pr[r] = *(const u32x4*)(pp + (size_t)(r * 128) * ldp + (kt_) * BK); \
;                               _Pragma("unroll") for (int r = 0; r < NQ; ++r) qr[r] = *(const u32x4*)(qp + (size_t)(r * 128) * ldq + (kt_) * BK); }
; #define G_STORE(pr, qr, so_) { unsigned char* w_ = wP + (so_); \
;                               _Pragma("unroll") for (int r = 0; r < NP; ++r) *(u32x4*)(w_ + r * 128 * LROW) = pr[r]; \
;                               _Pragma("unroll") for (int r = 0; r < NQ; ++r) *(u32x4*)(w_ + BI * LROW + r * 128 * LROW) = qr[r]; }
;     ...
;     if (MODE == 1) {
; #pragma unroll
;         for (int r = 0; r < NP; ++r) { p0[r] = *(const u32x4*)(pp + (size_t)(r * 128) * ldp); p1[r] = p0[r]; p2[r] = p0[r]; }
; #pragma unroll
;         for (int r = 0; r < NQ; ++r) { q0[r] = *(const u32x4*)(qp + (size_t)(r * 128) * ldq); q1[r] = q0[r]; q2[r] = q0[r]; }
;     }
;     G_LOAD(p0, q0, 0)
;     G_LOAD(p1, q1, 1)
;     G_LOAD(p2, q2, 2)
;     G_STORE(p0, q0, 0)
;     G_LOAD(p0, q0, 3)
;     G_STORE(p1, q1, STAGE)
;     __syncthreads();
;     F_LOAD(fa0, fb0, 0, 0)
;     int cur = 0, nxt = STAGE, wr = 2 * STAGE;
;     int kt = 0;
; #pragma unroll 1
;     for (; kt + 3 <= nk; kt += 3) {
;         G_HALF(p1, q1, p2, q2, kt)
;         G_HALF(p2, q2, p0, q0, kt + 1)
;         G_HALF(p0, q0, p1, q1, kt + 2)
;     }
.LBB0_995:
	s_waitcnt lgkmcnt(4)
	v_mfma_f32_32x32x16_bf16 v[112:127], v[144:147], v[180:183], v[112:127]
	ds_read_b128 v[216:219], v211 offset:22560
	s_waitcnt vmcnt(7)
	ds_write_b128 v195, v[176:179]
	s_waitcnt lgkmcnt(5)
	v_mfma_f32_32x32x16_bf16 v[0:15], v[144:147], v[128:131], v[0:15]
	ds_read_b128 v[176:179], v208 offset:2080
	global_load_dwordx4 v[144:147], v250, s[98:99] offset:256
	s_waitcnt lgkmcnt(5)
	v_mfma_f32_32x32x16_bf16 v[96:111], v[140:143], v[180:183], v[96:111]
	ds_read_b128 v[222:225], v211 offset:25120
	s_waitcnt vmcnt(6)
	ds_write_b128 v194, v[172:175]
	v_mfma_f32_32x32x16_bf16 v[32:47], v[140:143], v[128:131], v[32:47]
	ds_read_b128 v[172:175], v208 offset:4640
	global_load_dwordx4 v[140:143], v251, s[98:99] offset:256
	s_waitcnt lgkmcnt(7)
	v_mfma_f32_32x32x16_bf16 v[80:95], v[136:139], v[180:183], v[80:95]
	s_waitcnt vmcnt(5)
	ds_write_b128 v192, v[168:171]
	v_mfma_f32_32x32x16_bf16 v[48:63], v[136:139], v[128:131], v[48:63]
	ds_read_b128 v[168:171], v208 offset:7200
	global_load_dwordx4 v[136:139], v250, s[100:101] offset:256
	s_waitcnt lgkmcnt(8)
	v_mfma_f32_32x32x16_bf16 v[64:79], v[132:135], v[180:183], v[64:79]
	s_waitcnt vmcnt(4)
	ds_write_b128 v196, v[164:167]
	v_mfma_f32_32x32x16_bf16 v[16:31], v[132:135], v[128:131], v[16:31]
	ds_read_b128 v[132:135], v208 offset:9760
	global_load_dwordx4 v[128:131], v251, s[100:101] offset:256
	s_waitcnt lgkmcnt(7)
	v_mfma_f32_32x32x16_bf16 v[112:127], v[176:179], v[216:219], v[112:127]
	ds_read_b128 v[164:167], v211 offset:63488
	s_waitcnt lgkmcnt(7)
	v_mfma_f32_32x32x16_bf16 v[0:15], v[176:179], v[222:225], v[0:15]
	ds_read_b128 v[176:179], v208 offset:43008
	s_waitcnt lgkmcnt(6)
	v_mfma_f32_32x32x16_bf16 v[96:111], v[172:175], v[216:219], v[96:111]
	ds_read_b128 v[180:183], v210 offset:43520
	v_mfma_f32_32x32x16_bf16 v[32:47], v[172:175], v[222:225], v[32:47]
	ds_read_b128 v[172:175], v208 offset:45568
	s_waitcnt lgkmcnt(6)
	v_mfma_f32_32x32x16_bf16 v[80:95], v[168:171], v[216:219], v[80:95]
	v_mfma_f32_32x32x16_bf16 v[48:63], v[168:171], v[222:225], v[48:63]
	ds_read_b128 v[168:171], v208 offset:48128
	s_waitcnt lgkmcnt(5)
	v_mfma_f32_32x32x16_bf16 v[64:79], v[132:135], v[216:219], v[64:79]
	v_mfma_f32_32x32x16_bf16 v[16:31], v[132:135], v[222:225], v[16:31]
	ds_read_b128 v[132:135], v208 offset:50688
	s_barrier
	s_min_u32 s6, s11, 26
	s_waitcnt lgkmcnt(4)
	v_mfma_f32_32x32x16_bf16 v[112:127], v[176:179], v[164:167], v[112:127]
	ds_read_b128 v[216:219], v211 offset:63520
	ds_write_b128 v209, v[160:163] offset:2048
	s_waitcnt lgkmcnt(5)
	v_mfma_f32_32x32x16_bf16 v[0:15], v[176:179], v[180:183], v[0:15]
	global_load_dwordx4 v[176:179], v250, s[98:99] offset:320
	ds_read_b128 v[160:163], v208 offset:43040
	s_waitcnt lgkmcnt(5)
	v_mfma_f32_32x32x16_bf16 v[96:111], v[172:175], v[164:167], v[96:111]
	ds_read_b128 v[222:225], v210 offset:43552
	ds_write_b128 v209, v[156:159] offset:12288
	v_mfma_f32_32x32x16_bf16 v[32:47], v[172:175], v[180:183], v[32:47]
	global_load_dwordx4 v[172:175], v251, s[98:99] offset:320
	ds_read_b128 v[156:159], v208 offset:45600
	s_waitcnt lgkmcnt(7)
	v_mfma_f32_32x32x16_bf16 v[80:95], v[168:171], v[164:167], v[80:95]
	ds_write_b128 v209, v[152:155] offset:22528
	v_mfma_f32_32x32x16_bf16 v[48:63], v[168:171], v[180:183], v[48:63]
	global_load_dwordx4 v[168:171], v250, s[100:101] offset:320
	ds_read_b128 v[152:155], v208 offset:48160
	s_waitcnt lgkmcnt(8)
	v_mfma_f32_32x32x16_bf16 v[64:79], v[132:135], v[164:167], v[64:79]
	s_waitcnt vmcnt(7)
	ds_write_b128 v209, v[148:151] offset:32768
	v_mfma_f32_32x32x16_bf16 v[16:31], v[132:135], v[180:183], v[16:31]
	global_load_dwordx4 v[164:167], v251, s[100:101] offset:320
	ds_read_b128 v[132:135], v208 offset:50720
	s_waitcnt lgkmcnt(7)
	v_mfma_f32_32x32x16_bf16 v[112:127], v[160:163], v[216:219], v[112:127]
	ds_read_b128 v[148:151], v198
	s_waitcnt lgkmcnt(7)
	v_mfma_f32_32x32x16_bf16 v[0:15], v[160:163], v[222:225], v[0:15]
	ds_read_b128 v[160:163], v197
	s_waitcnt lgkmcnt(6)
	v_mfma_f32_32x32x16_bf16 v[96:111], v[156:159], v[216:219], v[96:111]
	ds_read_b128 v[180:183], v199
	v_mfma_f32_32x32x16_bf16 v[32:47], v[156:159], v[222:225], v[32:47]
	ds_read_b128 v[156:159], v200
	s_waitcnt lgkmcnt(6)
	v_mfma_f32_32x32x16_bf16 v[80:95], v[152:155], v[216:219], v[80:95]
	v_mfma_f32_32x32x16_bf16 v[48:63], v[152:155], v[222:225], v[48:63]
	ds_read_b128 v[152:155], v201
	s_waitcnt lgkmcnt(5)
	v_mfma_f32_32x32x16_bf16 v[64:79], v[132:135], v[216:219], v[64:79]
	v_mfma_f32_32x32x16_bf16 v[16:31], v[132:135], v[222:225], v[16:31]
	ds_read_b128 v[132:135], v202
	s_barrier
; #define G_LOAD(pr, qr, kt_) if (MODE != 1) { _Pragma("unroll") for (int r = 0; r < NP; ++r) pr[r] = *(const u32x4*)(pp + (size_t)(r * 128) * ldp + (kt_) * BK); \
;                               _Pragma("unroll") for (int r = 0; r < NQ; ++r) qr[r] = *(const u32x4*)(qp + (size_t)(r * 128) * ldq + (kt_) * BK); }
; #define G_STORE(pr, qr, so_) { unsigned char* w_ = wP + (so_); \
;                               _Pragma("unroll") for (int r = 0; r < NP; ++r) *(u32x4*)(w_ + r * 128 * LROW) = pr[r]; \
;                               _Pragma("unroll") for (int r = 0; r < NQ; ++r) *(u32x4*)(w_ + BI * LROW + r * 128 * LROW) = qr[r]; }
; #define F_LOAD(fa, fb, so_, ks_) { _Pragma("unroll") for (int it = 0; it < WI; ++it) fa[it] = *(const bf16x8*)(rP + (so_) + it * 32 * LROW + (ks_) * 32); \
;                                   _Pragma("unroll") for (int jt = 0; jt < 2; ++jt) fb[jt] = *(const bf16x8*)(rQ + (so_) + jt * 32 * LROW + (ks_) * 32); }
; #define G_LOAD(pr, qr, kt_) if (MODE != 1) { _Pragma("unroll") for (int r = 0; r < NP; ++r) pr[r] = *(const u32x4*)(pp + (size_t)(r * 128) * ldp + (kt_) * BK); \
;                               _Pragma("unroll") for (int r = 0; r < NQ; ++r) qr[r] = *(const u32x4*)(qp + (size_t)(r * 128) * ldq + (kt_) * BK); }
;     ...
;     if (MODE == 1) {
; #pragma unroll
;         for (int r = 0; r < NP; ++r) { p0[r] = *(const u32x4*)(pp + (size_t)(r * 128) * ldp); p1[r] = p0[r]; p2[r] = p0[r]; }
; #pragma unroll
;         for (int r = 0; r < NQ; ++r) { q0[r] = *(const u32x4*)(qp + (size_t)(r * 128) * ldq); q1[r] = q0[r]; q2[r] = q0[r]; }
;     }
;     G_LOAD(p0, q0, 0)
;     G_LOAD(p1, q1, 1)
;     G_LOAD(p2, q2, 2)
;     G_STORE(p0, q0, 0)
;     G_LOAD(p0, q0, 3)
;     G_STORE(p1, q1, STAGE)
;     __syncthreads();
;     F_LOAD(fa0, fb0, 0, 0)
;     int cur = 0, nxt = STAGE, wr = 2 * STAGE;
;     int kt = 0;
; #pragma unroll 1
;     for (; kt + 3 <= nk; kt += 3) {
;         G_HALF(p1, q1, p2, q2, kt)
;         G_HALF(p2, q2, p0, q0, kt + 1)
;         G_HALF(p0, q0, p1, q1, kt + 2)
;     }
;     if (kt < nk) G_HALF(p1, q1, p2, q2, kt)
;     if (kt + 1 < nk) G_HALF(p2, q2, p0, q0, kt + 1)
	s_min_u32 s6, s11, 25
	s_waitcnt lgkmcnt(4)
	v_mfma_f32_32x32x16_bf16 v[112:127], v[160:163], v[148:151], v[112:127]
	ds_read_b128 v[216:219], v203
	s_waitcnt vmcnt(7)
	ds_write_b128 v209, v[144:147] offset:43008
	s_waitcnt lgkmcnt(5)
	v_mfma_f32_32x32x16_bf16 v[0:15], v[160:163], v[180:183], v[0:15]
	global_load_dwordx4 v[160:163], v250, s[98:99] offset:384
	ds_read_b128 v[144:147], v204
	s_waitcnt lgkmcnt(5)
	v_mfma_f32_32x32x16_bf16 v[96:111], v[156:159], v[148:151], v[96:111]
	ds_read_b128 v[222:225], v205
	s_waitcnt vmcnt(7)
	ds_write_b128 v209, v[140:143] offset:53248
	v_mfma_f32_32x32x16_bf16 v[32:47], v[156:159], v[180:183], v[32:47]
	global_load_dwordx4 v[156:159], v251, s[98:99] offset:384
	ds_read_b128 v[140:143], v206
	s_waitcnt lgkmcnt(7)
	v_mfma_f32_32x32x16_bf16 v[80:95], v[152:155], v[148:151], v[80:95]
	s_waitcnt vmcnt(7)
	ds_write_b128 v209, v[136:139] offset:63488
	v_mfma_f32_32x32x16_bf16 v[48:63], v[152:155], v[180:183], v[48:63]
	global_load_dwordx4 v[152:155], v250, s[100:101] offset:384
	ds_read_b128 v[136:139], v207
	s_waitcnt lgkmcnt(8)
	v_mfma_f32_32x32x16_bf16 v[64:79], v[132:135], v[148:151], v[64:79]
	s_waitcnt vmcnt(7)
	ds_write_b128 v193, v[128:131]
	v_mfma_f32_32x32x16_bf16 v[16:31], v[132:135], v[180:183], v[16:31]
	ds_read_b128 v[132:135], v214
	global_load_dwordx4 v[148:151], v251, s[100:101] offset:384
	s_waitcnt lgkmcnt(7)
	v_mfma_f32_32x32x16_bf16 v[112:127], v[144:147], v[216:219], v[112:127]
	ds_read_b128 v[180:183], v211 offset:22528
	s_waitcnt lgkmcnt(7)
	v_mfma_f32_32x32x16_bf16 v[0:15], v[144:147], v[222:225], v[0:15]
	ds_read_b128 v[144:147], v208 offset:2048
	s_waitcnt lgkmcnt(6)
	v_mfma_f32_32x32x16_bf16 v[96:111], v[140:143], v[216:219], v[96:111]
	ds_read_b128 v[128:131], v211 offset:25088
	v_mfma_f32_32x32x16_bf16 v[32:47], v[140:143], v[222:225], v[32:47]
	ds_read_b128 v[140:143], v208 offset:4608
	s_waitcnt lgkmcnt(6)
	v_mfma_f32_32x32x16_bf16 v[80:95], v[136:139], v[216:219], v[80:95]
	v_mfma_f32_32x32x16_bf16 v[48:63], v[136:139], v[222:225], v[48:63]
	ds_read_b128 v[136:139], v208 offset:7168
	s_waitcnt lgkmcnt(5)
	v_mfma_f32_32x32x16_bf16 v[64:79], v[132:135], v[216:219], v[64:79]
	v_mfma_f32_32x32x16_bf16 v[16:31], v[132:135], v[222:225], v[16:31]
	ds_read_b128 v[132:135], v208 offset:9728
	s_add_i32 s11, s11, 3
	v_add_u32_e32 v250, 0xc0, v250
	s_cmp_lt_u32 s11, 30
	v_add_u32_e32 v251, 0xc0, v251
	s_barrier
	s_cbranch_scc1 .LBB0_995
	s_waitcnt lgkmcnt(0)
	v_mfma_f32_32x32x16_bf16 v[112:127], v[144:147], v[180:183], v[112:127]
	ds_read_b128 v[214:217], v211 offset:22560
	s_waitcnt vmcnt(7)
	ds_write_b128 v195, v[176:179]
	ds_read_b128 v[200:203], v208 offset:2080
	v_mfma_f32_32x32x16_bf16 v[96:111], v[140:143], v[180:183], v[96:111]
	ds_read_b128 v[188:191], v211 offset:25120
	s_waitcnt vmcnt(6)
	ds_write_b128 v194, v[172:175]
	ds_read_b128 v[204:207], v208 offset:4640
	v_mfma_f32_32x32x16_bf16 v[80:95], v[136:139], v[180:183], v[80:95]
	s_waitcnt vmcnt(5)
	ds_write_b128 v192, v[168:171]
	ds_read_b128 v[192:195], v208 offset:7200
	v_mfma_f32_32x32x16_bf16 v[64:79], v[132:135], v[180:183], v[64:79]
	s_waitcnt vmcnt(4)
	ds_write_b128 v196, v[164:167]
	ds_read_b128 v[196:199], v208 offset:9760
	s_waitcnt lgkmcnt(7)
	v_mfma_f32_32x32x16_bf16 v[112:127], v[200:203], v[214:217], v[112:127]
	ds_read_b128 v[222:225], v211 offset:63488
	ds_read_b128 v[184:187], v208 offset:43008
	s_waitcnt lgkmcnt(6)
	v_mfma_f32_32x32x16_bf16 v[96:111], v[204:207], v[214:217], v[96:111]
	ds_read_b128 v[164:167], v210 offset:43520
	ds_read_b128 v[176:179], v208 offset:45568
	s_waitcnt lgkmcnt(6)
	v_mfma_f32_32x32x16_bf16 v[80:95], v[192:195], v[214:217], v[80:95]
	ds_read_b128 v[172:175], v208 offset:48128
	s_waitcnt lgkmcnt(5)
	v_mfma_f32_32x32x16_bf16 v[64:79], v[196:199], v[214:217], v[64:79]
	ds_read_b128 v[168:171], v208 offset:50688
	s_waitcnt lgkmcnt(0)
	s_barrier
	v_mfma_f32_32x32x16_bf16 v[112:127], v[184:187], v[222:225], v[112:127]
	ds_read_b128 v[214:217], v211 offset:63520
	s_waitcnt vmcnt(3)
	ds_write_b128 v209, v[160:163] offset:2048
	ds_read_b128 v[180:183], v208 offset:43040
	v_mfma_f32_32x32x16_bf16 v[96:111], v[176:179], v[222:225], v[96:111]
	ds_read_b128 v[160:163], v210 offset:43552
	s_waitcnt vmcnt(2)
	ds_write_b128 v209, v[156:159] offset:12288
	ds_read_b128 v[156:159], v208 offset:45600
	v_mfma_f32_32x32x16_bf16 v[80:95], v[172:175], v[222:225], v[80:95]
	s_waitcnt vmcnt(1)
	ds_write_b128 v209, v[152:155] offset:22528
	ds_read_b128 v[152:155], v208 offset:48160
	v_mfma_f32_32x32x16_bf16 v[64:79], v[168:171], v[222:225], v[64:79]
	s_waitcnt vmcnt(0)
	ds_write_b128 v209, v[148:151] offset:32768
	ds_read_b128 v[148:151], v208 offset:50720
	s_waitcnt lgkmcnt(7)
	v_mfma_f32_32x32x16_bf16 v[112:127], v[180:183], v[214:217], v[112:127]
	s_waitcnt lgkmcnt(4)
	v_mfma_f32_32x32x16_bf16 v[96:111], v[156:159], v[214:217], v[96:111]
	s_waitcnt lgkmcnt(2)
	v_mfma_f32_32x32x16_bf16 v[80:95], v[152:155], v[214:217], v[80:95]
	s_waitcnt lgkmcnt(0)
	v_mfma_f32_32x32x16_bf16 v[64:79], v[148:151], v[214:217], v[64:79]
	s_add_i32 s12, s14, 0x100
	v_mov_b32_e32 v221, v220
	s_ashr_i32 s13, s12, 31
	s_barrier
; DI u32x2 pk4(float a, float b, float c, float d) { u32x2 r; r.x = pk2(a, b); r.y = pk2(c, d); return r; }
; DI float bf_lo(unsigned u) { return __uint_as_float(u << 16); }
; DI float bf_hi(unsigned u) { return __uint_as_float(u & 0xffff0000u); }
; template <int WI, int WGJ, class GetF, class FinF>
; DI void staged_rows(unsigned char* lds, int tid, GetF get, FinF fin) {
;     ...
;     for (int jt = 0; jt < 2; ++jt) {
;         unsigned char* wrow = lds + (wj * 32 + ln) * RS + (wi * WI * 32 + 4 * h) * 2;
; #pragma unroll
;         for (int it = 0; it < WI; ++it)
; #pragma unroll
;             for (int g = 0; g < 4; ++g) *(u32x2*)(wrow + (it * 32 + 8 * g) * 2) = get(it, jt, g);
;         __syncthreads();
; DI void phase4(const Params& p, unsigned char* smem, int tid) {
;     ...
;         {
;             int te = tid; asm volatile("" : "+v"(te));
;             const unsigned char* gb = ws + OFF_G + ((size_t)((4 + f) * 64 + tt) * 8 + (te >> 6)) * 16384 + (te & 63) * 16;
;             staged_rows<4, 4>(lds, te,
;                 [&](int it, int jt, int g) { const u32x4 b4 = *(const u32x4*)(gb + ((it * 2 + jt) * 2 + (g >> 1)) * 1024); const int e0 = (g & 1) * 2;
;                     const float g0 = fmaxf(bf_lo(b4[e0]), 8.6736174e-19f), g1 = fmaxf(bf_hi(b4[e0]), 8.6736174e-19f);
;                     const float g2 = fmaxf(bf_lo(b4[e0 + 1]), 8.6736174e-19f), g3 = fmaxf(bf_hi(b4[e0 + 1]), 8.6736174e-19f);
;                     return pk4(acc[it][jt][4 * g] * g0, acc[it][jt][4 * g + 1] * g1, acc[it][jt][4 * g + 2] * g2, acc[it][jt][4 * g + 3] * g3); },
;                 [&](int row, int col, u32x4 v) { __builtin_nontemporal_store(v, (u32x4*)(mx + (size_t)(r0 + row) * 1024 + f * 256 + col)); });
	s_lshl_b64 s[12:13], s[12:13], 17
	v_ashrrev_i32_e32 v208, 6, v221
	v_ashrrev_i32_e32 v209, 31, v208
	s_add_u32 s12, s24, s12
	v_lshlrev_b64 v[210:211], 14, v[208:209]
	s_addc_u32 s13, s25, s13
	v_lshlrev_b32_e32 v209, 4, v221
	v_lshl_add_u64 v[210:211], s[12:13], 0, v[210:211]
	v_and_b32_e32 v212, 0x3f0, v209
	v_lshl_add_u64 v[216:217], v[210:211], 0, v[212:213]
	global_load_dwordx4 v[222:225], v[216:217], off
	global_load_dwordx4 v[226:229], v[216:217], off offset:1024
	v_add_co_u32_e32 v214, vcc, s42, v216
	v_lshrrev_b32_e32 v210, 2, v221
	s_nop 0
	v_addc_co_u32_e32 v215, vcc, 0, v217, vcc
	global_load_dwordx4 v[230:233], v[214:215], off offset:-4096
	v_lshrrev_b32_e32 v211, 30, v208
	v_and_b32_e32 v212, 8, v210
	v_add_u32_e32 v210, v208, v211
	v_and_b32_e32 v211, 0x7ffffc, v210
	v_and_b32_e32 v209, 31, v221
	v_sub_u32_e32 v208, v208, v211
	v_lshlrev_b32_e32 v210, 6, v210
	v_lshl_or_b32 v208, v208, 5, v209
	v_add_co_u32_e32 v218, vcc, s40, v216
	v_and_b32_e32 v234, 0xffffff00, v210
	s_nop 0
	v_addc_co_u32_e32 v219, vcc, 0, v217, vcc
	v_mul_lo_u32 v235, v208, s50
	global_load_dwordx4 v[208:211], v[218:219], off offset:1024
	v_add3_u32 v234, 0, v235, v234
	v_add_u32_e32 v212, v234, v212
	v_add_u32_e32 v212, 0x800, v212
	s_lshl_b32 s11, s53, 9
	s_add_u32 s12, s3, s11
	s_mov_b32 s6, 0
	s_addc_u32 s13, s16, 0
	s_waitcnt vmcnt(3)
	v_lshlrev_b32_e32 v234, 16, v222
	v_and_b32_e32 v222, 0xffff0000, v222
	v_lshlrev_b32_e32 v235, 16, v223
	v_and_b32_e32 v223, 0xffff0000, v223
	v_lshlrev_b32_e32 v236, 16, v224
	v_and_b32_e32 v224, 0xffff0000, v224
	v_lshlrev_b32_e32 v237, 16, v225
	v_and_b32_e32 v225, 0xffff0000, v225
	s_waitcnt vmcnt(2)
	v_lshlrev_b32_e32 v238, 16, v226
	v_and_b32_e32 v226, 0xffff0000, v226
	v_lshlrev_b32_e32 v239, 16, v227
	v_and_b32_e32 v227, 0xffff0000, v227
	v_max_f32_e32 v234, v234, v234
	v_max_f32_e32 v241, v222, v222
	v_max_f32_e32 v235, v235, v235
	v_max_f32_e32 v242, v223, v223
	v_max_f32_e32 v236, v236, v236
	v_max_f32_e32 v243, v224, v224
	v_max_f32_e32 v237, v237, v237
	v_max_f32_e32 v244, v225, v225
	v_max_f32_e32 v245, v226, v226
	v_max_f32_e32 v246, v227, v227
	v_max_f32_e32 v222, 0x21800000, v234
	v_max_f32_e32 v223, 0x21800000, v241
	v_max_f32_e32 v224, 0x21800000, v235
	v_max_f32_e32 v225, 0x21800000, v242
	v_max_f32_e32 v226, 0x21800000, v236
	v_max_f32_e32 v227, 0x21800000, v243
	v_max_f32_e32 v234, 0x21800000, v237
	v_max_f32_e32 v235, 0x21800000, v244
	v_pk_mul_f32 v[112:113], v[112:113], v[222:223]
	v_pk_mul_f32 v[114:115], v[114:115], v[224:225]
	v_pk_mul_f32 v[116:117], v[116:117], v[226:227]
	v_pk_mul_f32 v[118:119], v[118:119], v[234:235]
	v_lshlrev_b32_e32 v240, 16, v228
	v_cvt_pk_bf16_f32 v112, v112, v113
	v_cvt_pk_bf16_f32 v113, v114, v115
	v_cvt_pk_bf16_f32 v114, v116, v117
	v_cvt_pk_bf16_f32 v115, v118, v119
	ds_write2_b64 v212, v[112:113], v[114:115] offset1:2
	v_max_f32_e32 v112, v240, v240
	v_max_f32_e32 v118, 0x21800000, v112
	v_and_b32_e32 v112, 0xffff0000, v228
	v_max_f32_e32 v238, v238, v238
	v_max_f32_e32 v112, v112, v112
	v_max_f32_e32 v236, 0x21800000, v238
	v_max_f32_e32 v237, 0x21800000, v245
	v_max_f32_e32 v119, 0x21800000, v112
	v_lshlrev_b32_e32 v112, 16, v229
	v_pk_mul_f32 v[120:121], v[120:121], v[236:237]
	v_max_f32_e32 v112, v112, v112
	v_cvt_pk_bf16_f32 v116, v120, v121
	v_max_f32_e32 v120, 0x21800000, v112
	v_and_b32_e32 v112, 0xffff0000, v229
	v_max_f32_e32 v121, v112, v112
	global_load_dwordx4 v[112:115], v[214:215], off
	v_max_f32_e32 v239, v239, v239
	v_max_f32_e32 v238, 0x21800000, v239
	v_max_f32_e32 v239, 0x21800000, v246
	v_max_f32_e32 v121, 0x21800000, v121
	v_pk_mul_f32 v[122:123], v[122:123], v[238:239]
	v_pk_mul_f32 v[118:119], v[124:125], v[118:119]
	v_pk_mul_f32 v[120:121], v[126:127], v[120:121]
	v_cvt_pk_bf16_f32 v117, v122, v123
	v_cvt_pk_bf16_f32 v118, v118, v119
	v_cvt_pk_bf16_f32 v119, v120, v121
	ds_write2_b64 v212, v[116:117], v[118:119] offset0:4 offset1:6
	s_waitcnt vmcnt(2)
	v_lshlrev_b32_e32 v116, 16, v230
	v_and_b32_e32 v117, 0xffff0000, v230
	v_lshlrev_b32_e32 v118, 16, v231
	v_and_b32_e32 v119, 0xffff0000, v231
	v_max_f32_e32 v116, v116, v116
	v_max_f32_e32 v117, v117, v117
	v_max_f32_e32 v118, v118, v118
	v_max_f32_e32 v119, v119, v119
	v_max_f32_e32 v116, 0x21800000, v116
	v_max_f32_e32 v117, 0x21800000, v117
	v_max_f32_e32 v118, 0x21800000, v118
	v_max_f32_e32 v119, 0x21800000, v119
	v_pk_mul_f32 v[96:97], v[96:97], v[116:117]
	v_pk_mul_f32 v[98:99], v[98:99], v[118:119]
	v_cvt_pk_bf16_f32 v96, v96, v97
	v_cvt_pk_bf16_f32 v97, v98, v99
	v_lshlrev_b32_e32 v98, 16, v232
	v_and_b32_e32 v99, 0xffff0000, v232
	v_lshlrev_b32_e32 v116, 16, v233
	v_and_b32_e32 v121, 0xffff0000, v233
	v_max_f32_e32 v98, v98, v98
	v_max_f32_e32 v99, v99, v99
	v_max_f32_e32 v116, v116, v116
	v_max_f32_e32 v121, v121, v121
	v_max_f32_e32 v98, 0x21800000, v98
	v_max_f32_e32 v99, 0x21800000, v99
	v_max_f32_e32 v120, 0x21800000, v116
	v_max_f32_e32 v121, 0x21800000, v121
	v_pk_mul_f32 v[98:99], v[100:101], v[98:99]
	v_pk_mul_f32 v[100:101], v[102:103], v[120:121]
	v_cvt_pk_bf16_f32 v98, v98, v99
	v_cvt_pk_bf16_f32 v99, v100, v101
	global_load_dwordx4 v[116:119], v[214:215], off offset:1024
	ds_write2_b64 v212, v[96:97], v[98:99] offset0:8 offset1:10
	s_waitcnt vmcnt(2)
; DI u32x2 pk4(float a, float b, float c, float d) { u32x2 r; r.x = pk2(a, b); r.y = pk2(c, d); return r; }
; DI float bf_lo(unsigned u) { return __uint_as_float(u << 16); }
; DI float bf_hi(unsigned u) { return __uint_as_float(u & 0xffff0000u); }
; template <int WI, int WGJ, class GetF, class FinF>
; DI void staged_rows(unsigned char* lds, int tid, GetF get, FinF fin) {
;     ...
;     for (int jt = 0; jt < 2; ++jt) {
;         unsigned char* wrow = lds + (wj * 32 + ln) * RS + (wi * WI * 32 + 4 * h) * 2;
; #pragma unroll
;         for (int it = 0; it < WI; ++it)
; #pragma unroll
;             for (int g = 0; g < 4; ++g) *(u32x2*)(wrow + (it * 32 + 8 * g) * 2) = get(it, jt, g);
;         __syncthreads();
; DI void phase4(const Params& p, unsigned char* smem, int tid) {
;     ...
;         {
;             int te = tid; asm volatile("" : "+v"(te));
;             const unsigned char* gb = ws + OFF_G + ((size_t)((4 + f) * 64 + tt) * 8 + (te >> 6)) * 16384 + (te & 63) * 16;
;             staged_rows<4, 4>(lds, te,
;                 [&](int it, int jt, int g) { const u32x4 b4 = *(const u32x4*)(gb + ((it * 2 + jt) * 2 + (g >> 1)) * 1024); const int e0 = (g & 1) * 2;
;                     const float g0 = fmaxf(bf_lo(b4[e0]), 8.6736174e-19f), g1 = fmaxf(bf_hi(b4[e0]), 8.6736174e-19f);
;                     const float g2 = fmaxf(bf_lo(b4[e0 + 1]), 8.6736174e-19f), g3 = fmaxf(bf_hi(b4[e0 + 1]), 8.6736174e-19f);
;                     return pk4(acc[it][jt][4 * g] * g0, acc[it][jt][4 * g + 1] * g1, acc[it][jt][4 * g + 2] * g2, acc[it][jt][4 * g + 3] * g3); },
;                 [&](int row, int col, u32x4 v) { __builtin_nontemporal_store(v, (u32x4*)(mx + (size_t)(r0 + row) * 1024 + f * 256 + col)); });
	v_lshlrev_b32_e32 v96, 16, v208
	v_and_b32_e32 v97, 0xffff0000, v208
	v_max_f32_e32 v96, v96, v96
	v_max_f32_e32 v97, v97, v97
	v_max_f32_e32 v96, 0x21800000, v96
	v_max_f32_e32 v97, 0x21800000, v97
	v_pk_mul_f32 v[96:97], v[104:105], v[96:97]
	v_lshlrev_b32_e32 v98, 16, v209
	v_and_b32_e32 v99, 0xffff0000, v209
	v_cvt_pk_bf16_f32 v102, v96, v97
	v_lshlrev_b32_e32 v96, 16, v210
	v_max_f32_e32 v98, v98, v98
	v_max_f32_e32 v99, v99, v99
	v_max_f32_e32 v96, v96, v96
	v_max_f32_e32 v98, 0x21800000, v98
	v_max_f32_e32 v99, 0x21800000, v99
	v_max_f32_e32 v104, 0x21800000, v96
	v_and_b32_e32 v96, 0xffff0000, v210
	v_pk_mul_f32 v[98:99], v[106:107], v[98:99]
	v_max_f32_e32 v105, v96, v96
	v_add_co_u32_e32 v96, vcc, s44, v216
	v_lshlrev_b32_e32 v106, 16, v211
	v_and_b32_e32 v107, 0xffff0000, v211
	v_addc_co_u32_e32 v97, vcc, 0, v217, vcc
	v_max_f32_e32 v106, v106, v106
	v_max_f32_e32 v107, v107, v107
	v_cvt_pk_bf16_f32 v103, v98, v99
	global_load_dwordx4 v[98:101], v[96:97], off
	v_max_f32_e32 v105, 0x21800000, v105
	v_max_f32_e32 v106, 0x21800000, v106
	v_max_f32_e32 v107, 0x21800000, v107
	v_pk_mul_f32 v[104:105], v[108:109], v[104:105]
	v_pk_mul_f32 v[106:107], v[110:111], v[106:107]
	v_cvt_pk_bf16_f32 v104, v104, v105
	v_cvt_pk_bf16_f32 v105, v106, v107
	ds_write2_b64 v212, v[102:103], v[104:105] offset0:12 offset1:14
	s_waitcnt vmcnt(2)
	v_lshlrev_b32_e32 v102, 16, v112
	v_and_b32_e32 v103, 0xffff0000, v112
	v_max_f32_e32 v102, v102, v102
	v_max_f32_e32 v103, v103, v103
	v_max_f32_e32 v102, 0x21800000, v102
	v_max_f32_e32 v103, 0x21800000, v103
	v_lshlrev_b32_e32 v104, 16, v113
	v_and_b32_e32 v105, 0xffff0000, v113
	v_max_f32_e32 v104, v104, v104
	v_max_f32_e32 v105, v105, v105
	v_pk_mul_f32 v[80:81], v[80:81], v[102:103]
	v_max_f32_e32 v104, 0x21800000, v104
	v_max_f32_e32 v105, 0x21800000, v105
	v_cvt_pk_bf16_f32 v102, v80, v81
	v_lshlrev_b32_e32 v80, 16, v114
	v_pk_mul_f32 v[82:83], v[82:83], v[104:105]
	v_max_f32_e32 v80, v80, v80
	v_cvt_pk_bf16_f32 v103, v82, v83
	v_max_f32_e32 v104, 0x21800000, v80
	global_load_dwordx4 v[80:83], v[96:97], off offset:1024
	v_and_b32_e32 v105, 0xffff0000, v114
	v_lshlrev_b32_e32 v106, 16, v115
	v_and_b32_e32 v107, 0xffff0000, v115
	v_max_f32_e32 v105, v105, v105
	v_max_f32_e32 v106, v106, v106
	v_max_f32_e32 v107, v107, v107
	v_max_f32_e32 v105, 0x21800000, v105
	v_max_f32_e32 v106, 0x21800000, v106
	v_max_f32_e32 v107, 0x21800000, v107
	v_pk_mul_f32 v[84:85], v[84:85], v[104:105]
	v_pk_mul_f32 v[86:87], v[86:87], v[106:107]
	v_cvt_pk_bf16_f32 v84, v84, v85
	v_cvt_pk_bf16_f32 v85, v86, v87
	ds_write2_b64 v212, v[102:103], v[84:85] offset0:16 offset1:18
	s_waitcnt vmcnt(2)
	v_lshlrev_b32_e32 v84, 16, v116
	v_and_b32_e32 v85, 0xffff0000, v116
	v_lshlrev_b32_e32 v86, 16, v117
	v_and_b32_e32 v87, 0xffff0000, v117
	v_max_f32_e32 v84, v84, v84
	v_max_f32_e32 v85, v85, v85
	v_max_f32_e32 v86, v86, v86
	v_max_f32_e32 v87, v87, v87
	v_max_f32_e32 v84, 0x21800000, v84
	v_max_f32_e32 v85, 0x21800000, v85
	v_max_f32_e32 v86, 0x21800000, v86
	v_max_f32_e32 v87, 0x21800000, v87
	v_pk_mul_f32 v[84:85], v[88:89], v[84:85]
	v_pk_mul_f32 v[86:87], v[90:91], v[86:87]
	v_cvt_pk_bf16_f32 v84, v84, v85
	v_cvt_pk_bf16_f32 v85, v86, v87
	v_lshlrev_b32_e32 v86, 16, v118
	v_and_b32_e32 v87, 0xffff0000, v118
	v_lshlrev_b32_e32 v88, 16, v119
	v_and_b32_e32 v89, 0xffff0000, v119
	v_max_f32_e32 v86, v86, v86
	v_max_f32_e32 v87, v87, v87
	v_max_f32_e32 v88, v88, v88
	v_max_f32_e32 v89, v89, v89
	v_max_f32_e32 v86, 0x21800000, v86
	v_max_f32_e32 v87, 0x21800000, v87
	v_max_f32_e32 v88, 0x21800000, v88
	v_max_f32_e32 v89, 0x21800000, v89
	v_pk_mul_f32 v[86:87], v[92:93], v[86:87]
	v_pk_mul_f32 v[88:89], v[94:95], v[88:89]
	v_cvt_pk_bf16_f32 v86, v86, v87
	v_cvt_pk_bf16_f32 v87, v88, v89
	ds_write2_b64 v212, v[84:85], v[86:87] offset0:20 offset1:22
	s_waitcnt vmcnt(1)
	v_lshlrev_b32_e32 v84, 16, v98
	v_and_b32_e32 v85, 0xffff0000, v98
	v_lshlrev_b32_e32 v86, 16, v99
	v_and_b32_e32 v87, 0xffff0000, v99
	v_max_f32_e32 v84, v84, v84
	v_max_f32_e32 v85, v85, v85
	v_max_f32_e32 v86, v86, v86
	v_max_f32_e32 v87, v87, v87
	v_max_f32_e32 v84, 0x21800000, v84
	v_max_f32_e32 v85, 0x21800000, v85
	v_max_f32_e32 v86, 0x21800000, v86
	v_max_f32_e32 v87, 0x21800000, v87
	v_pk_mul_f32 v[64:65], v[64:65], v[84:85]
	v_pk_mul_f32 v[66:67], v[66:67], v[86:87]
	v_cvt_pk_bf16_f32 v64, v64, v65
	v_cvt_pk_bf16_f32 v65, v66, v67
	v_lshlrev_b32_e32 v66, 16, v100
	v_and_b32_e32 v67, 0xffff0000, v100
	v_lshlrev_b32_e32 v84, 16, v101
	v_and_b32_e32 v85, 0xffff0000, v101
	v_max_f32_e32 v66, v66, v66
	v_max_f32_e32 v67, v67, v67
	v_max_f32_e32 v84, v84, v84
	v_max_f32_e32 v85, v85, v85
	v_max_f32_e32 v66, 0x21800000, v66
	v_max_f32_e32 v67, 0x21800000, v67
	v_max_f32_e32 v84, 0x21800000, v84
	v_max_f32_e32 v85, 0x21800000, v85
	v_pk_mul_f32 v[66:67], v[68:69], v[66:67]
	v_pk_mul_f32 v[68:69], v[70:71], v[84:85]
	v_cvt_pk_bf16_f32 v66, v66, v67
	v_cvt_pk_bf16_f32 v67, v68, v69
	ds_write2_b64 v212, v[64:65], v[66:67] offset0:24 offset1:26
	s_waitcnt vmcnt(0)
	v_lshlrev_b32_e32 v64, 16, v80
	v_and_b32_e32 v65, 0xffff0000, v80
	v_lshlrev_b32_e32 v66, 16, v81
	v_and_b32_e32 v67, 0xffff0000, v81
	v_max_f32_e32 v64, v64, v64
	v_max_f32_e32 v65, v65, v65
	v_max_f32_e32 v66, v66, v66
	v_max_f32_e32 v67, v67, v67
	v_max_f32_e32 v64, 0x21800000, v64
	v_max_f32_e32 v65, 0x21800000, v65
	v_max_f32_e32 v66, 0x21800000, v66
	v_max_f32_e32 v67, 0x21800000, v67
	v_pk_mul_f32 v[64:65], v[72:73], v[64:65]
	v_pk_mul_f32 v[66:67], v[74:75], v[66:67]
	v_cvt_pk_bf16_f32 v64, v64, v65
	v_cvt_pk_bf16_f32 v65, v66, v67
	v_lshlrev_b32_e32 v66, 16, v82
	v_and_b32_e32 v67, 0xffff0000, v82
	v_lshlrev_b32_e32 v68, 16, v83
	v_and_b32_e32 v69, 0xffff0000, v83
	v_max_f32_e32 v66, v66, v66
	v_max_f32_e32 v67, v67, v67
	v_max_f32_e32 v68, v68, v68
	v_max_f32_e32 v69, v69, v69
	v_max_f32_e32 v66, 0x21800000, v66
	v_max_f32_e32 v67, 0x21800000, v67
	v_max_f32_e32 v68, 0x21800000, v68
	v_max_f32_e32 v69, 0x21800000, v69
	v_pk_mul_f32 v[66:67], v[76:77], v[66:67]
	v_pk_mul_f32 v[68:69], v[78:79], v[68:69]
	v_cvt_pk_bf16_f32 v66, v66, v67
	v_cvt_pk_bf16_f32 v67, v68, v69
	ds_write2_b64 v212, v[64:65], v[66:67] offset0:28 offset1:30
	s_waitcnt lgkmcnt(0)
	s_barrier

; #define G_LOAD(pr, qr, kt_) if (MODE != 1) { _Pragma("unroll") for (int r = 0; r < NP; ++r) pr[r] = *(const u32x4*)(pp + (size_t)(r * 128) * ldp + (kt_) * BK); \
;                               _Pragma("unroll") for (int r = 0; r < NQ; ++r) qr[r] = *(const u32x4*)(qp + (size_t)(r * 128) * ldq + (kt_) * BK); }
; #define G_STORE(pr, qr, so_) { unsigned char* w_ = wP + (so_); \
;                               _Pragma("unroll") for (int r = 0; r < NP; ++r) *(u32x4*)(w_ + r * 128 * LROW) = pr[r]; \
;                               _Pragma("unroll") for (int r = 0; r < NQ; ++r) *(u32x4*)(w_ + BI * LROW + r * 128 * LROW) = qr[r]; }
; #define F_LOAD(fa, fb, so_, ks_) { _Pragma("unroll") for (int it = 0; it < WI; ++it) fa[it] = *(const bf16x8*)(rP + (so_) + it * 32 * LROW + (ks_) * 32); \
;                                   _Pragma("unroll") for (int jt = 0; jt < 2; ++jt) fb[jt] = *(const bf16x8*)(rQ + (so_) + jt * 32 * LROW + (ks_) * 32); }
; #define G_LOAD(pr, qr, kt_) if (MODE != 1) { _Pragma("unroll") for (int r = 0; r < NP; ++r) pr[r] = *(const u32x4*)(pp + (size_t)(r * 128) * ldp + (kt_) * BK); \
;                               _Pragma("unroll") for (int r = 0; r < NQ; ++r) qr[r] = *(const u32x4*)(qp + (size_t)(r * 128) * ldq + (kt_) * BK); }
; #define G_STORE(pr, qr, so_) { unsigned char* w_ = wP + (so_); \
;                               _Pragma("unroll") for (int r = 0; r < NP; ++r) *(u32x4*)(w_ + r * 128 * LROW) = pr[r]; \
;                               _Pragma("unroll") for (int r = 0; r < NQ; ++r) *(u32x4*)(w_ + BI * LROW + r * 128 * LROW) = qr[r]; }
;     ...
;     G_LOAD(p0, q0, 0)
;     G_LOAD(p1, q1, 1)
;     G_LOAD(p2, q2, 2)
;     G_STORE(p0, q0, 0)
;     G_LOAD(p0, q0, 3)
;     G_STORE(p1, q1, STAGE)
;     __syncthreads();
;     F_LOAD(fa0, fb0, 0, 0)
; DI void phase5(const Params& p, unsigned char* smem, int tid, bool coop) {
;     ...
;     for (int rb = 0; rb < 4 * 64; rb += per_round) {
;         const int idp = rb + xcd * (per_round >> 3) + cu;
;         if (idp >= 4 * 64) continue;
;         const int f = (idp & 31) >> 3, tt = (idp >> 5) * 8 + (idp & 7);
;         const int r0 = real_tile_row256(tt);
;         f32x16 acc[4][2];
;         int tl = tid; asm volatile("" : "+v"(tl));
;         gemm_tile3r<4, 4>((const bf16_t*)(ws + OFF_WOUT) + (size_t)f * 256 * 1024, 1024, mx + (size_t)r0 * 1024, 1024, 1024, lds, acc, tl);
.LBB0_1058:
	s_add_i32 s5, s17, s52
	s_cmpk_gt_i32 s5, 0xff
	s_cbranch_scc1 .LBB0_1057
	s_lshl_b32 s4, s51, 16
	s_and_b32 s14, s4, 0x180000
	s_and_b32 s4, s41, 7
	s_ashr_i32 s36, s5, 2
	s_lshl_b32 s31, s4, 8
	s_and_b32 s4, s36, -8
	s_and_b32 s6, s5, 7
	s_bfe_u32 s53, s5, 0x20003
	s_or_b32 s4, s4, s6
	s_ashr_i32 s5, s5, 6
	s_mulk_i32 s5, 0x1010
	s_lshl_b32 s30, s4, 8
	s_add_i32 s37, s5, 16
	s_and_b32 s5, s30, 0xf00
	s_add_i32 s6, s37, s5
	v_mov_b32_e32 v40, v194
	s_lshl_b32 s5, s53, 19
	s_add_u32 s34, s33, s5
	v_ashrrev_i32_e32 v32, 2, v40
	s_addc_u32 s35, s40, 0
	s_ashr_i32 s7, s6, 31
	v_ashrrev_i32_e32 v33, 31, v32
	s_lshl_b64 s[6:7], s[6:7], 11
	v_lshlrev_b64 v[34:35], 11, v[32:33]
	v_lshlrev_b32_e32 v2, 4, v40
	s_add_u32 s6, s3, s6
	v_and_b32_e32 v184, 48, v2
	v_lshl_add_u64 v[2:3], s[34:35], 0, v[34:35]
	s_mov_b64 s[98:99], s[34:35]
	s_addc_u32 s7, s16, s7
	v_lshl_add_u64 v[186:187], v[2:3], 0, v[184:185]
	v_add_u32_e32 v250, v34, v184
	v_add_u32_e32 v251, 0x40000, v250
	v_lshl_add_u64 v[0:1], s[6:7], 0, v[34:35]
	s_mov_b64 s[100:101], s[6:7]
	v_add_co_u32_e32 v36, vcc, s44, v186
	v_lshl_add_u64 v[188:189], v[0:1], 0, v[184:185]
	s_nop 0
	v_addc_co_u32_e32 v37, vcc, 0, v187, vcc
	v_add_co_u32_e32 v38, vcc, s44, v188
	v_ashrrev_i32_e32 v33, 6, v40
	s_nop 0
	v_addc_co_u32_e32 v39, vcc, 0, v189, vcc
	global_load_dwordx4 v[0:3], v[186:187], off
	global_load_dwordx4 v[4:7], v[186:187], off offset:64
	global_load_dwordx4 v[8:11], v[36:37], off
	global_load_dwordx4 v[12:15], v[36:37], off offset:64
	global_load_dwordx4 v[16:19], v[188:189], off
	global_load_dwordx4 v[20:23], v[188:189], off offset:64
	global_load_dwordx4 v[24:27], v[38:39], off
	global_load_dwordx4 v[28:31], v[38:39], off offset:64
	global_load_dwordx4 v[156:159], v[186:187], off offset:128
	global_load_dwordx4 v[140:143], v[186:187], off offset:192
	global_load_dwordx4 v[152:155], v[36:37], off offset:128
	global_load_dwordx4 v[136:139], v[36:37], off offset:192
	global_load_dwordx4 v[148:151], v[188:189], off offset:128
	global_load_dwordx4 v[132:135], v[188:189], off offset:192
	global_load_dwordx4 v[144:147], v[38:39], off offset:128
	global_load_dwordx4 v[128:131], v[38:39], off offset:192
	v_lshrrev_b32_e32 v42, 30, v33
	v_mul_lo_u32 v32, v32, s42
	v_add_u32_e32 v42, v33, v42
	v_and_b32_e32 v41, 31, v40
	v_add3_u32 v197, 0, v32, v184
	v_and_b32_e32 v32, 0x3ffffc, v42
	v_lshlrev_b32_e32 v42, 5, v42
	v_lshrrev_b32_e32 v40, 1, v40
	v_sub_u32_e32 v32, v33, v32
	v_and_or_b32 v33, v42, s43, v41
	v_and_b32_e32 v40, 16, v40
	v_mul_lo_u32 v33, v33, s42
	v_lshl_or_b32 v32, v32, 6, v41
	s_add_u32 s6, s56, s14
	v_mul_lo_u32 v32, v32, s42
	v_add3_u32 v198, 0, v33, v40
	s_addc_u32 s7, s57, 0
	v_add_u32_e32 v202, 0x12000, v197
	v_add3_u32 v200, 0, v32, v40
	v_lshl_add_u64 v[190:191], s[6:7], 0, v[34:35]
	s_lshl_b32 s6, s36, 8
	s_and_b32 s6, s6, 0x800
	s_or_b32 s6, s6, s31
	s_add_i32 s6, s37, s6
	s_ashr_i32 s7, s6, 31
	s_lshl_b64 s[6:7], s[6:7], 11
	s_add_u32 s6, s56, s6
	s_addc_u32 s7, s57, s7
	s_mov_b32 s5, 0
	v_add_u32_e32 v201, 0x19800, v197
	v_add_u32_e32 v199, 0x5800, v200
	v_add_u32_e32 v205, 0x14800, v197
	v_add_u32_e32 v206, 0x14800, v198
	v_add_u32_e32 v207, 0x19800, v200
	v_add_u32_e32 v204, 0x17000, v197
	v_add_u32_e32 v203, 0x1c000, v197
	v_add_u32_e32 v208, 0x1a200, v200
	v_add_u32_e32 v209, 0x15200, v198
	v_add_u32_e32 v210, 0x15c00, v198
	v_add_u32_e32 v211, 0x16600, v198
	v_add_u32_e32 v212, 0x19820, v200
	v_add_u32_e32 v213, 0x14820, v198
	v_add_u32_e32 v214, 0x1a220, v200
	v_add_u32_e32 v215, 0x15220, v198
	v_add_u32_e32 v216, 0x15c20, v198
	v_add_u32_e32 v217, 0x16620, v198
	v_lshl_add_u64 v[192:193], s[6:7], 0, v[34:35]
	s_waitcnt vmcnt(15)
	ds_write_b128 v197, v[0:3] offset:2048
	s_waitcnt vmcnt(14)
	ds_write_b128 v197, v[4:7] offset:43008
	s_waitcnt vmcnt(13)
	ds_write_b128 v197, v[8:11] offset:12288
	s_waitcnt vmcnt(12)
	ds_write_b128 v197, v[12:15] offset:53248
	s_waitcnt vmcnt(11)
	ds_write_b128 v197, v[16:19] offset:22528
	s_waitcnt vmcnt(10)
	ds_write_b128 v197, v[20:23] offset:63488
	s_waitcnt vmcnt(9)
	ds_write_b128 v197, v[24:27] offset:32768
	s_waitcnt vmcnt(8)
	ds_write_b128 v202, v[28:31]
	s_waitcnt lgkmcnt(0)
	s_barrier
	ds_read_b128 v[180:183], v198 offset:2048
	ds_read_b128 v[176:179], v198 offset:4608
	ds_read_b128 v[172:175], v198 offset:7168
	ds_read_b128 v[168:171], v198 offset:9728
	ds_read_b128 v[160:163], v200 offset:22528
	ds_read_b128 v[164:167], v200 offset:25088
	v_mov_b32_e32 v0, 0
	v_mov_b32_e32 v1, v0
	v_mov_b32_e32 v2, v0
	v_mov_b32_e32 v3, v0
	v_mov_b32_e32 v4, v0
	v_mov_b32_e32 v5, v0
	v_mov_b32_e32 v6, v0
	v_mov_b32_e32 v7, v0
	v_mov_b32_e32 v8, v0
	v_mov_b32_e32 v9, v0
	v_mov_b32_e32 v10, v0
	v_mov_b32_e32 v11, v0
	v_mov_b32_e32 v12, v0
	v_mov_b32_e32 v13, v0
	v_mov_b32_e32 v14, v0
	v_mov_b32_e32 v15, v0
	v_mov_b32_e32 v64, v0
	v_mov_b32_e32 v65, v0
	v_mov_b32_e32 v66, v0
	v_mov_b32_e32 v67, v0
	v_mov_b32_e32 v68, v0
	v_mov_b32_e32 v69, v0
	v_mov_b32_e32 v70, v0
	v_mov_b32_e32 v71, v0
	v_mov_b32_e32 v72, v0
	v_mov_b32_e32 v73, v0
	v_mov_b32_e32 v74, v0
	v_mov_b32_e32 v75, v0
	v_mov_b32_e32 v76, v0
	v_mov_b32_e32 v77, v0
	v_mov_b32_e32 v78, v0
	v_mov_b32_e32 v79, v0
	v_mov_b32_e32 v16, v0
	v_mov_b32_e32 v17, v0
	v_mov_b32_e32 v18, v0
	v_mov_b32_e32 v19, v0
	v_mov_b32_e32 v20, v0
	v_mov_b32_e32 v21, v0
	v_mov_b32_e32 v22, v0
	v_mov_b32_e32 v23, v0
	v_mov_b32_e32 v24, v0
	v_mov_b32_e32 v25, v0
	v_mov_b32_e32 v26, v0
	v_mov_b32_e32 v27, v0
	v_mov_b32_e32 v28, v0
	v_mov_b32_e32 v29, v0
	v_mov_b32_e32 v30, v0
	v_mov_b32_e32 v31, v0
	v_mov_b32_e32 v80, v0
	v_mov_b32_e32 v81, v0
	v_mov_b32_e32 v82, v0
	v_mov_b32_e32 v83, v0
; #define G_LOAD(pr, qr, kt_) if (MODE != 1) { _Pragma("unroll") for (int r = 0; r < NP; ++r) pr[r] = *(const u32x4*)(pp + (size_t)(r * 128) * ldp + (kt_) * BK); \
;                               _Pragma("unroll") for (int r = 0; r < NQ; ++r) qr[r] = *(const u32x4*)(qp + (size_t)(r * 128) * ldq + (kt_) * BK); }
; #define G_STORE(pr, qr, so_) { unsigned char* w_ = wP + (so_); \
;                               _Pragma("unroll") for (int r = 0; r < NP; ++r) *(u32x4*)(w_ + r * 128 * LROW) = pr[r]; \
;                               _Pragma("unroll") for (int r = 0; r < NQ; ++r) *(u32x4*)(w_ + BI * LROW + r * 128 * LROW) = qr[r]; }
; #define F_LOAD(fa, fb, so_, ks_) { _Pragma("unroll") for (int it = 0; it < WI; ++it) fa[it] = *(const bf16x8*)(rP + (so_) + it * 32 * LROW + (ks_) * 32); \
;                                   _Pragma("unroll") for (int jt = 0; jt < 2; ++jt) fb[jt] = *(const bf16x8*)(rQ + (so_) + jt * 32 * LROW + (ks_) * 32); }
; #define G_LOAD(pr, qr, kt_) if (MODE != 1) { _Pragma("unroll") for (int r = 0; r < NP; ++r) pr[r] = *(const u32x4*)(pp + (size_t)(r * 128) * ldp + (kt_) * BK); \
;                               _Pragma("unroll") for (int r = 0; r < NQ; ++r) qr[r] = *(const u32x4*)(qp + (size_t)(r * 128) * ldq + (kt_) * BK); }
;     ...
;     if (ZERO) {
; #pragma unroll
;         for (int it = 0; it < WI; ++it)
; #pragma unroll
;             for (int jt = 0; jt < 2; ++jt)
; #pragma unroll
;                 for (int r = 0; r < 16; ++r) acc[it][jt][r] = 0.f;
;     }
;     ...
;     if (MODE == 1) {
; #pragma unroll
;         for (int r = 0; r < NP; ++r) { p0[r] = *(const u32x4*)(pp + (size_t)(r * 128) * ldp); p1[r] = p0[r]; p2[r] = p0[r]; }
; #pragma unroll
;         for (int r = 0; r < NQ; ++r) { q0[r] = *(const u32x4*)(qp + (size_t)(r * 128) * ldq); q1[r] = q0[r]; q2[r] = q0[r]; }
;     }
;     G_LOAD(p0, q0, 0)
;     G_LOAD(p1, q1, 1)
;     G_LOAD(p2, q2, 2)
;     G_STORE(p0, q0, 0)
;     G_LOAD(p0, q0, 3)
;     G_STORE(p1, q1, STAGE)
;     __syncthreads();
;     F_LOAD(fa0, fb0, 0, 0)
;     int cur = 0, nxt = STAGE, wr = 2 * STAGE;
;     int kt = 0;
; #pragma unroll 1
;     for (; kt + 3 <= nk; kt += 3) {
;         G_HALF(p1, q1, p2, q2, kt)
;         G_HALF(p2, q2, p0, q0, kt + 1)
;         G_HALF(p0, q0, p1, q1, kt + 2)
;     }
	v_mov_b32_e32 v84, v0
	v_mov_b32_e32 v85, v0
	v_mov_b32_e32 v86, v0
	v_mov_b32_e32 v87, v0
	v_mov_b32_e32 v88, v0
	v_mov_b32_e32 v89, v0
	v_mov_b32_e32 v90, v0
	v_mov_b32_e32 v91, v0
	v_mov_b32_e32 v92, v0
	v_mov_b32_e32 v93, v0
	v_mov_b32_e32 v94, v0
	v_mov_b32_e32 v95, v0
	v_mov_b32_e32 v32, v0
	v_mov_b32_e32 v33, v0
	v_mov_b32_e32 v34, v0
	v_mov_b32_e32 v35, v0
	v_mov_b32_e32 v36, v0
	v_mov_b32_e32 v37, v0
	v_mov_b32_e32 v38, v0
	v_mov_b32_e32 v39, v0
	v_mov_b32_e32 v40, v0
	v_mov_b32_e32 v41, v0
	v_mov_b32_e32 v42, v0
	v_mov_b32_e32 v43, v0
	v_mov_b32_e32 v44, v0
	v_mov_b32_e32 v45, v0
	v_mov_b32_e32 v46, v0
	v_mov_b32_e32 v47, v0
	v_mov_b32_e32 v96, v0
	v_mov_b32_e32 v97, v0
	v_mov_b32_e32 v98, v0
	v_mov_b32_e32 v99, v0
	v_mov_b32_e32 v100, v0
	v_mov_b32_e32 v101, v0
	v_mov_b32_e32 v102, v0
	v_mov_b32_e32 v103, v0
	v_mov_b32_e32 v104, v0
	v_mov_b32_e32 v105, v0
	v_mov_b32_e32 v106, v0
	v_mov_b32_e32 v107, v0
	v_mov_b32_e32 v108, v0
	v_mov_b32_e32 v109, v0
	v_mov_b32_e32 v110, v0
	v_mov_b32_e32 v111, v0
	v_mov_b32_e32 v48, v0
	v_mov_b32_e32 v49, v0
	v_mov_b32_e32 v50, v0
	v_mov_b32_e32 v51, v0
	v_mov_b32_e32 v52, v0
	v_mov_b32_e32 v53, v0
	v_mov_b32_e32 v54, v0
	v_mov_b32_e32 v55, v0
	v_mov_b32_e32 v56, v0
	v_mov_b32_e32 v57, v0
	v_mov_b32_e32 v58, v0
	v_mov_b32_e32 v59, v0
	v_mov_b32_e32 v60, v0
	v_mov_b32_e32 v61, v0
	v_mov_b32_e32 v62, v0
	v_mov_b32_e32 v63, v0
	v_mov_b32_e32 v112, v0
	v_mov_b32_e32 v113, v0
	v_mov_b32_e32 v114, v0
	v_mov_b32_e32 v115, v0
	v_mov_b32_e32 v116, v0
	v_mov_b32_e32 v117, v0
	v_mov_b32_e32 v118, v0
	v_mov_b32_e32 v119, v0
	v_mov_b32_e32 v120, v0
	v_mov_b32_e32 v121, v0
	v_mov_b32_e32 v122, v0
	v_mov_b32_e32 v123, v0
	v_mov_b32_e32 v124, v0
	v_mov_b32_e32 v125, v0
	v_mov_b32_e32 v126, v0
	v_mov_b32_e32 v127, v0
	s_waitcnt lgkmcnt(0)
.LBB0_1060:
	s_nop 0
	s_waitcnt lgkmcnt(4)
	v_mfma_f32_32x32x16_bf16 v[112:127], v[180:183], v[160:163], v[112:127]
	ds_read_b128 v[218:221], v200 offset:22560
	s_waitcnt vmcnt(7)
	ds_write_b128 v205, v[156:159]
	s_waitcnt lgkmcnt(5)
	v_mfma_f32_32x32x16_bf16 v[48:63], v[180:183], v[164:167], v[48:63]
	global_load_dwordx4 v[180:183], v250, s[98:99] offset:256
	ds_read_b128 v[156:159], v198 offset:2080
	s_waitcnt lgkmcnt(5)
	v_mfma_f32_32x32x16_bf16 v[96:111], v[176:179], v[160:163], v[96:111]
	ds_read_b128 v[222:225], v200 offset:25120
	s_waitcnt vmcnt(6)
	ds_write_b128 v204, v[152:155]
	v_mfma_f32_32x32x16_bf16 v[32:47], v[176:179], v[164:167], v[32:47]
	global_load_dwordx4 v[176:179], v251, s[98:99] offset:256
	ds_read_b128 v[152:155], v198 offset:4640
	s_waitcnt lgkmcnt(7)
	v_mfma_f32_32x32x16_bf16 v[80:95], v[172:175], v[160:163], v[80:95]
	s_waitcnt vmcnt(5)
	ds_write_b128 v201, v[148:151]
	v_mfma_f32_32x32x16_bf16 v[16:31], v[172:175], v[164:167], v[16:31]
	global_load_dwordx4 v[172:175], v250, s[100:101] offset:256
	ds_read_b128 v[148:151], v198 offset:7200
	s_waitcnt lgkmcnt(8)
	v_mfma_f32_32x32x16_bf16 v[64:79], v[168:171], v[160:163], v[64:79]
	s_waitcnt vmcnt(4)
	ds_write_b128 v203, v[144:147]
	v_mfma_f32_32x32x16_bf16 v[0:15], v[168:171], v[164:167], v[0:15]
	global_load_dwordx4 v[160:163], v251, s[100:101] offset:256
	ds_read_b128 v[144:147], v198 offset:9760
	s_waitcnt lgkmcnt(7)
	v_mfma_f32_32x32x16_bf16 v[112:127], v[156:159], v[218:221], v[112:127]
	ds_read_b128 v[164:167], v200 offset:63488
	s_waitcnt lgkmcnt(7)
	v_mfma_f32_32x32x16_bf16 v[48:63], v[156:159], v[222:225], v[48:63]
	ds_read_b128 v[156:159], v198 offset:43008
	s_waitcnt lgkmcnt(6)
	v_mfma_f32_32x32x16_bf16 v[96:111], v[152:155], v[218:221], v[96:111]
	ds_read_b128 v[168:171], v199 offset:43520
	v_mfma_f32_32x32x16_bf16 v[32:47], v[152:155], v[222:225], v[32:47]
	ds_read_b128 v[152:155], v198 offset:45568
	s_waitcnt lgkmcnt(6)
	v_mfma_f32_32x32x16_bf16 v[80:95], v[148:151], v[218:221], v[80:95]
	v_mfma_f32_32x32x16_bf16 v[16:31], v[148:151], v[222:225], v[16:31]
	ds_read_b128 v[148:151], v198 offset:48128
	s_waitcnt lgkmcnt(5)
	v_mfma_f32_32x32x16_bf16 v[64:79], v[144:147], v[218:221], v[64:79]
	v_mfma_f32_32x32x16_bf16 v[0:15], v[144:147], v[222:225], v[0:15]
	ds_read_b128 v[144:147], v198 offset:50688
	s_barrier
	s_waitcnt lgkmcnt(4)
	v_mfma_f32_32x32x16_bf16 v[112:127], v[156:159], v[164:167], v[112:127]
	ds_read_b128 v[218:221], v200 offset:63520
	ds_write_b128 v197, v[140:143] offset:2048
	s_waitcnt lgkmcnt(5)
	v_mfma_f32_32x32x16_bf16 v[48:63], v[156:159], v[168:171], v[48:63]
	global_load_dwordx4 v[156:159], v250, s[98:99] offset:320
	ds_read_b128 v[140:143], v198 offset:43040
	s_waitcnt lgkmcnt(5)
	v_mfma_f32_32x32x16_bf16 v[96:111], v[152:155], v[164:167], v[96:111]
	ds_read_b128 v[222:225], v199 offset:43552
	ds_write_b128 v197, v[136:139] offset:12288
	v_mfma_f32_32x32x16_bf16 v[32:47], v[152:155], v[168:171], v[32:47]
	global_load_dwordx4 v[152:155], v251, s[98:99] offset:320
	ds_read_b128 v[136:139], v198 offset:45600
	s_waitcnt lgkmcnt(7)
	v_mfma_f32_32x32x16_bf16 v[80:95], v[148:151], v[164:167], v[80:95]
	ds_write_b128 v197, v[132:135] offset:22528
	v_mfma_f32_32x32x16_bf16 v[16:31], v[148:151], v[168:171], v[16:31]
	global_load_dwordx4 v[148:151], v250, s[100:101] offset:320
	ds_read_b128 v[132:135], v198 offset:48160
	s_waitcnt lgkmcnt(8)
	v_mfma_f32_32x32x16_bf16 v[64:79], v[144:147], v[164:167], v[64:79]
	s_waitcnt vmcnt(7)
	ds_write_b128 v197, v[128:131] offset:32768
	v_mfma_f32_32x32x16_bf16 v[0:15], v[144:147], v[168:171], v[0:15]
	global_load_dwordx4 v[144:147], v251, s[100:101] offset:320
	ds_read_b128 v[128:131], v198 offset:50720
	s_waitcnt lgkmcnt(7)
	v_mfma_f32_32x32x16_bf16 v[112:127], v[140:143], v[218:221], v[112:127]
	ds_read_b128 v[164:167], v207
	s_waitcnt lgkmcnt(7)
	v_mfma_f32_32x32x16_bf16 v[48:63], v[140:143], v[222:225], v[48:63]
	ds_read_b128 v[140:143], v206
	s_waitcnt lgkmcnt(6)
	v_mfma_f32_32x32x16_bf16 v[96:111], v[136:139], v[218:221], v[96:111]
	ds_read_b128 v[168:171], v208
	v_mfma_f32_32x32x16_bf16 v[32:47], v[136:139], v[222:225], v[32:47]
	ds_read_b128 v[136:139], v209
	s_waitcnt lgkmcnt(6)
	v_mfma_f32_32x32x16_bf16 v[80:95], v[132:135], v[218:221], v[80:95]
	v_mfma_f32_32x32x16_bf16 v[16:31], v[132:135], v[222:225], v[16:31]
	ds_read_b128 v[132:135], v210
	s_waitcnt lgkmcnt(5)
	v_mfma_f32_32x32x16_bf16 v[64:79], v[128:131], v[218:221], v[64:79]
	v_mfma_f32_32x32x16_bf16 v[0:15], v[128:131], v[222:225], v[0:15]
	ds_read_b128 v[128:131], v211
	s_barrier
; #define G_LOAD(pr, qr, kt_) if (MODE != 1) { _Pragma("unroll") for (int r = 0; r < NP; ++r) pr[r] = *(const u32x4*)(pp + (size_t)(r * 128) * ldp + (kt_) * BK); \
;                               _Pragma("unroll") for (int r = 0; r < NQ; ++r) qr[r] = *(const u32x4*)(qp + (size_t)(r * 128) * ldq + (kt_) * BK); }
; #define G_STORE(pr, qr, so_) { unsigned char* w_ = wP + (so_); \
;                               _Pragma("unroll") for (int r = 0; r < NP; ++r) *(u32x4*)(w_ + r * 128 * LROW) = pr[r]; \
;                               _Pragma("unroll") for (int r = 0; r < NQ; ++r) *(u32x4*)(w_ + BI * LROW + r * 128 * LROW) = qr[r]; }
; #define F_LOAD(fa, fb, so_, ks_) { _Pragma("unroll") for (int it = 0; it < WI; ++it) fa[it] = *(const bf16x8*)(rP + (so_) + it * 32 * LROW + (ks_) * 32); \
;                                   _Pragma("unroll") for (int jt = 0; jt < 2; ++jt) fb[jt] = *(const bf16x8*)(rQ + (so_) + jt * 32 * LROW + (ks_) * 32); }
; #define G_LOAD(pr, qr, kt_) if (MODE != 1) { _Pragma("unroll") for (int r = 0; r < NP; ++r) pr[r] = *(const u32x4*)(pp + (size_t)(r * 128) * ldp + (kt_) * BK); \
;                               _Pragma("unroll") for (int r = 0; r < NQ; ++r) qr[r] = *(const u32x4*)(qp + (size_t)(r * 128) * ldq + (kt_) * BK); }
;     ...
;     if (MODE == 1) {
; #pragma unroll
;         for (int r = 0; r < NP; ++r) { p0[r] = *(const u32x4*)(pp + (size_t)(r * 128) * ldp); p1[r] = p0[r]; p2[r] = p0[r]; }
; #pragma unroll
;         for (int r = 0; r < NQ; ++r) { q0[r] = *(const u32x4*)(qp + (size_t)(r * 128) * ldq); q1[r] = q0[r]; q2[r] = q0[r]; }
;     }
;     G_LOAD(p0, q0, 0)
;     G_LOAD(p1, q1, 1)
;     G_LOAD(p2, q2, 2)
;     G_STORE(p0, q0, 0)
;     G_LOAD(p0, q0, 3)
;     G_STORE(p1, q1, STAGE)
;     __syncthreads();
;     F_LOAD(fa0, fb0, 0, 0)
;     int cur = 0, nxt = STAGE, wr = 2 * STAGE;
;     int kt = 0;
; #pragma unroll 1
;     for (; kt + 3 <= nk; kt += 3) {
;         G_HALF(p1, q1, p2, q2, kt)
;         G_HALF(p2, q2, p0, q0, kt + 1)
;         G_HALF(p0, q0, p1, q1, kt + 2)
;     }
;     if (kt < nk) G_HALF(p1, q1, p2, q2, kt)
;     if (kt + 1 < nk) G_HALF(p2, q2, p0, q0, kt + 1)
	s_waitcnt lgkmcnt(4)
	v_mfma_f32_32x32x16_bf16 v[112:127], v[140:143], v[164:167], v[112:127]
	ds_read_b128 v[218:221], v212
	s_waitcnt vmcnt(7)
	ds_write_b128 v197, v[180:183] offset:43008
	s_waitcnt lgkmcnt(5)
	v_mfma_f32_32x32x16_bf16 v[48:63], v[140:143], v[168:171], v[48:63]
	global_load_dwordx4 v[140:143], v250, s[98:99] offset:384
	ds_read_b128 v[180:183], v213
	s_waitcnt lgkmcnt(5)
	v_mfma_f32_32x32x16_bf16 v[96:111], v[136:139], v[164:167], v[96:111]
	ds_read_b128 v[222:225], v214
	s_waitcnt vmcnt(7)
	ds_write_b128 v197, v[176:179] offset:53248
	v_mfma_f32_32x32x16_bf16 v[32:47], v[136:139], v[168:171], v[32:47]
	ds_read_b128 v[176:179], v215
	global_load_dwordx4 v[136:139], v251, s[98:99] offset:384
	s_waitcnt lgkmcnt(7)
	v_mfma_f32_32x32x16_bf16 v[80:95], v[132:135], v[164:167], v[80:95]
	s_waitcnt vmcnt(7)
	ds_write_b128 v197, v[172:175] offset:63488
	v_mfma_f32_32x32x16_bf16 v[16:31], v[132:135], v[168:171], v[16:31]
	global_load_dwordx4 v[132:135], v250, s[100:101] offset:384
	ds_read_b128 v[172:175], v216
	s_waitcnt lgkmcnt(8)
	v_mfma_f32_32x32x16_bf16 v[64:79], v[128:131], v[164:167], v[64:79]
	s_waitcnt vmcnt(7)
	ds_write_b128 v202, v[160:163]
	v_mfma_f32_32x32x16_bf16 v[0:15], v[128:131], v[168:171], v[0:15]
	ds_read_b128 v[168:171], v217
	global_load_dwordx4 v[128:131], v251, s[100:101] offset:384
	s_waitcnt lgkmcnt(7)
	v_mfma_f32_32x32x16_bf16 v[112:127], v[180:183], v[218:221], v[112:127]
	ds_read_b128 v[160:163], v200 offset:22528
	s_waitcnt lgkmcnt(7)
	v_mfma_f32_32x32x16_bf16 v[48:63], v[180:183], v[222:225], v[48:63]
	ds_read_b128 v[180:183], v198 offset:2048
	s_waitcnt lgkmcnt(6)
	v_mfma_f32_32x32x16_bf16 v[96:111], v[176:179], v[218:221], v[96:111]
	ds_read_b128 v[164:167], v200 offset:25088
	v_mfma_f32_32x32x16_bf16 v[32:47], v[176:179], v[222:225], v[32:47]
	ds_read_b128 v[176:179], v198 offset:4608
	s_waitcnt lgkmcnt(6)
	v_mfma_f32_32x32x16_bf16 v[80:95], v[172:175], v[218:221], v[80:95]
	v_mfma_f32_32x32x16_bf16 v[16:31], v[172:175], v[222:225], v[16:31]
	ds_read_b128 v[172:175], v198 offset:7168
	s_waitcnt lgkmcnt(5)
	v_mfma_f32_32x32x16_bf16 v[64:79], v[168:171], v[218:221], v[64:79]
	v_mfma_f32_32x32x16_bf16 v[0:15], v[168:171], v[222:225], v[0:15]
	ds_read_b128 v[168:171], v198 offset:9728
	s_add_i32 s5, s5, 3
	v_add_u32_e32 v250, 0xc0, v250
	s_cmp_lt_u32 s5, 30
	v_add_u32_e32 v251, 0xc0, v251
	s_barrier
	s_cbranch_scc1 .LBB0_1060
	s_waitcnt lgkmcnt(0)
	v_mfma_f32_32x32x16_bf16 v[112:127], v[180:183], v[160:163], v[112:127]
	ds_read_b128 v[186:189], v200 offset:22560
	s_waitcnt vmcnt(7)
	ds_write_b128 v205, v[156:159]
	v_mfma_f32_32x32x16_bf16 v[48:63], v[180:183], v[164:167], v[48:63]
	ds_read_b128 v[156:159], v198 offset:2080
	v_mfma_f32_32x32x16_bf16 v[96:111], v[176:179], v[160:163], v[96:111]
	ds_read_b128 v[180:183], v200 offset:25120
	s_waitcnt vmcnt(6)
	ds_write_b128 v204, v[152:155]
	v_mfma_f32_32x32x16_bf16 v[32:47], v[176:179], v[164:167], v[32:47]
	ds_read_b128 v[152:155], v198 offset:4640
	v_mfma_f32_32x32x16_bf16 v[80:95], v[172:175], v[160:163], v[80:95]
	s_waitcnt vmcnt(5)
	ds_write_b128 v201, v[148:151]
	v_mfma_f32_32x32x16_bf16 v[16:31], v[172:175], v[164:167], v[16:31]
	ds_read_b128 v[148:151], v198 offset:7200
	v_mfma_f32_32x32x16_bf16 v[64:79], v[168:171], v[160:163], v[64:79]
	s_waitcnt vmcnt(4)
	ds_write_b128 v203, v[144:147]
	v_mfma_f32_32x32x16_bf16 v[0:15], v[168:171], v[164:167], v[0:15]
	ds_read_b128 v[144:147], v198 offset:9760
	s_waitcnt lgkmcnt(7)
	v_mfma_f32_32x32x16_bf16 v[112:127], v[156:159], v[186:189], v[112:127]
	ds_read_b128 v[160:163], v200 offset:63488
	s_waitcnt lgkmcnt(7)
	v_mfma_f32_32x32x16_bf16 v[48:63], v[156:159], v[180:183], v[48:63]
	ds_read_b128 v[156:159], v198 offset:43008
	s_waitcnt lgkmcnt(6)
	v_mfma_f32_32x32x16_bf16 v[96:111], v[152:155], v[186:189], v[96:111]
	ds_read_b128 v[164:167], v199 offset:43520
	v_mfma_f32_32x32x16_bf16 v[32:47], v[152:155], v[180:183], v[32:47]
	ds_read_b128 v[152:155], v198 offset:45568
	s_waitcnt lgkmcnt(6)
	v_mfma_f32_32x32x16_bf16 v[80:95], v[148:151], v[186:189], v[80:95]
	v_mfma_f32_32x32x16_bf16 v[16:31], v[148:151], v[180:183], v[16:31]
	ds_read_b128 v[148:151], v198 offset:48128
	s_waitcnt lgkmcnt(5)
	v_mfma_f32_32x32x16_bf16 v[64:79], v[144:147], v[186:189], v[64:79]
	v_mfma_f32_32x32x16_bf16 v[0:15], v[144:147], v[180:183], v[0:15]
	ds_read_b128 v[144:147], v198 offset:50688
	s_waitcnt lgkmcnt(0)
	s_barrier
; #define G_HALF(pl, ql, ps, qs, kt_) { const int k4_ = min((kt_) + 4, nk - 1); \
;         SB G_LOAD(pl, ql, k4_) F_LOAD(fa1, fb1, cur, 1) SB G_MFMA(fa0, fb0) SB G_STORE(ps, qs, wr) F_LOAD(fa0, fb0, nxt, 0) SB G_MFMA(fa1, fb1) SB \
;         __syncthreads(); { const int t_ = cur; cur = nxt; nxt = wr; wr = t_; } }
; #define G_HALF(pl, ql, ps, qs, kt_) { const int k4_ = min((kt_) + 4, nk - 1); \
;         SB R_BURST1(fb0, fb1, cur, 1, pl, ql, k4_, ps, qs, wr) R_BURST2(fb1, fb0, nxt, 0, ps, qs, wr) \
;         __syncthreads(); { const int t_ = cur; cur = nxt; nxt = wr; wr = t_; } }
; #define G_HALF(pl, ql, ps, qs, kt_) { const int k4_ = min((kt_) + 4, nk - 1); \
;         SB R_BURST1(fb0, fb1, cur, 1, pl, ql, k4_, ps, qs, wr) R_BURST2(fb1, fb0, nxt, 0, ps, qs, wr) \
;         __syncthreads(); { const int t_ = cur; cur = nxt; nxt = wr; wr = t_; } }
;     ...
;     if (kt < nk) G_HALF(p1, q1, p2, q2, kt)
;     if (kt + 1 < nk) G_HALF(p2, q2, p0, q0, kt + 1)
; DI void phase5(const Params& p, unsigned char* smem, int tid, bool coop) {
;     ...
; #pragma unroll
;         for (int jt = 0; jt < 2; ++jt) {
;             const int tr = tt * 256 + wj * 64 + jt * 32 + ln;
;             float sq = 0.f;
; #pragma unroll
;             for (int it = 0; it < 4; ++it)
; #pragma unroll
;                 for (int r = 0; r < 16; ++r) sq += acc[it][jt][r] * acc[it][jt][r];
;             { const auto sw = __builtin_amdgcn_permlane32_swap(__float_as_uint(sq), __float_as_uint(sq), false, false);
;               sq = __uint_as_float(sw[0]) + __uint_as_float(sw[1]); }
;             if (h == 0) atomicAdd(ssq + tr, sq);
;         }
	v_mfma_f32_32x32x16_bf16 v[112:127], v[156:159], v[160:163], v[112:127]
	ds_read_b128 v[168:171], v200 offset:63520
	s_waitcnt vmcnt(3)
	ds_write_b128 v197, v[140:143] offset:2048
	v_mfma_f32_32x32x16_bf16 v[48:63], v[156:159], v[164:167], v[48:63]
	ds_read_b128 v[140:143], v198 offset:43040
	v_mfma_f32_32x32x16_bf16 v[96:111], v[152:155], v[160:163], v[96:111]
	ds_read_b128 v[156:159], v199 offset:43552
	s_waitcnt vmcnt(2)
	ds_write_b128 v197, v[136:139] offset:12288
	v_mfma_f32_32x32x16_bf16 v[32:47], v[152:155], v[164:167], v[32:47]
	ds_read_b128 v[136:139], v198 offset:45600
	v_mfma_f32_32x32x16_bf16 v[80:95], v[148:151], v[160:163], v[80:95]
	s_waitcnt vmcnt(1)
	ds_write_b128 v197, v[132:135] offset:22528
	v_mfma_f32_32x32x16_bf16 v[16:31], v[148:151], v[164:167], v[16:31]
	ds_read_b128 v[132:135], v198 offset:48160
	v_mfma_f32_32x32x16_bf16 v[64:79], v[144:147], v[160:163], v[64:79]
	s_waitcnt vmcnt(0)
	ds_write_b128 v197, v[128:131] offset:32768
	v_mfma_f32_32x32x16_bf16 v[0:15], v[144:147], v[164:167], v[0:15]
	ds_read_b128 v[128:131], v198 offset:50720
	s_waitcnt lgkmcnt(7)
	v_mfma_f32_32x32x16_bf16 v[112:127], v[140:143], v[168:171], v[112:127]
	s_waitcnt lgkmcnt(6)
	v_mfma_f32_32x32x16_bf16 v[48:63], v[140:143], v[156:159], v[48:63]
	s_waitcnt lgkmcnt(4)
	v_mfma_f32_32x32x16_bf16 v[96:111], v[136:139], v[168:171], v[96:111]
	v_mfma_f32_32x32x16_bf16 v[32:47], v[136:139], v[156:159], v[32:47]
	s_waitcnt lgkmcnt(2)
	v_mfma_f32_32x32x16_bf16 v[80:95], v[132:135], v[168:171], v[80:95]
	v_mfma_f32_32x32x16_bf16 v[16:31], v[132:135], v[156:159], v[16:31]
	s_waitcnt lgkmcnt(0)
	v_mfma_f32_32x32x16_bf16 v[64:79], v[128:131], v[168:171], v[64:79]
	v_mfma_f32_32x32x16_bf16 v[0:15], v[128:131], v[156:159], v[0:15]
	v_readfirstlane_b32 s98, v194
	v_ashrrev_i32_e32 v252, 8, v194
	v_bfe_u32 v253, v194, 5, 1
	v_lshlrev_b32_e32 v252, 9, v252
	v_lshl_add_u32 v252, v253, 4, v252
	s_lshl_b32 s99, s53, 10
	s_add_u32 s36, s8, s99
	s_addc_u32 s37, s9, 0
	s_add_u32 s100, s26, s99
	s_addc_u32 s101, s27, 0
	global_load_dwordx4 v[146:149], v252, s[36:37]
	global_load_dwordx4 v[150:153], v252, s[36:37] offset:32
	global_load_dwordx4 v[154:157], v252, s[36:37] offset:64
	global_load_dwordx4 v[158:161], v252, s[36:37] offset:96
	global_load_dwordx4 v[162:165], v252, s[36:37] offset:128
	global_load_dwordx4 v[166:169], v252, s[36:37] offset:160
	global_load_dwordx4 v[170:173], v252, s[36:37] offset:192
	global_load_dwordx4 v[174:177], v252, s[36:37] offset:224
	global_load_dwordx4 v[178:181], v252, s[36:37] offset:256
	global_load_dwordx4 v[186:189], v252, s[36:37] offset:288
	global_load_dwordx4 v[190:193], v252, s[36:37] offset:320
	global_load_dwordx4 v[198:201], v252, s[36:37] offset:352
	global_load_dwordx4 v[202:205], v252, s[36:37] offset:384
	global_load_dwordx4 v[206:209], v252, s[36:37] offset:416
	global_load_dwordx4 v[210:213], v252, s[36:37] offset:448
	global_load_dwordx4 v[214:217], v252, s[36:37] offset:480
	v_lshrrev_b32_e32 v254, 7, v194
	v_lshlrev_b32_e32 v254, 18, v254
	v_bfe_u32 v253, v194, 6, 1
	v_lshl_add_u32 v254, v253, 16, v254
	v_and_b32_e32 v253, 63, v194
	v_lshl_add_u32 v254, v253, 4, v254
	s_lshl_b32 s99, s30, 12
	v_add_u32_e32 v254, s99, v254
	v_lshrrev_b32_e32 v246, 6, v194
	v_mul_u32_u24_e32 v246, 0x2100, v246
	v_lshl_add_u32 v246, v253, 3, v246
	s_nop 0
	v_mul_f32_e32 v128, v113, v113
	v_fmac_f32_e32 v128, v112, v112
	v_fmac_f32_e32 v128, v114, v114
	v_fmac_f32_e32 v128, v115, v115
	v_fmac_f32_e32 v128, v116, v116
	v_fmac_f32_e32 v128, v117, v117
	v_fmac_f32_e32 v128, v118, v118
	v_fmac_f32_e32 v128, v119, v119
	v_fmac_f32_e32 v128, v120, v120
	v_fmac_f32_e32 v128, v121, v121
	v_fmac_f32_e32 v128, v122, v122
	v_fmac_f32_e32 v128, v123, v123
	v_fmac_f32_e32 v128, v124, v124
	v_fmac_f32_e32 v128, v125, v125
	v_fmac_f32_e32 v128, v126, v126
	v_fmac_f32_e32 v128, v127, v127
	v_fmac_f32_e32 v128, v96, v96
	v_fmac_f32_e32 v128, v97, v97
	v_fmac_f32_e32 v128, v98, v98
	v_fmac_f32_e32 v128, v99, v99
	v_fmac_f32_e32 v128, v100, v100
	v_fmac_f32_e32 v128, v101, v101
	v_fmac_f32_e32 v128, v102, v102
	v_fmac_f32_e32 v128, v103, v103
	v_fmac_f32_e32 v128, v104, v104
	v_fmac_f32_e32 v128, v105, v105
	v_fmac_f32_e32 v128, v106, v106
	v_fmac_f32_e32 v128, v107, v107
	v_fmac_f32_e32 v128, v108, v108
	v_fmac_f32_e32 v128, v109, v109
	v_fmac_f32_e32 v128, v110, v110
	v_fmac_f32_e32 v128, v111, v111
	v_fmac_f32_e32 v128, v80, v80
	v_fmac_f32_e32 v128, v81, v81
	v_fmac_f32_e32 v128, v82, v82
	v_fmac_f32_e32 v128, v83, v83
	v_fmac_f32_e32 v128, v84, v84
	v_fmac_f32_e32 v128, v85, v85
	v_fmac_f32_e32 v128, v86, v86
	v_fmac_f32_e32 v128, v87, v87
	v_fmac_f32_e32 v128, v88, v88
	v_fmac_f32_e32 v128, v89, v89
	v_fmac_f32_e32 v128, v90, v90
	v_fmac_f32_e32 v128, v91, v91
	v_fmac_f32_e32 v128, v92, v92
	v_fmac_f32_e32 v128, v93, v93
	v_fmac_f32_e32 v128, v94, v94
	v_fmac_f32_e32 v128, v95, v95
	v_fmac_f32_e32 v128, v64, v64
	v_fmac_f32_e32 v128, v65, v65
	v_fmac_f32_e32 v128, v66, v66
	v_fmac_f32_e32 v128, v67, v67
	v_fmac_f32_e32 v128, v68, v68
	v_fmac_f32_e32 v128, v69, v69
	v_fmac_f32_e32 v128, v70, v70
	v_fmac_f32_e32 v128, v71, v71
	v_fmac_f32_e32 v128, v72, v72
	v_fmac_f32_e32 v128, v73, v73
	v_fmac_f32_e32 v128, v74, v74
	v_fmac_f32_e32 v128, v75, v75
	v_fmac_f32_e32 v128, v76, v76
	v_fmac_f32_e32 v128, v77, v77
	v_mov_b32_e32 v142, v194
	v_fmac_f32_e32 v128, v78, v78
	s_barrier
	v_fmac_f32_e32 v128, v79, v79
	v_and_b32_e32 v134, 0xc0, v142
	v_and_b32_e32 v143, 31, v142
	v_bfe_u32 v129, v142, 5, 1
	v_or3_b32 v130, v134, s30, v143
	v_mov_b32_e32 v132, v128
	v_cmp_eq_u32_e32 vcc, 0, v129
	s_nop 0
	v_permlane32_swap_b32_e32 v128, v132
	v_ashrrev_i32_e32 v131, 31, v130
	s_and_saveexec_b64 s[6:7], vcc
	s_cbranch_execz .LBB0_1063
	v_add_f32_e32 v128, v128, v132
	v_lshl_add_u64 v[132:133], v[130:131], 2, s[18:19]
	global_atomic_add_f32 v[132:133], v128, off
